# GEMM K-loops: s_setprio 1 before the opening barrier, redundant post-barrier lgkmcnt(0) and mid-block setprio pair dropped, s_setprio 0 after the closing barrier (shorter barrier turnaround), on top o
# speedup vs baseline: 1.0070x; 1.0070x over previous
; #define PG8_STAGE(bufoff, gbase, voff) do { _Pragma("unroll") for (int _i = 0; _i < 2; ++_i) \
;         __builtin_amdgcn_global_load_lds((const unsigned*)((const char*)(gbase) + (voff)[_i]), (LAS unsigned*)(lds + (bufoff) + ldsw + _i * 8192), 16, 0, 0); } while (0)
; #define PG8_LDA(dst, b, h) do { _Pragma("unroll") for (int m = 0; m < 4; ++m) _Pragma("unroll") for (int k = 0; k < 2; ++k) dst[m][k] = *(const LAS bf16x8*)(lds + PG8_SA(b, h) + aoff + m * 2048 + k * 1024); } while (0)
; #define PG8_LDB(dst, b, h) do { _Pragma("unroll") for (int n = 0; n < 2; ++n) _Pragma("unroll") for (int k = 0; k < 2; ++k) dst[n][k] = *(const LAS bf16x8*)(lds + PG8_SB(b, h) + boff + n * 2048 + k * 1024); } while (0)
; #define PG8_MMA(ai, bj, At, Bt) do { __builtin_amdgcn_s_setprio(1); _Pragma("unroll") for (int m = 0; m < 4; ++m) _Pragma("unroll") for (int n = 0; n < 2; ++n) _Pragma("unroll") for (int k = 0; k < 2; ++k) \
;         acc[ai][bj][m][n] = __builtin_amdgcn_mfma_f32_16x16x32_bf16(Bt[n][k], At[m][k], acc[ai][bj][m][n], 0, 0, 0); __builtin_amdgcn_s_setprio(0); } while (0)
; #define PG8_WAIT_V(n) asm volatile("s_waitcnt vmcnt(" #n ")" ::: "memory")
; #define PG8_WAIT_L(n) asm volatile("s_waitcnt lgkmcnt(" #n ")" ::: "memory")
; #define PG8_BAR __builtin_amdgcn_s_barrier()
; #define PG8_SCHED __builtin_amdgcn_sched_barrier(0)
; template <class Epi, class Sched, bool ALIGN_EPI = true, bool SP2 = true>
; __device__ __forceinline__ void gemm_phase(LAS unsigned char* lds, const Gemm g, const Sched& S, const Epi& E) {
;     ...
;             PG8_LDB(B0, 0, 0); PG8_LDB(B1, 0, 1); PG8_SCHED; PG8_LDA(At, 0, 0); PG8_STAGE(PG8_SA(1, 1), a1 + hstep, voffA);
;             PG8_WAIT_V(8); PG8_WAIT_L(0); PG8_BAR; PG8_MMA(0, 0, At, B0); PG8_MMA(0, 1, At, B1); PG8_BAR; PG8_SCHED;
;             PG8_LDA(At, 0, 1); PG8_STAGE(PG8_SB(0, 0), b2, voffB); PG8_STAGE(PG8_SB(0, 1), b2 + hstep, voffB); PG8_STAGE(PG8_SA(0, 0), a2, voffA);
;             PG8_WAIT_V(8); PG8_WAIT_L(0); PG8_BAR; PG8_MMA(1, 0, At, B0); PG8_MMA(1, 1, At, B1); PG8_BAR; PG8_SCHED;
.LBB0_138:
	ds_read_b128 v[130:133], v170
	ds_read_b128 v[134:137], v170 offset:1024
	ds_read_b128 v[176:179], v170 offset:2048
	ds_read_b128 v[180:183], v170 offset:3072
	ds_read_b128 v[184:187], v171
	ds_read_b128 v[188:191], v171 offset:1024
	ds_read_b128 v[192:195], v171 offset:2048
	ds_read_b128 v[196:199], v171 offset:3072
	s_add_u32 s40, s38, 0xfff00080
	s_addc_u32 s41, s39, -1
	s_cmp_eq_u32 s66, 60
	s_cselect_b32 s43, s5, s41
	s_cselect_b32 s42, s18, s40
	s_cselect_b32 s41, s27, s65
	s_cselect_b32 s40, s29, s64
	v_lshl_add_u64 v[216:217], s[38:39], 0, v[152:153]
	s_add_i32 m0, s37, 0xc000
	ds_read_b128 v[200:203], v172
	ds_read_b128 v[204:207], v172 offset:1024
	ds_read_b128 v[208:211], v172 offset:2048
	ds_read_b128 v[212:215], v172 offset:3072
	ds_read_b128 v[220:223], v172 offset:4096
	ds_read_b128 v[224:227], v172 offset:5120
	ds_read_b128 v[228:231], v172 offset:6144
	ds_read_b128 v[232:235], v172 offset:7168
	global_load_lds_dwordx4 v[216:217], off
	v_lshl_add_u64 v[216:217], s[38:39], 0, v[154:155]
	s_add_i32 m0, s37, 0xe000
	s_nop 0
	global_load_lds_dwordx4 v[216:217], off
	s_waitcnt vmcnt(8)
	s_waitcnt lgkmcnt(0)
	s_setprio 1
	s_barrier
	v_mfma_f32_16x16x32_bf16 v[126:129], v[130:133], v[200:203], v[126:129]
	v_mfma_f32_16x16x32_bf16 v[122:125], v[176:179], v[200:203], v[122:125]
	v_mfma_f32_16x16x32_bf16 v[106:109], v[176:179], v[208:211], v[106:109]
	v_mfma_f32_16x16x32_bf16 v[110:113], v[130:133], v[208:211], v[110:113]
	v_mfma_f32_16x16x32_bf16 v[94:97], v[130:133], v[220:223], v[94:97]
	v_mfma_f32_16x16x32_bf16 v[90:93], v[176:179], v[220:223], v[90:93]
	v_mfma_f32_16x16x32_bf16 v[74:77], v[176:179], v[228:231], v[74:77]
	v_mfma_f32_16x16x32_bf16 v[78:81], v[130:133], v[228:231], v[78:81]
	v_mfma_f32_16x16x32_bf16 v[126:129], v[134:137], v[204:207], v[126:129]
	v_mfma_f32_16x16x32_bf16 v[122:125], v[180:183], v[204:207], v[122:125]
	v_mfma_f32_16x16x32_bf16 v[106:109], v[180:183], v[212:215], v[106:109]
	v_mfma_f32_16x16x32_bf16 v[110:113], v[134:137], v[212:215], v[110:113]
	v_mfma_f32_16x16x32_bf16 v[94:97], v[134:137], v[224:227], v[94:97]
	v_mfma_f32_16x16x32_bf16 v[90:93], v[180:183], v[224:227], v[90:93]
	v_mfma_f32_16x16x32_bf16 v[74:77], v[180:183], v[232:235], v[74:77]
	v_mfma_f32_16x16x32_bf16 v[78:81], v[134:137], v[232:235], v[78:81]
	v_mfma_f32_16x16x32_bf16 v[118:121], v[184:187], v[200:203], v[118:121]
	v_mfma_f32_16x16x32_bf16 v[114:117], v[192:195], v[200:203], v[114:117]
	v_mfma_f32_16x16x32_bf16 v[98:101], v[192:195], v[208:211], v[98:101]
	v_mfma_f32_16x16x32_bf16 v[102:105], v[184:187], v[208:211], v[102:105]
	v_mfma_f32_16x16x32_bf16 v[86:89], v[184:187], v[220:223], v[86:89]
	v_mfma_f32_16x16x32_bf16 v[82:85], v[192:195], v[220:223], v[82:85]
	v_mfma_f32_16x16x32_bf16 v[66:69], v[192:195], v[228:231], v[66:69]
	v_mfma_f32_16x16x32_bf16 v[70:73], v[184:187], v[228:231], v[70:73]
	v_mfma_f32_16x16x32_bf16 v[118:121], v[188:191], v[204:207], v[118:121]
	v_mfma_f32_16x16x32_bf16 v[114:117], v[196:199], v[204:207], v[114:117]
	v_mfma_f32_16x16x32_bf16 v[98:101], v[196:199], v[212:215], v[98:101]
	v_mfma_f32_16x16x32_bf16 v[102:105], v[188:191], v[212:215], v[102:105]
	v_mfma_f32_16x16x32_bf16 v[86:89], v[188:191], v[224:227], v[86:89]
	v_mfma_f32_16x16x32_bf16 v[82:85], v[196:199], v[224:227], v[82:85]
	v_mfma_f32_16x16x32_bf16 v[66:69], v[196:199], v[232:235], v[66:69]
	v_mfma_f32_16x16x32_bf16 v[70:73], v[188:191], v[232:235], v[70:73]
	s_barrier
	s_setprio 0
	s_add_i32 s67, s60, s45
	v_lshl_add_u64 v[216:217], s[40:41], 0, v[140:141]
	s_mov_b32 m0, s67
	ds_read_b128 v[200:203], v172 offset:16384
	ds_read_b128 v[204:207], v172 offset:17408
	ds_read_b128 v[208:211], v172 offset:18432
	ds_read_b128 v[212:215], v172 offset:19456
	ds_read_b128 v[220:223], v172 offset:20480
	ds_read_b128 v[224:227], v172 offset:21504
	ds_read_b128 v[228:231], v172 offset:22528
	ds_read_b128 v[232:235], v172 offset:23552
	global_load_lds_dwordx4 v[216:217], off
	s_add_i32 m0, s67, 0x2000
	s_add_u32 s68, s40, 0x100000
	v_lshl_add_u64 v[218:219], s[40:41], 0, v[144:145]
	s_addc_u32 s69, s41, 0
	s_add_i32 s67, s61, s45
	global_load_lds_dwordx4 v[218:219], off
	v_lshl_add_u64 v[236:237], s[68:69], 0, v[140:141]
	s_mov_b32 m0, s67
	v_lshl_add_u64 v[238:239], s[42:43], 0, v[142:143]
	global_load_lds_dwordx4 v[236:237], off
	v_lshl_add_u64 v[236:237], s[68:69], 0, v[144:145]
	s_add_i32 m0, s67, 0x2000
	s_nop 0
	global_load_lds_dwordx4 v[236:237], off
	v_lshl_add_u64 v[236:237], s[42:43], 0, v[138:139]
	s_mov_b32 m0, s37
	s_nop 0
	global_load_lds_dwordx4 v[236:237], off
	s_mov_b32 m0, s47
	s_nop 0
	global_load_lds_dwordx4 v[238:239], off
	s_waitcnt vmcnt(8)
	s_waitcnt lgkmcnt(0)
	s_setprio 1
	s_barrier
; #define PG8_STAGE(bufoff, gbase, voff) do { _Pragma("unroll") for (int _i = 0; _i < 2; ++_i) \
;         __builtin_amdgcn_global_load_lds((const unsigned*)((const char*)(gbase) + (voff)[_i]), (LAS unsigned*)(lds + (bufoff) + ldsw + _i * 8192), 16, 0, 0); } while (0)
; #define PG8_LDA(dst, b, h) do { _Pragma("unroll") for (int m = 0; m < 4; ++m) _Pragma("unroll") for (int k = 0; k < 2; ++k) dst[m][k] = *(const LAS bf16x8*)(lds + PG8_SA(b, h) + aoff + m * 2048 + k * 1024); } while (0)
; #define PG8_LDB(dst, b, h) do { _Pragma("unroll") for (int n = 0; n < 2; ++n) _Pragma("unroll") for (int k = 0; k < 2; ++k) dst[n][k] = *(const LAS bf16x8*)(lds + PG8_SB(b, h) + boff + n * 2048 + k * 1024); } while (0)
; #define PG8_MMA(ai, bj, At, Bt) do { __builtin_amdgcn_s_setprio(1); _Pragma("unroll") for (int m = 0; m < 4; ++m) _Pragma("unroll") for (int n = 0; n < 2; ++n) _Pragma("unroll") for (int k = 0; k < 2; ++k) \
;         acc[ai][bj][m][n] = __builtin_amdgcn_mfma_f32_16x16x32_bf16(Bt[n][k], At[m][k], acc[ai][bj][m][n], 0, 0, 0); __builtin_amdgcn_s_setprio(0); } while (0)
; #define PG8_WAIT_V(n) asm volatile("s_waitcnt vmcnt(" #n ")" ::: "memory")
; #define PG8_WAIT_L(n) asm volatile("s_waitcnt lgkmcnt(" #n ")" ::: "memory")
; #define PG8_BAR __builtin_amdgcn_s_barrier()
; #define PG8_SCHED __builtin_amdgcn_sched_barrier(0)
; template <class Epi, class Sched, bool ALIGN_EPI = true, bool SP2 = true>
; __device__ __forceinline__ void gemm_phase(LAS unsigned char* lds, const Gemm g, const Sched& S, const Epi& E) {
;     ...
;             PG8_WAIT_V(8); PG8_WAIT_L(0); PG8_BAR; PG8_MMA(1, 0, At, B0); PG8_MMA(1, 1, At, B1); PG8_BAR; PG8_SCHED;
;             PG8_LDB(B0, 1, 0); PG8_LDB(B1, 1, 1); PG8_SCHED; PG8_LDA(At, 1, 0); PG8_STAGE(PG8_SA(0, 1), a2 + hstep, voffA);
;             PG8_WAIT_V(8); PG8_WAIT_L(0); PG8_BAR; PG8_MMA(0, 0, At, B0); PG8_MMA(0, 1, At, B1); PG8_BAR; PG8_SCHED;
	v_mfma_f32_16x16x32_bf16 v[62:65], v[130:133], v[200:203], v[62:65]
	v_mfma_f32_16x16x32_bf16 v[58:61], v[176:179], v[200:203], v[58:61]
	v_mfma_f32_16x16x32_bf16 v[42:45], v[176:179], v[208:211], v[42:45]
	v_mfma_f32_16x16x32_bf16 v[46:49], v[130:133], v[208:211], v[46:49]
	v_mfma_f32_16x16x32_bf16 v[30:33], v[130:133], v[220:223], v[30:33]
	v_mfma_f32_16x16x32_bf16 v[26:29], v[176:179], v[220:223], v[26:29]
	v_mfma_f32_16x16x32_bf16 v[10:13], v[176:179], v[228:231], v[10:13]
	v_mfma_f32_16x16x32_bf16 v[14:17], v[130:133], v[228:231], v[14:17]
	v_mfma_f32_16x16x32_bf16 v[62:65], v[134:137], v[204:207], v[62:65]
	v_mfma_f32_16x16x32_bf16 v[58:61], v[180:183], v[204:207], v[58:61]
	v_mfma_f32_16x16x32_bf16 v[42:45], v[180:183], v[212:215], v[42:45]
	v_mfma_f32_16x16x32_bf16 v[46:49], v[134:137], v[212:215], v[46:49]
	v_mfma_f32_16x16x32_bf16 v[30:33], v[134:137], v[224:227], v[30:33]
	v_mfma_f32_16x16x32_bf16 v[26:29], v[180:183], v[224:227], v[26:29]
	v_mfma_f32_16x16x32_bf16 v[10:13], v[180:183], v[232:235], v[10:13]
	v_mfma_f32_16x16x32_bf16 v[14:17], v[134:137], v[232:235], v[14:17]
	v_mfma_f32_16x16x32_bf16 v[54:57], v[184:187], v[200:203], v[54:57]
	v_mfma_f32_16x16x32_bf16 v[50:53], v[192:195], v[200:203], v[50:53]
	v_mfma_f32_16x16x32_bf16 v[34:37], v[192:195], v[208:211], v[34:37]
	v_mfma_f32_16x16x32_bf16 v[38:41], v[184:187], v[208:211], v[38:41]
	v_mfma_f32_16x16x32_bf16 v[22:25], v[184:187], v[220:223], v[22:25]
	v_mfma_f32_16x16x32_bf16 v[18:21], v[192:195], v[220:223], v[18:21]
	v_mfma_f32_16x16x32_bf16 v[2:5], v[192:195], v[228:231], v[2:5]
	v_mfma_f32_16x16x32_bf16 v[6:9], v[184:187], v[228:231], v[6:9]
	v_mfma_f32_16x16x32_bf16 v[54:57], v[188:191], v[204:207], v[54:57]
	v_mfma_f32_16x16x32_bf16 v[50:53], v[196:199], v[204:207], v[50:53]
	v_mfma_f32_16x16x32_bf16 v[34:37], v[196:199], v[212:215], v[34:37]
	v_mfma_f32_16x16x32_bf16 v[38:41], v[188:191], v[212:215], v[38:41]
	v_mfma_f32_16x16x32_bf16 v[22:25], v[188:191], v[224:227], v[22:25]
	v_mfma_f32_16x16x32_bf16 v[18:21], v[196:199], v[224:227], v[18:21]
	v_mfma_f32_16x16x32_bf16 v[2:5], v[196:199], v[232:235], v[2:5]
	v_mfma_f32_16x16x32_bf16 v[6:9], v[188:191], v[232:235], v[6:9]
	s_barrier
	s_setprio 0
	s_add_i32 s67, 0, 0x18000
	v_add_u32_e32 v146, s67, v160
	s_add_i32 s68, 0, 0x1c000
	ds_read_b128 v[130:133], v146
	ds_read_b128 v[134:137], v146 offset:1024
	ds_read_b128 v[176:179], v146 offset:2048
	ds_read_b128 v[180:183], v146 offset:3072
	v_add_u32_e32 v146, s68, v160
	ds_read_b128 v[184:187], v146
	ds_read_b128 v[188:191], v146 offset:1024
	ds_read_b128 v[192:195], v146 offset:2048
	ds_read_b128 v[196:199], v146 offset:3072
	s_add_u32 s42, s42, 0x100000
	s_addc_u32 s43, s43, 0
	s_mov_b32 m0, s48
	v_lshl_add_u64 v[240:241], s[42:43], 0, v[138:139]
	ds_read_b128 v[200:203], v172 offset:32768
	ds_read_b128 v[204:207], v172 offset:33792
	ds_read_b128 v[208:211], v172 offset:34816
	ds_read_b128 v[212:215], v172 offset:35840
	ds_read_b128 v[220:223], v172 offset:36864
	ds_read_b128 v[224:227], v172 offset:37888
	ds_read_b128 v[228:231], v172 offset:38912
	ds_read_b128 v[232:235], v172 offset:39936
	global_load_lds_dwordx4 v[240:241], off
	v_lshl_add_u64 v[240:241], s[42:43], 0, v[142:143]
	s_mov_b32 m0, s49
	s_nop 0
	global_load_lds_dwordx4 v[240:241], off
	s_waitcnt vmcnt(8)
	s_waitcnt lgkmcnt(0)
	s_setprio 1
	s_barrier
	v_mfma_f32_16x16x32_bf16 v[126:129], v[130:133], v[200:203], v[126:129]
	v_mfma_f32_16x16x32_bf16 v[122:125], v[176:179], v[200:203], v[122:125]
	v_mfma_f32_16x16x32_bf16 v[106:109], v[176:179], v[208:211], v[106:109]
	v_mfma_f32_16x16x32_bf16 v[110:113], v[130:133], v[208:211], v[110:113]
	v_mfma_f32_16x16x32_bf16 v[94:97], v[130:133], v[220:223], v[94:97]
	v_mfma_f32_16x16x32_bf16 v[90:93], v[176:179], v[220:223], v[90:93]
	v_mfma_f32_16x16x32_bf16 v[74:77], v[176:179], v[228:231], v[74:77]
	v_mfma_f32_16x16x32_bf16 v[78:81], v[130:133], v[228:231], v[78:81]
	v_mfma_f32_16x16x32_bf16 v[126:129], v[134:137], v[204:207], v[126:129]
	v_mfma_f32_16x16x32_bf16 v[122:125], v[180:183], v[204:207], v[122:125]
	v_mfma_f32_16x16x32_bf16 v[106:109], v[180:183], v[212:215], v[106:109]
	v_mfma_f32_16x16x32_bf16 v[110:113], v[134:137], v[212:215], v[110:113]
	v_mfma_f32_16x16x32_bf16 v[94:97], v[134:137], v[224:227], v[94:97]
	v_mfma_f32_16x16x32_bf16 v[90:93], v[180:183], v[224:227], v[90:93]
	v_mfma_f32_16x16x32_bf16 v[74:77], v[180:183], v[232:235], v[74:77]
	v_mfma_f32_16x16x32_bf16 v[78:81], v[134:137], v[232:235], v[78:81]
	v_mfma_f32_16x16x32_bf16 v[118:121], v[184:187], v[200:203], v[118:121]
	v_mfma_f32_16x16x32_bf16 v[114:117], v[192:195], v[200:203], v[114:117]
	v_mfma_f32_16x16x32_bf16 v[98:101], v[192:195], v[208:211], v[98:101]
	v_mfma_f32_16x16x32_bf16 v[102:105], v[184:187], v[208:211], v[102:105]
	v_mfma_f32_16x16x32_bf16 v[86:89], v[184:187], v[220:223], v[86:89]
	v_mfma_f32_16x16x32_bf16 v[82:85], v[192:195], v[220:223], v[82:85]
	v_mfma_f32_16x16x32_bf16 v[66:69], v[192:195], v[228:231], v[66:69]
	v_mfma_f32_16x16x32_bf16 v[70:73], v[184:187], v[228:231], v[70:73]
	v_mfma_f32_16x16x32_bf16 v[118:121], v[188:191], v[204:207], v[118:121]
	v_mfma_f32_16x16x32_bf16 v[114:117], v[196:199], v[204:207], v[114:117]
	v_mfma_f32_16x16x32_bf16 v[98:101], v[196:199], v[212:215], v[98:101]
	v_mfma_f32_16x16x32_bf16 v[102:105], v[188:191], v[212:215], v[102:105]
	v_mfma_f32_16x16x32_bf16 v[86:89], v[188:191], v[224:227], v[86:89]
	v_mfma_f32_16x16x32_bf16 v[82:85], v[196:199], v[224:227], v[82:85]
	v_mfma_f32_16x16x32_bf16 v[66:69], v[196:199], v[232:235], v[66:69]
	v_mfma_f32_16x16x32_bf16 v[70:73], v[188:191], v[232:235], v[70:73]
	s_barrier
; #define PG8_STAGE(bufoff, gbase, voff) do { _Pragma("unroll") for (int _i = 0; _i < 2; ++_i) \
;         __builtin_amdgcn_global_load_lds((const unsigned*)((const char*)(gbase) + (voff)[_i]), (LAS unsigned*)(lds + (bufoff) + ldsw + _i * 8192), 16, 0, 0); } while (0)
; #define PG8_LDA(dst, b, h) do { _Pragma("unroll") for (int m = 0; m < 4; ++m) _Pragma("unroll") for (int k = 0; k < 2; ++k) dst[m][k] = *(const LAS bf16x8*)(lds + PG8_SA(b, h) + aoff + m * 2048 + k * 1024); } while (0)
; #define PG8_MMA(ai, bj, At, Bt) do { __builtin_amdgcn_s_setprio(1); _Pragma("unroll") for (int m = 0; m < 4; ++m) _Pragma("unroll") for (int n = 0; n < 2; ++n) _Pragma("unroll") for (int k = 0; k < 2; ++k) \
;         acc[ai][bj][m][n] = __builtin_amdgcn_mfma_f32_16x16x32_bf16(Bt[n][k], At[m][k], acc[ai][bj][m][n], 0, 0, 0); __builtin_amdgcn_s_setprio(0); } while (0)
; #define PG8_WAIT_V(n) asm volatile("s_waitcnt vmcnt(" #n ")" ::: "memory")
; #define PG8_WAIT_L(n) asm volatile("s_waitcnt lgkmcnt(" #n ")" ::: "memory")
; #define PG8_BAR __builtin_amdgcn_s_barrier()
; #define PG8_SCHED __builtin_amdgcn_sched_barrier(0)
; template <class Epi, class Sched, bool ALIGN_EPI = true, bool SP2 = true>
; __device__ __forceinline__ void gemm_phase(LAS unsigned char* lds, const Gemm g, const Sched& S, const Epi& E) {
;     ...
;             PG8_WAIT_V(8); PG8_WAIT_L(0); PG8_BAR; PG8_MMA(0, 0, At, B0); PG8_MMA(0, 1, At, B1); PG8_BAR; PG8_SCHED;
;             PG8_LDA(At, 1, 1); PG8_STAGE(PG8_SB(1, 0), b3, voffB); PG8_STAGE(PG8_SB(1, 1), b3 + hstep, voffB); PG8_STAGE(PG8_SA(1, 0), a3, voffA);
;             PG8_WAIT_V(8); PG8_WAIT_L(0); PG8_BAR; PG8_MMA(1, 0, At, B0); PG8_MMA(1, 1, At, B1); PG8_BAR; PG8_SCHED;
;     ...
;         if constexpr (ALIGN_EPI) { if (wr == 0) PG8_BAR; }
	s_setprio 0
	s_add_i32 s42, s67, s45
	v_lshl_add_u64 v[216:217], v[216:217], 0, s[22:23]
	s_mov_b32 m0, s42
	ds_read_b128 v[200:203], v172 offset:49152
	ds_read_b128 v[204:207], v172 offset:50176
	ds_read_b128 v[208:211], v172 offset:51200
	ds_read_b128 v[212:215], v172 offset:52224
	ds_read_b128 v[220:223], v172 offset:53248
	ds_read_b128 v[224:227], v172 offset:54272
	ds_read_b128 v[228:231], v172 offset:55296
	ds_read_b128 v[232:235], v172 offset:56320
	global_load_lds_dwordx4 v[216:217], off
	s_add_i32 m0, s42, 0x2000
	s_add_u32 s40, s40, 0x100080
	v_lshl_add_u64 v[216:217], v[218:219], 0, s[22:23]
	s_addc_u32 s41, s41, 0
	s_add_i32 s42, s68, s45
	global_load_lds_dwordx4 v[216:217], off
	v_lshl_add_u64 v[216:217], s[40:41], 0, v[140:141]
	s_mov_b32 m0, s42
	s_nop 0
	global_load_lds_dwordx4 v[216:217], off
	v_lshl_add_u64 v[216:217], s[40:41], 0, v[144:145]
	s_add_i32 m0, s42, 0x2000
	s_nop 0
	global_load_lds_dwordx4 v[216:217], off
	v_lshl_add_u64 v[216:217], v[236:237], 0, s[22:23]
	s_mov_b32 m0, s54
	s_nop 0
	global_load_lds_dwordx4 v[216:217], off
	v_lshl_add_u64 v[216:217], v[238:239], 0, s[22:23]
	s_mov_b32 m0, s55
	s_nop 0
	global_load_lds_dwordx4 v[216:217], off
	s_waitcnt vmcnt(8)
	s_waitcnt lgkmcnt(0)
	s_setprio 1
	s_barrier
	v_mfma_f32_16x16x32_bf16 v[62:65], v[130:133], v[200:203], v[62:65]
	v_mfma_f32_16x16x32_bf16 v[58:61], v[176:179], v[200:203], v[58:61]
	v_mfma_f32_16x16x32_bf16 v[42:45], v[176:179], v[208:211], v[42:45]
	v_mfma_f32_16x16x32_bf16 v[46:49], v[130:133], v[208:211], v[46:49]
	v_mfma_f32_16x16x32_bf16 v[30:33], v[130:133], v[220:223], v[30:33]
	v_mfma_f32_16x16x32_bf16 v[26:29], v[176:179], v[220:223], v[26:29]
	v_mfma_f32_16x16x32_bf16 v[10:13], v[176:179], v[228:231], v[10:13]
	v_mfma_f32_16x16x32_bf16 v[14:17], v[130:133], v[228:231], v[14:17]
	v_mfma_f32_16x16x32_bf16 v[62:65], v[134:137], v[204:207], v[62:65]
	v_mfma_f32_16x16x32_bf16 v[58:61], v[180:183], v[204:207], v[58:61]
	v_mfma_f32_16x16x32_bf16 v[42:45], v[180:183], v[212:215], v[42:45]
	v_mfma_f32_16x16x32_bf16 v[46:49], v[134:137], v[212:215], v[46:49]
	v_mfma_f32_16x16x32_bf16 v[30:33], v[134:137], v[224:227], v[30:33]
	v_mfma_f32_16x16x32_bf16 v[26:29], v[180:183], v[224:227], v[26:29]
	v_mfma_f32_16x16x32_bf16 v[10:13], v[180:183], v[232:235], v[10:13]
	v_mfma_f32_16x16x32_bf16 v[14:17], v[134:137], v[232:235], v[14:17]
	v_mfma_f32_16x16x32_bf16 v[54:57], v[184:187], v[200:203], v[54:57]
	v_mfma_f32_16x16x32_bf16 v[50:53], v[192:195], v[200:203], v[50:53]
	v_mfma_f32_16x16x32_bf16 v[34:37], v[192:195], v[208:211], v[34:37]
	v_mfma_f32_16x16x32_bf16 v[38:41], v[184:187], v[208:211], v[38:41]
	v_mfma_f32_16x16x32_bf16 v[22:25], v[184:187], v[220:223], v[22:25]
	v_mfma_f32_16x16x32_bf16 v[18:21], v[192:195], v[220:223], v[18:21]
	v_mfma_f32_16x16x32_bf16 v[2:5], v[192:195], v[228:231], v[2:5]
	v_mfma_f32_16x16x32_bf16 v[6:9], v[184:187], v[228:231], v[6:9]
	v_mfma_f32_16x16x32_bf16 v[54:57], v[188:191], v[204:207], v[54:57]
	v_mfma_f32_16x16x32_bf16 v[50:53], v[196:199], v[204:207], v[50:53]
	v_mfma_f32_16x16x32_bf16 v[34:37], v[196:199], v[212:215], v[34:37]
	v_mfma_f32_16x16x32_bf16 v[38:41], v[188:191], v[212:215], v[38:41]
	v_mfma_f32_16x16x32_bf16 v[22:25], v[188:191], v[224:227], v[22:25]
	v_mfma_f32_16x16x32_bf16 v[18:21], v[196:199], v[224:227], v[18:21]
	v_mfma_f32_16x16x32_bf16 v[2:5], v[196:199], v[232:235], v[2:5]
	v_mfma_f32_16x16x32_bf16 v[6:9], v[188:191], v[232:235], v[6:9]
	s_barrier
	s_setprio 0
	s_add_i32 s66, s66, 2
	s_add_u32 s38, s38, 0x100
	s_addc_u32 s39, s39, 0
	s_add_u32 s64, s64, 0x100
	s_addc_u32 s65, s65, 0
	s_cmp_gt_u32 s66, 61
	s_cbranch_scc0 .LBB0_138
	s_and_b64 vcc, exec, s[24:25]
	s_cbranch_vccz .LBB0_141
	s_barrier

; #define PG8_STAGE(bufoff, gbase, voff) do { _Pragma("unroll") for (int _i = 0; _i < 2; ++_i) \
;         __builtin_amdgcn_global_load_lds((const unsigned*)((const char*)(gbase) + (voff)[_i]), (LAS unsigned*)(lds + (bufoff) + ldsw + _i * 8192), 16, 0, 0); } while (0)
; #define PG8_LDA(dst, b, h) do { _Pragma("unroll") for (int m = 0; m < 4; ++m) _Pragma("unroll") for (int k = 0; k < 2; ++k) dst[m][k] = *(const LAS bf16x8*)(lds + PG8_SA(b, h) + aoff + m * 2048 + k * 1024); } while (0)
; #define PG8_LDB(dst, b, h) do { _Pragma("unroll") for (int n = 0; n < 2; ++n) _Pragma("unroll") for (int k = 0; k < 2; ++k) dst[n][k] = *(const LAS bf16x8*)(lds + PG8_SB(b, h) + boff + n * 2048 + k * 1024); } while (0)
; #define PG8_MMA(ai, bj, At, Bt) do { __builtin_amdgcn_s_setprio(1); _Pragma("unroll") for (int m = 0; m < 4; ++m) _Pragma("unroll") for (int n = 0; n < 2; ++n) _Pragma("unroll") for (int k = 0; k < 2; ++k) \
;         acc[ai][bj][m][n] = __builtin_amdgcn_mfma_f32_16x16x32_bf16(Bt[n][k], At[m][k], acc[ai][bj][m][n], 0, 0, 0); __builtin_amdgcn_s_setprio(0); } while (0)
; #define PG8_BAR __builtin_amdgcn_s_barrier()
; template <class Epi, class Sched, bool ALIGN_EPI = true, bool SP2 = true>
; __device__ __forceinline__ void gemm_phase(LAS unsigned char* lds, const Gemm g, const Sched& S, const Epi& E) {
;     ...
;         const char* nA = has_next ? PG8_ABASE(nxt) : cA; const char* nB = has_next ? PG8_BBASE(nxt) : cB;
;         for (int t = 0; t < nt; t += 2) {
;             const bool last = (t == nt - 2);
;             const char* a1 = cA + (size_t)(t + 1) * kstep;
;             const char* a2 = last ? nA : cA + (size_t)(t + 2) * kstep; const char* b2 = last ? nB : cB + (size_t)(t + 2) * kstep;
;             const char* a3 = a2 + kstep; const char* b3 = b2 + kstep;
;             if (last && has_next) S.a_ready(nxt);
;             if constexpr (SP2) {
;             PG8_LDB(B0, 0, 0); PG8_LDB(B1, 0, 1); PG8_SCHED; PG8_LDA(At, 0, 0); PG8_STAGE(PG8_SA(1, 1), a1 + hstep, voffA);
;             PG8_WAIT_V(8); PG8_WAIT_L(0); PG8_BAR; PG8_MMA(0, 0, At, B0); PG8_MMA(0, 1, At, B1); PG8_BAR; PG8_SCHED;
;             PG8_LDA(At, 0, 1); PG8_STAGE(PG8_SB(0, 0), b2, voffB); PG8_STAGE(PG8_SB(0, 1), b2 + hstep, voffB); PG8_STAGE(PG8_SA(0, 0), a2, voffA);
;             PG8_WAIT_V(8); PG8_WAIT_L(0); PG8_BAR; PG8_MMA(1, 0, At, B0); PG8_MMA(1, 1, At, B1); PG8_BAR; PG8_SCHED;
.LBB0_451:
	ds_read_b128 v[146:149], v152
	ds_read_b128 v[156:159], v152 offset:1024
	ds_read_b128 v[160:163], v152 offset:2048
	ds_read_b128 v[164:167], v152 offset:3072
	ds_read_b128 v[168:171], v153
	ds_read_b128 v[172:175], v153 offset:1024
	ds_read_b128 v[176:179], v153 offset:2048
	ds_read_b128 v[180:183], v153 offset:3072
	s_add_u32 s22, s20, 0xfffc0080
	s_addc_u32 s23, s21, -1
	s_cmp_eq_u32 s49, 12
	s_cselect_b32 s25, s13, s23
	s_cselect_b32 s24, s45, s22
	s_cselect_b32 s23, s11, s48
	s_cselect_b32 s22, s46, s47
	v_lshl_add_u64 v[216:217], s[20:21], 0, v[138:139]
	s_add_i32 m0, s19, 0xc000
	ds_read_b128 v[184:187], v154
	ds_read_b128 v[188:191], v154 offset:1024
	ds_read_b128 v[192:195], v154 offset:2048
	ds_read_b128 v[196:199], v154 offset:3072
	ds_read_b128 v[200:203], v154 offset:4096
	ds_read_b128 v[204:207], v154 offset:5120
	ds_read_b128 v[208:211], v154 offset:6144
	ds_read_b128 v[212:215], v154 offset:7168
	global_load_lds_dwordx4 v[216:217], off
	v_lshl_add_u64 v[216:217], s[20:21], 0, v[140:141]
	s_add_i32 m0, s19, 0xe000
	s_nop 0
	global_load_lds_dwordx4 v[216:217], off
	s_waitcnt vmcnt(8)
	s_waitcnt lgkmcnt(0)
	s_setprio 1
	s_barrier
	v_mfma_f32_16x16x32_bf16 v[126:129], v[146:149], v[184:187], v[126:129]
	v_mfma_f32_16x16x32_bf16 v[122:125], v[160:163], v[184:187], v[122:125]
	v_mfma_f32_16x16x32_bf16 v[118:121], v[146:149], v[192:195], v[118:121]
	v_mfma_f32_16x16x32_bf16 v[110:113], v[160:163], v[192:195], v[110:113]
	v_mfma_f32_16x16x32_bf16 v[102:105], v[146:149], v[200:203], v[102:105]
	v_mfma_f32_16x16x32_bf16 v[94:97], v[160:163], v[200:203], v[94:97]
	v_mfma_f32_16x16x32_bf16 v[86:89], v[146:149], v[208:211], v[86:89]
	v_mfma_f32_16x16x32_bf16 v[78:81], v[160:163], v[208:211], v[78:81]
	v_mfma_f32_16x16x32_bf16 v[126:129], v[156:159], v[188:191], v[126:129]
	v_mfma_f32_16x16x32_bf16 v[122:125], v[164:167], v[188:191], v[122:125]
	v_mfma_f32_16x16x32_bf16 v[118:121], v[156:159], v[196:199], v[118:121]
	v_mfma_f32_16x16x32_bf16 v[110:113], v[164:167], v[196:199], v[110:113]
	v_mfma_f32_16x16x32_bf16 v[102:105], v[156:159], v[204:207], v[102:105]
	v_mfma_f32_16x16x32_bf16 v[94:97], v[164:167], v[204:207], v[94:97]
	v_mfma_f32_16x16x32_bf16 v[86:89], v[156:159], v[212:215], v[86:89]
	v_mfma_f32_16x16x32_bf16 v[78:81], v[164:167], v[212:215], v[78:81]
	v_mfma_f32_16x16x32_bf16 v[114:117], v[168:171], v[184:187], v[114:117]
	v_mfma_f32_16x16x32_bf16 v[106:109], v[176:179], v[184:187], v[106:109]
	v_mfma_f32_16x16x32_bf16 v[98:101], v[168:171], v[192:195], v[98:101]
	v_mfma_f32_16x16x32_bf16 v[90:93], v[176:179], v[192:195], v[90:93]
	v_mfma_f32_16x16x32_bf16 v[82:85], v[168:171], v[200:203], v[82:85]
	v_mfma_f32_16x16x32_bf16 v[74:77], v[176:179], v[200:203], v[74:77]
	v_mfma_f32_16x16x32_bf16 v[70:73], v[168:171], v[208:211], v[70:73]
	v_mfma_f32_16x16x32_bf16 v[66:69], v[176:179], v[208:211], v[66:69]
	v_mfma_f32_16x16x32_bf16 v[114:117], v[172:175], v[188:191], v[114:117]
	v_mfma_f32_16x16x32_bf16 v[106:109], v[180:183], v[188:191], v[106:109]
	v_mfma_f32_16x16x32_bf16 v[98:101], v[172:175], v[196:199], v[98:101]
	v_mfma_f32_16x16x32_bf16 v[90:93], v[180:183], v[196:199], v[90:93]
	v_mfma_f32_16x16x32_bf16 v[82:85], v[172:175], v[204:207], v[82:85]
	v_mfma_f32_16x16x32_bf16 v[74:77], v[180:183], v[204:207], v[74:77]
	v_mfma_f32_16x16x32_bf16 v[70:73], v[172:175], v[212:215], v[70:73]
	v_mfma_f32_16x16x32_bf16 v[66:69], v[180:183], v[212:215], v[66:69]
	s_barrier
	s_setprio 0
	s_add_i32 s50, s42, s31
	v_lshl_add_u64 v[216:217], s[22:23], 0, v[132:133]
	s_mov_b32 m0, s50
	ds_read_b128 v[184:187], v154 offset:16384
	ds_read_b128 v[188:191], v154 offset:17408
	ds_read_b128 v[192:195], v154 offset:18432
	ds_read_b128 v[196:199], v154 offset:19456
	ds_read_b128 v[200:203], v154 offset:20480
	ds_read_b128 v[204:207], v154 offset:21504
	ds_read_b128 v[208:211], v154 offset:22528
	ds_read_b128 v[212:215], v154 offset:23552
	global_load_lds_dwordx4 v[216:217], off
	s_add_i32 m0, s50, 0x2000
	s_add_u32 s50, s22, 0x40000
	v_lshl_add_u64 v[218:219], s[22:23], 0, v[136:137]
	s_addc_u32 s51, s23, 0
	s_add_i32 s52, s43, s31
	global_load_lds_dwordx4 v[218:219], off
	v_lshl_add_u64 v[220:221], s[50:51], 0, v[132:133]
	s_mov_b32 m0, s52
	v_lshl_add_u64 v[222:223], s[24:25], 0, v[134:135]
	global_load_lds_dwordx4 v[220:221], off
	v_lshl_add_u64 v[220:221], s[50:51], 0, v[136:137]
	s_add_i32 m0, s52, 0x2000
	s_nop 0
	global_load_lds_dwordx4 v[220:221], off
	v_lshl_add_u64 v[220:221], s[24:25], 0, v[130:131]
	s_mov_b32 m0, s19
	s_nop 0
	global_load_lds_dwordx4 v[220:221], off
	s_mov_b32 m0, s33
	s_nop 0
	global_load_lds_dwordx4 v[222:223], off
	s_waitcnt vmcnt(8)
	s_waitcnt lgkmcnt(0)
	s_setprio 1
	s_barrier
; #define PG8_STAGE(bufoff, gbase, voff) do { _Pragma("unroll") for (int _i = 0; _i < 2; ++_i) \
;         __builtin_amdgcn_global_load_lds((const unsigned*)((const char*)(gbase) + (voff)[_i]), (LAS unsigned*)(lds + (bufoff) + ldsw + _i * 8192), 16, 0, 0); } while (0)
; #define PG8_LDA(dst, b, h) do { _Pragma("unroll") for (int m = 0; m < 4; ++m) _Pragma("unroll") for (int k = 0; k < 2; ++k) dst[m][k] = *(const LAS bf16x8*)(lds + PG8_SA(b, h) + aoff + m * 2048 + k * 1024); } while (0)
; #define PG8_LDB(dst, b, h) do { _Pragma("unroll") for (int n = 0; n < 2; ++n) _Pragma("unroll") for (int k = 0; k < 2; ++k) dst[n][k] = *(const LAS bf16x8*)(lds + PG8_SB(b, h) + boff + n * 2048 + k * 1024); } while (0)
; #define PG8_MMA(ai, bj, At, Bt) do { __builtin_amdgcn_s_setprio(1); _Pragma("unroll") for (int m = 0; m < 4; ++m) _Pragma("unroll") for (int n = 0; n < 2; ++n) _Pragma("unroll") for (int k = 0; k < 2; ++k) \
;         acc[ai][bj][m][n] = __builtin_amdgcn_mfma_f32_16x16x32_bf16(Bt[n][k], At[m][k], acc[ai][bj][m][n], 0, 0, 0); __builtin_amdgcn_s_setprio(0); } while (0)
; #define PG8_WAIT_V(n) asm volatile("s_waitcnt vmcnt(" #n ")" ::: "memory")
; #define PG8_WAIT_L(n) asm volatile("s_waitcnt lgkmcnt(" #n ")" ::: "memory")
; #define PG8_BAR __builtin_amdgcn_s_barrier()
; #define PG8_SCHED __builtin_amdgcn_sched_barrier(0)
; template <class Epi, class Sched, bool ALIGN_EPI = true, bool SP2 = true>
; __device__ __forceinline__ void gemm_phase(LAS unsigned char* lds, const Gemm g, const Sched& S, const Epi& E) {
;     ...
;             PG8_WAIT_V(8); PG8_WAIT_L(0); PG8_BAR; PG8_MMA(1, 0, At, B0); PG8_MMA(1, 1, At, B1); PG8_BAR; PG8_SCHED;
;             PG8_LDB(B0, 1, 0); PG8_LDB(B1, 1, 1); PG8_SCHED; PG8_LDA(At, 1, 0); PG8_STAGE(PG8_SA(0, 1), a2 + hstep, voffA);
;             PG8_WAIT_V(8); PG8_WAIT_L(0); PG8_BAR; PG8_MMA(0, 0, At, B0); PG8_MMA(0, 1, At, B1); PG8_BAR; PG8_SCHED;
	v_mfma_f32_16x16x32_bf16 v[62:65], v[146:149], v[184:187], v[62:65]
	v_mfma_f32_16x16x32_bf16 v[58:61], v[160:163], v[184:187], v[58:61]
	v_mfma_f32_16x16x32_bf16 v[54:57], v[146:149], v[192:195], v[54:57]
	v_mfma_f32_16x16x32_bf16 v[46:49], v[160:163], v[192:195], v[46:49]
	v_mfma_f32_16x16x32_bf16 v[38:41], v[146:149], v[200:203], v[38:41]
	v_mfma_f32_16x16x32_bf16 v[30:33], v[160:163], v[200:203], v[30:33]
	v_mfma_f32_16x16x32_bf16 v[22:25], v[146:149], v[208:211], v[22:25]
	v_mfma_f32_16x16x32_bf16 v[14:17], v[160:163], v[208:211], v[14:17]
	v_mfma_f32_16x16x32_bf16 v[62:65], v[156:159], v[188:191], v[62:65]
	v_mfma_f32_16x16x32_bf16 v[58:61], v[164:167], v[188:191], v[58:61]
	v_mfma_f32_16x16x32_bf16 v[54:57], v[156:159], v[196:199], v[54:57]
	v_mfma_f32_16x16x32_bf16 v[46:49], v[164:167], v[196:199], v[46:49]
	v_mfma_f32_16x16x32_bf16 v[38:41], v[156:159], v[204:207], v[38:41]
	v_mfma_f32_16x16x32_bf16 v[30:33], v[164:167], v[204:207], v[30:33]
	v_mfma_f32_16x16x32_bf16 v[22:25], v[156:159], v[212:215], v[22:25]
	v_mfma_f32_16x16x32_bf16 v[14:17], v[164:167], v[212:215], v[14:17]
	v_mfma_f32_16x16x32_bf16 v[50:53], v[168:171], v[184:187], v[50:53]
	v_mfma_f32_16x16x32_bf16 v[42:45], v[176:179], v[184:187], v[42:45]
	v_mfma_f32_16x16x32_bf16 v[34:37], v[168:171], v[192:195], v[34:37]
	v_mfma_f32_16x16x32_bf16 v[26:29], v[176:179], v[192:195], v[26:29]
	v_mfma_f32_16x16x32_bf16 v[18:21], v[168:171], v[200:203], v[18:21]
	v_mfma_f32_16x16x32_bf16 v[10:13], v[176:179], v[200:203], v[10:13]
	v_mfma_f32_16x16x32_bf16 v[6:9], v[168:171], v[208:211], v[6:9]
	v_mfma_f32_16x16x32_bf16 v[2:5], v[176:179], v[208:211], v[2:5]
	v_mfma_f32_16x16x32_bf16 v[50:53], v[172:175], v[188:191], v[50:53]
	v_mfma_f32_16x16x32_bf16 v[42:45], v[180:183], v[188:191], v[42:45]
	v_mfma_f32_16x16x32_bf16 v[34:37], v[172:175], v[196:199], v[34:37]
	v_mfma_f32_16x16x32_bf16 v[26:29], v[180:183], v[196:199], v[26:29]
	v_mfma_f32_16x16x32_bf16 v[18:21], v[172:175], v[204:207], v[18:21]
	v_mfma_f32_16x16x32_bf16 v[10:13], v[180:183], v[204:207], v[10:13]
	v_mfma_f32_16x16x32_bf16 v[6:9], v[172:175], v[212:215], v[6:9]
	v_mfma_f32_16x16x32_bf16 v[2:5], v[180:183], v[212:215], v[2:5]
	s_barrier
	s_setprio 0
	s_add_i32 s50, 0, 0x18000
	v_add_u32_e32 v155, s50, v150
	s_add_i32 s51, 0, 0x1c000
	ds_read_b128 v[146:149], v155
	ds_read_b128 v[156:159], v155 offset:1024
	ds_read_b128 v[160:163], v155 offset:2048
	ds_read_b128 v[164:167], v155 offset:3072
	v_add_u32_e32 v155, s51, v150
	ds_read_b128 v[168:171], v155
	ds_read_b128 v[172:175], v155 offset:1024
	ds_read_b128 v[176:179], v155 offset:2048
	ds_read_b128 v[180:183], v155 offset:3072
	s_add_u32 s24, s24, 0x40000
	s_addc_u32 s25, s25, 0
	s_mov_b32 m0, s34
	v_lshl_add_u64 v[224:225], s[24:25], 0, v[130:131]
	ds_read_b128 v[184:187], v154 offset:32768
	ds_read_b128 v[188:191], v154 offset:33792
	ds_read_b128 v[192:195], v154 offset:34816
	ds_read_b128 v[196:199], v154 offset:35840
	ds_read_b128 v[200:203], v154 offset:36864
	ds_read_b128 v[204:207], v154 offset:37888
	ds_read_b128 v[208:211], v154 offset:38912
	ds_read_b128 v[212:215], v154 offset:39936
	global_load_lds_dwordx4 v[224:225], off
	v_lshl_add_u64 v[224:225], s[24:25], 0, v[134:135]
	s_mov_b32 m0, s35
	s_nop 0
	global_load_lds_dwordx4 v[224:225], off
	s_waitcnt vmcnt(8)
	s_waitcnt lgkmcnt(0)
	s_setprio 1
	s_barrier
	v_mfma_f32_16x16x32_bf16 v[126:129], v[146:149], v[184:187], v[126:129]
	v_mfma_f32_16x16x32_bf16 v[122:125], v[160:163], v[184:187], v[122:125]
	v_mfma_f32_16x16x32_bf16 v[118:121], v[146:149], v[192:195], v[118:121]
	v_mfma_f32_16x16x32_bf16 v[110:113], v[160:163], v[192:195], v[110:113]
	v_mfma_f32_16x16x32_bf16 v[102:105], v[146:149], v[200:203], v[102:105]
	v_mfma_f32_16x16x32_bf16 v[94:97], v[160:163], v[200:203], v[94:97]
	v_mfma_f32_16x16x32_bf16 v[86:89], v[146:149], v[208:211], v[86:89]
	v_mfma_f32_16x16x32_bf16 v[78:81], v[160:163], v[208:211], v[78:81]
	v_mfma_f32_16x16x32_bf16 v[126:129], v[156:159], v[188:191], v[126:129]
	v_mfma_f32_16x16x32_bf16 v[122:125], v[164:167], v[188:191], v[122:125]
	v_mfma_f32_16x16x32_bf16 v[118:121], v[156:159], v[196:199], v[118:121]
	v_mfma_f32_16x16x32_bf16 v[110:113], v[164:167], v[196:199], v[110:113]
	v_mfma_f32_16x16x32_bf16 v[102:105], v[156:159], v[204:207], v[102:105]
	v_mfma_f32_16x16x32_bf16 v[94:97], v[164:167], v[204:207], v[94:97]
	v_mfma_f32_16x16x32_bf16 v[86:89], v[156:159], v[212:215], v[86:89]
	v_mfma_f32_16x16x32_bf16 v[78:81], v[164:167], v[212:215], v[78:81]
	v_mfma_f32_16x16x32_bf16 v[114:117], v[168:171], v[184:187], v[114:117]
	v_mfma_f32_16x16x32_bf16 v[106:109], v[176:179], v[184:187], v[106:109]
	v_mfma_f32_16x16x32_bf16 v[98:101], v[168:171], v[192:195], v[98:101]
	v_mfma_f32_16x16x32_bf16 v[90:93], v[176:179], v[192:195], v[90:93]
	v_mfma_f32_16x16x32_bf16 v[82:85], v[168:171], v[200:203], v[82:85]
	v_mfma_f32_16x16x32_bf16 v[74:77], v[176:179], v[200:203], v[74:77]
	v_mfma_f32_16x16x32_bf16 v[70:73], v[168:171], v[208:211], v[70:73]
	v_mfma_f32_16x16x32_bf16 v[66:69], v[176:179], v[208:211], v[66:69]
	v_mfma_f32_16x16x32_bf16 v[114:117], v[172:175], v[188:191], v[114:117]
	v_mfma_f32_16x16x32_bf16 v[106:109], v[180:183], v[188:191], v[106:109]
	v_mfma_f32_16x16x32_bf16 v[98:101], v[172:175], v[196:199], v[98:101]
	v_mfma_f32_16x16x32_bf16 v[90:93], v[180:183], v[196:199], v[90:93]
	v_mfma_f32_16x16x32_bf16 v[82:85], v[172:175], v[204:207], v[82:85]
	v_mfma_f32_16x16x32_bf16 v[74:77], v[180:183], v[204:207], v[74:77]
	v_mfma_f32_16x16x32_bf16 v[70:73], v[172:175], v[212:215], v[70:73]
	v_mfma_f32_16x16x32_bf16 v[66:69], v[180:183], v[212:215], v[66:69]
	s_barrier
; #define PG8_STAGE(bufoff, gbase, voff) do { _Pragma("unroll") for (int _i = 0; _i < 2; ++_i) \
;         __builtin_amdgcn_global_load_lds((const unsigned*)((const char*)(gbase) + (voff)[_i]), (LAS unsigned*)(lds + (bufoff) + ldsw + _i * 8192), 16, 0, 0); } while (0)
; #define PG8_LDA(dst, b, h) do { _Pragma("unroll") for (int m = 0; m < 4; ++m) _Pragma("unroll") for (int k = 0; k < 2; ++k) dst[m][k] = *(const LAS bf16x8*)(lds + PG8_SA(b, h) + aoff + m * 2048 + k * 1024); } while (0)
; #define PG8_MMA(ai, bj, At, Bt) do { __builtin_amdgcn_s_setprio(1); _Pragma("unroll") for (int m = 0; m < 4; ++m) _Pragma("unroll") for (int n = 0; n < 2; ++n) _Pragma("unroll") for (int k = 0; k < 2; ++k) \
;         acc[ai][bj][m][n] = __builtin_amdgcn_mfma_f32_16x16x32_bf16(Bt[n][k], At[m][k], acc[ai][bj][m][n], 0, 0, 0); __builtin_amdgcn_s_setprio(0); } while (0)
; #define PG8_WAIT_V(n) asm volatile("s_waitcnt vmcnt(" #n ")" ::: "memory")
; #define PG8_WAIT_L(n) asm volatile("s_waitcnt lgkmcnt(" #n ")" ::: "memory")
; #define PG8_BAR __builtin_amdgcn_s_barrier()
; #define PG8_SCHED __builtin_amdgcn_sched_barrier(0)
; template <class Epi, class Sched, bool ALIGN_EPI = true, bool SP2 = true>
; __device__ __forceinline__ void gemm_phase(LAS unsigned char* lds, const Gemm g, const Sched& S, const Epi& E) {
;     ...
;             PG8_WAIT_V(8); PG8_WAIT_L(0); PG8_BAR; PG8_MMA(0, 0, At, B0); PG8_MMA(0, 1, At, B1); PG8_BAR; PG8_SCHED;
;             PG8_LDA(At, 1, 1); PG8_STAGE(PG8_SB(1, 0), b3, voffB); PG8_STAGE(PG8_SB(1, 1), b3 + hstep, voffB); PG8_STAGE(PG8_SA(1, 0), a3, voffA);
;             PG8_WAIT_V(8); PG8_WAIT_L(0); PG8_BAR; PG8_MMA(1, 0, At, B0); PG8_MMA(1, 1, At, B1); PG8_BAR; PG8_SCHED;
;     ...
;         if constexpr (ALIGN_EPI) { if (wr == 0) PG8_BAR; }
	s_setprio 0
	s_add_i32 s24, s50, s31
	v_lshl_add_u64 v[216:217], v[216:217], 0, s[6:7]
	s_mov_b32 m0, s24
	ds_read_b128 v[184:187], v154 offset:49152
	ds_read_b128 v[188:191], v154 offset:50176
	ds_read_b128 v[192:195], v154 offset:51200
	ds_read_b128 v[196:199], v154 offset:52224
	ds_read_b128 v[200:203], v154 offset:53248
	ds_read_b128 v[204:207], v154 offset:54272
	ds_read_b128 v[208:211], v154 offset:55296
	ds_read_b128 v[212:215], v154 offset:56320
	global_load_lds_dwordx4 v[216:217], off
	s_add_i32 m0, s24, 0x2000
	s_add_u32 s22, s22, 0x40080
	v_lshl_add_u64 v[216:217], v[218:219], 0, s[6:7]
	s_addc_u32 s23, s23, 0
	s_add_i32 s24, s51, s31
	global_load_lds_dwordx4 v[216:217], off
	v_lshl_add_u64 v[216:217], s[22:23], 0, v[132:133]
	s_mov_b32 m0, s24
	s_nop 0
	global_load_lds_dwordx4 v[216:217], off
	v_lshl_add_u64 v[216:217], s[22:23], 0, v[136:137]
	s_add_i32 m0, s24, 0x2000
	s_nop 0
	global_load_lds_dwordx4 v[216:217], off
	v_lshl_add_u64 v[216:217], v[220:221], 0, s[6:7]
	s_mov_b32 m0, s39
	s_nop 0
	global_load_lds_dwordx4 v[216:217], off
	v_lshl_add_u64 v[216:217], v[222:223], 0, s[6:7]
	s_mov_b32 m0, s40
	s_nop 0
	global_load_lds_dwordx4 v[216:217], off
	s_waitcnt vmcnt(8)
	s_waitcnt lgkmcnt(0)
	s_setprio 1
	s_barrier
	v_mfma_f32_16x16x32_bf16 v[62:65], v[146:149], v[184:187], v[62:65]
	v_mfma_f32_16x16x32_bf16 v[58:61], v[160:163], v[184:187], v[58:61]
	v_mfma_f32_16x16x32_bf16 v[54:57], v[146:149], v[192:195], v[54:57]
	v_mfma_f32_16x16x32_bf16 v[46:49], v[160:163], v[192:195], v[46:49]
	v_mfma_f32_16x16x32_bf16 v[38:41], v[146:149], v[200:203], v[38:41]
	v_mfma_f32_16x16x32_bf16 v[30:33], v[160:163], v[200:203], v[30:33]
	v_mfma_f32_16x16x32_bf16 v[22:25], v[146:149], v[208:211], v[22:25]
	v_mfma_f32_16x16x32_bf16 v[14:17], v[160:163], v[208:211], v[14:17]
	v_mfma_f32_16x16x32_bf16 v[62:65], v[156:159], v[188:191], v[62:65]
	v_mfma_f32_16x16x32_bf16 v[58:61], v[164:167], v[188:191], v[58:61]
	v_mfma_f32_16x16x32_bf16 v[54:57], v[156:159], v[196:199], v[54:57]
	v_mfma_f32_16x16x32_bf16 v[46:49], v[164:167], v[196:199], v[46:49]
	v_mfma_f32_16x16x32_bf16 v[38:41], v[156:159], v[204:207], v[38:41]
	v_mfma_f32_16x16x32_bf16 v[30:33], v[164:167], v[204:207], v[30:33]
	v_mfma_f32_16x16x32_bf16 v[22:25], v[156:159], v[212:215], v[22:25]
	v_mfma_f32_16x16x32_bf16 v[14:17], v[164:167], v[212:215], v[14:17]
	v_mfma_f32_16x16x32_bf16 v[50:53], v[168:171], v[184:187], v[50:53]
	v_mfma_f32_16x16x32_bf16 v[42:45], v[176:179], v[184:187], v[42:45]
	v_mfma_f32_16x16x32_bf16 v[34:37], v[168:171], v[192:195], v[34:37]
	v_mfma_f32_16x16x32_bf16 v[26:29], v[176:179], v[192:195], v[26:29]
	v_mfma_f32_16x16x32_bf16 v[18:21], v[168:171], v[200:203], v[18:21]
	v_mfma_f32_16x16x32_bf16 v[10:13], v[176:179], v[200:203], v[10:13]
	v_mfma_f32_16x16x32_bf16 v[6:9], v[168:171], v[208:211], v[6:9]
	v_mfma_f32_16x16x32_bf16 v[2:5], v[176:179], v[208:211], v[2:5]
	v_mfma_f32_16x16x32_bf16 v[50:53], v[172:175], v[188:191], v[50:53]
	v_mfma_f32_16x16x32_bf16 v[42:45], v[180:183], v[188:191], v[42:45]
	v_mfma_f32_16x16x32_bf16 v[34:37], v[172:175], v[196:199], v[34:37]
	v_mfma_f32_16x16x32_bf16 v[26:29], v[180:183], v[196:199], v[26:29]
	v_mfma_f32_16x16x32_bf16 v[18:21], v[172:175], v[204:207], v[18:21]
	v_mfma_f32_16x16x32_bf16 v[10:13], v[180:183], v[204:207], v[10:13]
	v_mfma_f32_16x16x32_bf16 v[6:9], v[172:175], v[212:215], v[6:9]
	v_mfma_f32_16x16x32_bf16 v[2:5], v[180:183], v[212:215], v[2:5]
	s_barrier
	s_setprio 0
	s_add_i32 s49, s49, 2
	s_add_u32 s20, s20, 0x100
	s_addc_u32 s21, s21, 0
	s_add_u32 s47, s47, 0x100
	s_addc_u32 s48, s48, 0
	s_cmp_gt_u32 s49, 13
	s_cbranch_scc0 .LBB0_451
	s_and_b64 vcc, exec, s[8:9]
	s_cbranch_vccz .LBB0_454
	s_barrier

; #define PG8_STAGE(bufoff, gbase, voff) do { _Pragma("unroll") for (int _i = 0; _i < 2; ++_i) \
;         __builtin_amdgcn_global_load_lds((const unsigned*)((const char*)(gbase) + (voff)[_i]), (LAS unsigned*)(lds + (bufoff) + ldsw + _i * 8192), 16, 0, 0); } while (0)
; #define PG8_LDA(dst, b, h) do { _Pragma("unroll") for (int m = 0; m < 4; ++m) _Pragma("unroll") for (int k = 0; k < 2; ++k) dst[m][k] = *(const LAS bf16x8*)(lds + PG8_SA(b, h) + aoff + m * 2048 + k * 1024); } while (0)
; #define PG8_LDB(dst, b, h) do { _Pragma("unroll") for (int n = 0; n < 2; ++n) _Pragma("unroll") for (int k = 0; k < 2; ++k) dst[n][k] = *(const LAS bf16x8*)(lds + PG8_SB(b, h) + boff + n * 2048 + k * 1024); } while (0)
; #define PG8_MMA(ai, bj, At, Bt) do { __builtin_amdgcn_s_setprio(1); _Pragma("unroll") for (int m = 0; m < 4; ++m) _Pragma("unroll") for (int n = 0; n < 2; ++n) _Pragma("unroll") for (int k = 0; k < 2; ++k) \
;         acc[ai][bj][m][n] = __builtin_amdgcn_mfma_f32_16x16x32_bf16(Bt[n][k], At[m][k], acc[ai][bj][m][n], 0, 0, 0); __builtin_amdgcn_s_setprio(0); } while (0)
; #define PG8_BAR __builtin_amdgcn_s_barrier()
; template <class Epi, class Sched, bool ALIGN_EPI = true, bool SP2 = true>
; __device__ __forceinline__ void gemm_phase(LAS unsigned char* lds, const Gemm g, const Sched& S, const Epi& E) {
;     ...
;         const char* nA = has_next ? PG8_ABASE(nxt) : cA; const char* nB = has_next ? PG8_BBASE(nxt) : cB;
;         for (int t = 0; t < nt; t += 2) {
;             const bool last = (t == nt - 2);
;             const char* a1 = cA + (size_t)(t + 1) * kstep;
;             const char* a2 = last ? nA : cA + (size_t)(t + 2) * kstep; const char* b2 = last ? nB : cB + (size_t)(t + 2) * kstep;
;             const char* a3 = a2 + kstep; const char* b3 = b2 + kstep;
;             if (last && has_next) S.a_ready(nxt);
;             if constexpr (SP2) {
;             PG8_LDB(B0, 0, 0); PG8_LDB(B1, 0, 1); PG8_SCHED; PG8_LDA(At, 0, 0); PG8_STAGE(PG8_SA(1, 1), a1 + hstep, voffA);
;             PG8_WAIT_V(8); PG8_WAIT_L(0); PG8_BAR; PG8_MMA(0, 0, At, B0); PG8_MMA(0, 1, At, B1); PG8_BAR; PG8_SCHED;
;             PG8_LDA(At, 0, 1); PG8_STAGE(PG8_SB(0, 0), b2, voffB); PG8_STAGE(PG8_SB(0, 1), b2 + hstep, voffB); PG8_STAGE(PG8_SA(0, 0), a2, voffA);
;             PG8_WAIT_V(8); PG8_WAIT_L(0); PG8_BAR; PG8_MMA(1, 0, At, B0); PG8_MMA(1, 1, At, B1); PG8_BAR; PG8_SCHED;
.LBB0_1460:
	ds_read_b128 v[114:117], v221
	ds_read_b128 v[118:121], v221 offset:1024
	ds_read_b128 v[130:133], v221 offset:2048
	ds_read_b128 v[134:137], v221 offset:3072
	ds_read_b128 v[142:145], v222
	ds_read_b128 v[150:153], v222 offset:1024
	ds_read_b128 v[154:157], v222 offset:2048
	ds_read_b128 v[158:161], v222 offset:3072
	s_add_u32 s36, s34, 0xfff80080
	s_addc_u32 s37, s35, -1
	s_cmp_eq_u32 s64, 28
	s_cselect_b32 s39, s25, s37
	s_cselect_b32 s38, s31, s36
	s_cselect_b32 s37, s23, s63
	s_cselect_b32 s36, s61, s62
	v_lshl_add_u64 v[210:211], s[34:35], 0, v[202:203]
	s_add_i32 m0, s44, 0xc000
	ds_read_b128 v[162:165], v223
	ds_read_b128 v[166:169], v223 offset:1024
	ds_read_b128 v[170:173], v223 offset:2048
	ds_read_b128 v[174:177], v223 offset:3072
	ds_read_b128 v[178:181], v223 offset:4096
	ds_read_b128 v[182:185], v223 offset:5120
	ds_read_b128 v[186:189], v223 offset:6144
	ds_read_b128 v[190:193], v223 offset:7168
	global_load_lds_dwordx4 v[210:211], off
	v_lshl_add_u64 v[210:211], s[34:35], 0, v[204:205]
	s_add_i32 m0, s44, 0xe000
	s_nop 0
	global_load_lds_dwordx4 v[210:211], off
	s_waitcnt vmcnt(8)
	s_waitcnt lgkmcnt(0)
	s_setprio 1
	s_barrier
	v_mfma_f32_16x16x32_bf16 v[146:149], v[114:117], v[162:165], v[146:149]
	v_mfma_f32_16x16x32_bf16 v[138:141], v[130:133], v[162:165], v[138:141]
	v_mfma_f32_16x16x32_bf16 v[110:113], v[114:117], v[170:173], v[110:113]
	v_mfma_f32_16x16x32_bf16 v[106:109], v[130:133], v[170:173], v[106:109]
	v_mfma_f32_16x16x32_bf16 v[94:97], v[114:117], v[178:181], v[94:97]
	v_mfma_f32_16x16x32_bf16 v[90:93], v[130:133], v[178:181], v[90:93]
	v_mfma_f32_16x16x32_bf16 v[78:81], v[114:117], v[186:189], v[78:81]
	v_mfma_f32_16x16x32_bf16 v[74:77], v[130:133], v[186:189], v[74:77]
	v_mfma_f32_16x16x32_bf16 v[146:149], v[118:121], v[166:169], v[146:149]
	v_mfma_f32_16x16x32_bf16 v[138:141], v[134:137], v[166:169], v[138:141]
	v_mfma_f32_16x16x32_bf16 v[110:113], v[118:121], v[174:177], v[110:113]
	v_mfma_f32_16x16x32_bf16 v[106:109], v[134:137], v[174:177], v[106:109]
	v_mfma_f32_16x16x32_bf16 v[94:97], v[118:121], v[182:185], v[94:97]
	v_mfma_f32_16x16x32_bf16 v[90:93], v[134:137], v[182:185], v[90:93]
	v_mfma_f32_16x16x32_bf16 v[78:81], v[118:121], v[190:193], v[78:81]
	v_mfma_f32_16x16x32_bf16 v[74:77], v[134:137], v[190:193], v[74:77]
	v_mfma_f32_16x16x32_bf16 v[126:129], v[142:145], v[162:165], v[126:129]
	v_mfma_f32_16x16x32_bf16 v[122:125], v[154:157], v[162:165], v[122:125]
	v_mfma_f32_16x16x32_bf16 v[102:105], v[142:145], v[170:173], v[102:105]
	v_mfma_f32_16x16x32_bf16 v[98:101], v[154:157], v[170:173], v[98:101]
	v_mfma_f32_16x16x32_bf16 v[86:89], v[142:145], v[178:181], v[86:89]
	v_mfma_f32_16x16x32_bf16 v[82:85], v[154:157], v[178:181], v[82:85]
	v_mfma_f32_16x16x32_bf16 v[70:73], v[142:145], v[186:189], v[70:73]
	v_mfma_f32_16x16x32_bf16 v[66:69], v[154:157], v[186:189], v[66:69]
	v_mfma_f32_16x16x32_bf16 v[126:129], v[150:153], v[166:169], v[126:129]
	v_mfma_f32_16x16x32_bf16 v[122:125], v[158:161], v[166:169], v[122:125]
	v_mfma_f32_16x16x32_bf16 v[102:105], v[150:153], v[174:177], v[102:105]
	v_mfma_f32_16x16x32_bf16 v[98:101], v[158:161], v[174:177], v[98:101]
	v_mfma_f32_16x16x32_bf16 v[86:89], v[150:153], v[182:185], v[86:89]
	v_mfma_f32_16x16x32_bf16 v[82:85], v[158:161], v[182:185], v[82:85]
	v_mfma_f32_16x16x32_bf16 v[70:73], v[150:153], v[190:193], v[70:73]
	v_mfma_f32_16x16x32_bf16 v[66:69], v[158:161], v[190:193], v[66:69]
	s_barrier
	s_setprio 0
	s_add_i32 s65, s57, s43
	v_lshl_add_u64 v[210:211], s[36:37], 0, v[196:197]
	s_mov_b32 m0, s65
	ds_read_b128 v[162:165], v223 offset:16384
	ds_read_b128 v[166:169], v223 offset:17408
	ds_read_b128 v[170:173], v223 offset:18432
	ds_read_b128 v[174:177], v223 offset:19456
	ds_read_b128 v[178:181], v223 offset:20480
	ds_read_b128 v[182:185], v223 offset:21504
	ds_read_b128 v[186:189], v223 offset:22528
	ds_read_b128 v[190:193], v223 offset:23552
	global_load_lds_dwordx4 v[210:211], off
	s_add_i32 m0, s65, 0x2000
	s_add_u32 s66, s36, 0x80000
	v_lshl_add_u64 v[212:213], s[36:37], 0, v[200:201]
	s_addc_u32 s67, s37, 0
	s_add_i32 s65, s58, s43
	global_load_lds_dwordx4 v[212:213], off
	v_lshl_add_u64 v[214:215], s[66:67], 0, v[196:197]
	s_mov_b32 m0, s65
	v_lshl_add_u64 v[216:217], s[38:39], 0, v[198:199]
	global_load_lds_dwordx4 v[214:215], off
	v_lshl_add_u64 v[214:215], s[66:67], 0, v[200:201]
	s_add_i32 m0, s65, 0x2000
	s_nop 0
	global_load_lds_dwordx4 v[214:215], off
	v_lshl_add_u64 v[214:215], s[38:39], 0, v[194:195]
	s_mov_b32 m0, s44
	s_nop 0
	global_load_lds_dwordx4 v[214:215], off
	s_mov_b32 m0, s45
	s_nop 0
	global_load_lds_dwordx4 v[216:217], off
	s_waitcnt vmcnt(8)
	s_waitcnt lgkmcnt(0)
	s_setprio 1
	s_barrier
; #define PG8_STAGE(bufoff, gbase, voff) do { _Pragma("unroll") for (int _i = 0; _i < 2; ++_i) \
;         __builtin_amdgcn_global_load_lds((const unsigned*)((const char*)(gbase) + (voff)[_i]), (LAS unsigned*)(lds + (bufoff) + ldsw + _i * 8192), 16, 0, 0); } while (0)
; #define PG8_LDA(dst, b, h) do { _Pragma("unroll") for (int m = 0; m < 4; ++m) _Pragma("unroll") for (int k = 0; k < 2; ++k) dst[m][k] = *(const LAS bf16x8*)(lds + PG8_SA(b, h) + aoff + m * 2048 + k * 1024); } while (0)
; #define PG8_LDB(dst, b, h) do { _Pragma("unroll") for (int n = 0; n < 2; ++n) _Pragma("unroll") for (int k = 0; k < 2; ++k) dst[n][k] = *(const LAS bf16x8*)(lds + PG8_SB(b, h) + boff + n * 2048 + k * 1024); } while (0)
; #define PG8_MMA(ai, bj, At, Bt) do { __builtin_amdgcn_s_setprio(1); _Pragma("unroll") for (int m = 0; m < 4; ++m) _Pragma("unroll") for (int n = 0; n < 2; ++n) _Pragma("unroll") for (int k = 0; k < 2; ++k) \
;         acc[ai][bj][m][n] = __builtin_amdgcn_mfma_f32_16x16x32_bf16(Bt[n][k], At[m][k], acc[ai][bj][m][n], 0, 0, 0); __builtin_amdgcn_s_setprio(0); } while (0)
; #define PG8_WAIT_V(n) asm volatile("s_waitcnt vmcnt(" #n ")" ::: "memory")
; #define PG8_WAIT_L(n) asm volatile("s_waitcnt lgkmcnt(" #n ")" ::: "memory")
; #define PG8_BAR __builtin_amdgcn_s_barrier()
; #define PG8_SCHED __builtin_amdgcn_sched_barrier(0)
; template <class Epi, class Sched, bool ALIGN_EPI = true, bool SP2 = true>
; __device__ __forceinline__ void gemm_phase(LAS unsigned char* lds, const Gemm g, const Sched& S, const Epi& E) {
;     ...
;             PG8_WAIT_V(8); PG8_WAIT_L(0); PG8_BAR; PG8_MMA(1, 0, At, B0); PG8_MMA(1, 1, At, B1); PG8_BAR; PG8_SCHED;
;             PG8_LDB(B0, 1, 0); PG8_LDB(B1, 1, 1); PG8_SCHED; PG8_LDA(At, 1, 0); PG8_STAGE(PG8_SA(0, 1), a2 + hstep, voffA);
;             PG8_WAIT_V(8); PG8_WAIT_L(0); PG8_BAR; PG8_MMA(0, 0, At, B0); PG8_MMA(0, 1, At, B1); PG8_BAR; PG8_SCHED;
	v_mfma_f32_16x16x32_bf16 v[62:65], v[114:117], v[162:165], v[62:65]
	v_mfma_f32_16x16x32_bf16 v[58:61], v[130:133], v[162:165], v[58:61]
	v_mfma_f32_16x16x32_bf16 v[46:49], v[114:117], v[170:173], v[46:49]
	v_mfma_f32_16x16x32_bf16 v[42:45], v[130:133], v[170:173], v[42:45]
	v_mfma_f32_16x16x32_bf16 v[30:33], v[114:117], v[178:181], v[30:33]
	v_mfma_f32_16x16x32_bf16 v[26:29], v[130:133], v[178:181], v[26:29]
	v_mfma_f32_16x16x32_bf16 v[14:17], v[114:117], v[186:189], v[14:17]
	v_mfma_f32_16x16x32_bf16 v[10:13], v[130:133], v[186:189], v[10:13]
	v_mfma_f32_16x16x32_bf16 v[62:65], v[118:121], v[166:169], v[62:65]
	v_mfma_f32_16x16x32_bf16 v[58:61], v[134:137], v[166:169], v[58:61]
	v_mfma_f32_16x16x32_bf16 v[46:49], v[118:121], v[174:177], v[46:49]
	v_mfma_f32_16x16x32_bf16 v[42:45], v[134:137], v[174:177], v[42:45]
	v_mfma_f32_16x16x32_bf16 v[30:33], v[118:121], v[182:185], v[30:33]
	v_mfma_f32_16x16x32_bf16 v[26:29], v[134:137], v[182:185], v[26:29]
	v_mfma_f32_16x16x32_bf16 v[14:17], v[118:121], v[190:193], v[14:17]
	v_mfma_f32_16x16x32_bf16 v[10:13], v[134:137], v[190:193], v[10:13]
	v_mfma_f32_16x16x32_bf16 v[54:57], v[142:145], v[162:165], v[54:57]
	v_mfma_f32_16x16x32_bf16 v[50:53], v[154:157], v[162:165], v[50:53]
	v_mfma_f32_16x16x32_bf16 v[38:41], v[142:145], v[170:173], v[38:41]
	v_mfma_f32_16x16x32_bf16 v[34:37], v[154:157], v[170:173], v[34:37]
	v_mfma_f32_16x16x32_bf16 v[22:25], v[142:145], v[178:181], v[22:25]
	v_mfma_f32_16x16x32_bf16 v[18:21], v[154:157], v[178:181], v[18:21]
	v_mfma_f32_16x16x32_bf16 v[6:9], v[142:145], v[186:189], v[6:9]
	v_mfma_f32_16x16x32_bf16 v[2:5], v[154:157], v[186:189], v[2:5]
	v_mfma_f32_16x16x32_bf16 v[54:57], v[150:153], v[166:169], v[54:57]
	v_mfma_f32_16x16x32_bf16 v[50:53], v[158:161], v[166:169], v[50:53]
	v_mfma_f32_16x16x32_bf16 v[38:41], v[150:153], v[174:177], v[38:41]
	v_mfma_f32_16x16x32_bf16 v[34:37], v[158:161], v[174:177], v[34:37]
	v_mfma_f32_16x16x32_bf16 v[22:25], v[150:153], v[182:185], v[22:25]
	v_mfma_f32_16x16x32_bf16 v[18:21], v[158:161], v[182:185], v[18:21]
	v_mfma_f32_16x16x32_bf16 v[6:9], v[150:153], v[190:193], v[6:9]
	v_mfma_f32_16x16x32_bf16 v[2:5], v[158:161], v[190:193], v[2:5]
	s_barrier
	s_setprio 0
	s_add_i32 s65, 0, 0x18000
	s_add_i32 s66, 0, 0x1c000
	v_add_u32_e32 v134, s65, v219
	v_add_u32_e32 v158, s66, v219
	ds_read_b128 v[114:117], v134
	ds_read_b128 v[118:121], v134 offset:1024
	ds_read_b128 v[130:133], v134 offset:2048
	ds_read_b128 v[134:137], v134 offset:3072
	ds_read_b128 v[142:145], v158
	ds_read_b128 v[150:153], v158 offset:1024
	ds_read_b128 v[154:157], v158 offset:2048
	ds_read_b128 v[158:161], v158 offset:3072
	s_add_u32 s38, s38, 0x80000
	s_addc_u32 s39, s39, 0
	s_mov_b32 m0, s46
	v_lshl_add_u64 v[224:225], s[38:39], 0, v[194:195]
	ds_read_b128 v[162:165], v223 offset:32768
	ds_read_b128 v[166:169], v223 offset:33792
	ds_read_b128 v[170:173], v223 offset:34816
	ds_read_b128 v[174:177], v223 offset:35840
	ds_read_b128 v[178:181], v223 offset:36864
	ds_read_b128 v[182:185], v223 offset:37888
	ds_read_b128 v[186:189], v223 offset:38912
	ds_read_b128 v[190:193], v223 offset:39936
	global_load_lds_dwordx4 v[224:225], off
	v_lshl_add_u64 v[224:225], s[38:39], 0, v[198:199]
	s_mov_b32 m0, s47
	s_nop 0
	global_load_lds_dwordx4 v[224:225], off
	s_waitcnt vmcnt(8)
	s_waitcnt lgkmcnt(0)
	s_setprio 1
	s_barrier
	v_mfma_f32_16x16x32_bf16 v[146:149], v[114:117], v[162:165], v[146:149]
	v_mfma_f32_16x16x32_bf16 v[138:141], v[130:133], v[162:165], v[138:141]
	v_mfma_f32_16x16x32_bf16 v[110:113], v[114:117], v[170:173], v[110:113]
	v_mfma_f32_16x16x32_bf16 v[106:109], v[130:133], v[170:173], v[106:109]
	v_mfma_f32_16x16x32_bf16 v[94:97], v[114:117], v[178:181], v[94:97]
	v_mfma_f32_16x16x32_bf16 v[90:93], v[130:133], v[178:181], v[90:93]
	v_mfma_f32_16x16x32_bf16 v[78:81], v[114:117], v[186:189], v[78:81]
	v_mfma_f32_16x16x32_bf16 v[74:77], v[130:133], v[186:189], v[74:77]
	v_mfma_f32_16x16x32_bf16 v[146:149], v[118:121], v[166:169], v[146:149]
	v_mfma_f32_16x16x32_bf16 v[138:141], v[134:137], v[166:169], v[138:141]
	v_mfma_f32_16x16x32_bf16 v[110:113], v[118:121], v[174:177], v[110:113]
	v_mfma_f32_16x16x32_bf16 v[106:109], v[134:137], v[174:177], v[106:109]
	v_mfma_f32_16x16x32_bf16 v[94:97], v[118:121], v[182:185], v[94:97]
	v_mfma_f32_16x16x32_bf16 v[90:93], v[134:137], v[182:185], v[90:93]
	v_mfma_f32_16x16x32_bf16 v[78:81], v[118:121], v[190:193], v[78:81]
	v_mfma_f32_16x16x32_bf16 v[74:77], v[134:137], v[190:193], v[74:77]
	v_mfma_f32_16x16x32_bf16 v[126:129], v[142:145], v[162:165], v[126:129]
	v_mfma_f32_16x16x32_bf16 v[122:125], v[154:157], v[162:165], v[122:125]
	v_mfma_f32_16x16x32_bf16 v[102:105], v[142:145], v[170:173], v[102:105]
	v_mfma_f32_16x16x32_bf16 v[98:101], v[154:157], v[170:173], v[98:101]
	v_mfma_f32_16x16x32_bf16 v[86:89], v[142:145], v[178:181], v[86:89]
	v_mfma_f32_16x16x32_bf16 v[82:85], v[154:157], v[178:181], v[82:85]
	v_mfma_f32_16x16x32_bf16 v[70:73], v[142:145], v[186:189], v[70:73]
	v_mfma_f32_16x16x32_bf16 v[66:69], v[154:157], v[186:189], v[66:69]
	v_mfma_f32_16x16x32_bf16 v[126:129], v[150:153], v[166:169], v[126:129]
	v_mfma_f32_16x16x32_bf16 v[122:125], v[158:161], v[166:169], v[122:125]
	v_mfma_f32_16x16x32_bf16 v[102:105], v[150:153], v[174:177], v[102:105]
	v_mfma_f32_16x16x32_bf16 v[98:101], v[158:161], v[174:177], v[98:101]
	v_mfma_f32_16x16x32_bf16 v[86:89], v[150:153], v[182:185], v[86:89]
	v_mfma_f32_16x16x32_bf16 v[82:85], v[158:161], v[182:185], v[82:85]
	v_mfma_f32_16x16x32_bf16 v[70:73], v[150:153], v[190:193], v[70:73]
	v_mfma_f32_16x16x32_bf16 v[66:69], v[158:161], v[190:193], v[66:69]
	s_barrier
; #define PG8_STAGE(bufoff, gbase, voff) do { _Pragma("unroll") for (int _i = 0; _i < 2; ++_i) \
;         __builtin_amdgcn_global_load_lds((const unsigned*)((const char*)(gbase) + (voff)[_i]), (LAS unsigned*)(lds + (bufoff) + ldsw + _i * 8192), 16, 0, 0); } while (0)
; #define PG8_LDA(dst, b, h) do { _Pragma("unroll") for (int m = 0; m < 4; ++m) _Pragma("unroll") for (int k = 0; k < 2; ++k) dst[m][k] = *(const LAS bf16x8*)(lds + PG8_SA(b, h) + aoff + m * 2048 + k * 1024); } while (0)
; #define PG8_MMA(ai, bj, At, Bt) do { __builtin_amdgcn_s_setprio(1); _Pragma("unroll") for (int m = 0; m < 4; ++m) _Pragma("unroll") for (int n = 0; n < 2; ++n) _Pragma("unroll") for (int k = 0; k < 2; ++k) \
;         acc[ai][bj][m][n] = __builtin_amdgcn_mfma_f32_16x16x32_bf16(Bt[n][k], At[m][k], acc[ai][bj][m][n], 0, 0, 0); __builtin_amdgcn_s_setprio(0); } while (0)
; #define PG8_WAIT_V(n) asm volatile("s_waitcnt vmcnt(" #n ")" ::: "memory")
; #define PG8_WAIT_L(n) asm volatile("s_waitcnt lgkmcnt(" #n ")" ::: "memory")
; #define PG8_BAR __builtin_amdgcn_s_barrier()
; #define PG8_SCHED __builtin_amdgcn_sched_barrier(0)
; template <class Epi, class Sched, bool ALIGN_EPI = true, bool SP2 = true>
; __device__ __forceinline__ void gemm_phase(LAS unsigned char* lds, const Gemm g, const Sched& S, const Epi& E) {
;     ...
;             PG8_WAIT_V(8); PG8_WAIT_L(0); PG8_BAR; PG8_MMA(0, 0, At, B0); PG8_MMA(0, 1, At, B1); PG8_BAR; PG8_SCHED;
;             PG8_LDA(At, 1, 1); PG8_STAGE(PG8_SB(1, 0), b3, voffB); PG8_STAGE(PG8_SB(1, 1), b3 + hstep, voffB); PG8_STAGE(PG8_SA(1, 0), a3, voffA);
;             PG8_WAIT_V(8); PG8_WAIT_L(0); PG8_BAR; PG8_MMA(1, 0, At, B0); PG8_MMA(1, 1, At, B1); PG8_BAR; PG8_SCHED;
;     ...
;         if constexpr (ALIGN_EPI) { if (wr == 0) PG8_BAR; }
	s_setprio 0
	s_add_i32 s38, s65, s43
	v_lshl_add_u64 v[210:211], v[210:211], 0, s[12:13]
	s_mov_b32 m0, s38
	ds_read_b128 v[162:165], v223 offset:49152
	ds_read_b128 v[166:169], v223 offset:50176
	ds_read_b128 v[170:173], v223 offset:51200
	ds_read_b128 v[174:177], v223 offset:52224
	ds_read_b128 v[178:181], v223 offset:53248
	ds_read_b128 v[182:185], v223 offset:54272
	ds_read_b128 v[186:189], v223 offset:55296
	ds_read_b128 v[190:193], v223 offset:56320
	global_load_lds_dwordx4 v[210:211], off
	s_add_i32 m0, s38, 0x2000
	s_add_u32 s36, s36, 0x80080
	v_lshl_add_u64 v[210:211], v[212:213], 0, s[12:13]
	s_addc_u32 s37, s37, 0
	s_add_i32 s38, s66, s43
	global_load_lds_dwordx4 v[210:211], off
	v_lshl_add_u64 v[210:211], s[36:37], 0, v[196:197]
	s_mov_b32 m0, s38
	s_nop 0
	global_load_lds_dwordx4 v[210:211], off
	v_lshl_add_u64 v[210:211], s[36:37], 0, v[200:201]
	s_add_i32 m0, s38, 0x2000
	s_nop 0
	global_load_lds_dwordx4 v[210:211], off
	v_lshl_add_u64 v[210:211], v[214:215], 0, s[12:13]
	s_mov_b32 m0, s54
	s_nop 0
	global_load_lds_dwordx4 v[210:211], off
	v_lshl_add_u64 v[210:211], v[216:217], 0, s[12:13]
	s_mov_b32 m0, s55
	s_nop 0
	global_load_lds_dwordx4 v[210:211], off
	s_waitcnt vmcnt(8)
	s_waitcnt lgkmcnt(0)
	s_setprio 1
	s_barrier
	v_mfma_f32_16x16x32_bf16 v[62:65], v[114:117], v[162:165], v[62:65]
	v_mfma_f32_16x16x32_bf16 v[58:61], v[130:133], v[162:165], v[58:61]
	v_mfma_f32_16x16x32_bf16 v[46:49], v[114:117], v[170:173], v[46:49]
	v_mfma_f32_16x16x32_bf16 v[42:45], v[130:133], v[170:173], v[42:45]
	v_mfma_f32_16x16x32_bf16 v[30:33], v[114:117], v[178:181], v[30:33]
	v_mfma_f32_16x16x32_bf16 v[26:29], v[130:133], v[178:181], v[26:29]
	v_mfma_f32_16x16x32_bf16 v[14:17], v[114:117], v[186:189], v[14:17]
	v_mfma_f32_16x16x32_bf16 v[10:13], v[130:133], v[186:189], v[10:13]
	v_mfma_f32_16x16x32_bf16 v[62:65], v[118:121], v[166:169], v[62:65]
	v_mfma_f32_16x16x32_bf16 v[58:61], v[134:137], v[166:169], v[58:61]
	v_mfma_f32_16x16x32_bf16 v[46:49], v[118:121], v[174:177], v[46:49]
	v_mfma_f32_16x16x32_bf16 v[42:45], v[134:137], v[174:177], v[42:45]
	v_mfma_f32_16x16x32_bf16 v[30:33], v[118:121], v[182:185], v[30:33]
	v_mfma_f32_16x16x32_bf16 v[26:29], v[134:137], v[182:185], v[26:29]
	v_mfma_f32_16x16x32_bf16 v[14:17], v[118:121], v[190:193], v[14:17]
	v_mfma_f32_16x16x32_bf16 v[10:13], v[134:137], v[190:193], v[10:13]
	v_mfma_f32_16x16x32_bf16 v[54:57], v[142:145], v[162:165], v[54:57]
	v_mfma_f32_16x16x32_bf16 v[50:53], v[154:157], v[162:165], v[50:53]
	v_mfma_f32_16x16x32_bf16 v[38:41], v[142:145], v[170:173], v[38:41]
	v_mfma_f32_16x16x32_bf16 v[34:37], v[154:157], v[170:173], v[34:37]
	v_mfma_f32_16x16x32_bf16 v[22:25], v[142:145], v[178:181], v[22:25]
	v_mfma_f32_16x16x32_bf16 v[18:21], v[154:157], v[178:181], v[18:21]
	v_mfma_f32_16x16x32_bf16 v[6:9], v[142:145], v[186:189], v[6:9]
	v_mfma_f32_16x16x32_bf16 v[2:5], v[154:157], v[186:189], v[2:5]
	v_mfma_f32_16x16x32_bf16 v[54:57], v[150:153], v[166:169], v[54:57]
	v_mfma_f32_16x16x32_bf16 v[50:53], v[158:161], v[166:169], v[50:53]
	v_mfma_f32_16x16x32_bf16 v[38:41], v[150:153], v[174:177], v[38:41]
	v_mfma_f32_16x16x32_bf16 v[34:37], v[158:161], v[174:177], v[34:37]
	v_mfma_f32_16x16x32_bf16 v[22:25], v[150:153], v[182:185], v[22:25]
	v_mfma_f32_16x16x32_bf16 v[18:21], v[158:161], v[182:185], v[18:21]
	v_mfma_f32_16x16x32_bf16 v[6:9], v[150:153], v[190:193], v[6:9]
	v_mfma_f32_16x16x32_bf16 v[2:5], v[158:161], v[190:193], v[2:5]
	s_barrier
	s_setprio 0
	s_add_i32 s64, s64, 2
	s_add_u32 s34, s34, 0x100
	s_addc_u32 s35, s35, 0
	s_add_u32 s62, s62, 0x100
	s_addc_u32 s63, s63, 0
	s_cmp_gt_u32 s64, 29
	s_cbranch_scc0 .LBB0_1460
	s_and_b64 vcc, exec, s[14:15]
	s_cbranch_vccz .LBB0_1463
	s_barrier

; #define PG8_STAGE(bufoff, gbase, voff) do { _Pragma("unroll") for (int _i = 0; _i < 2; ++_i) \
;         __builtin_amdgcn_global_load_lds((const unsigned*)((const char*)(gbase) + (voff)[_i]), (LAS unsigned*)(lds + (bufoff) + ldsw + _i * 8192), 16, 0, 0); } while (0)
; #define PG8_LDA(dst, b, h) do { _Pragma("unroll") for (int m = 0; m < 4; ++m) _Pragma("unroll") for (int k = 0; k < 2; ++k) dst[m][k] = *(const LAS bf16x8*)(lds + PG8_SA(b, h) + aoff + m * 2048 + k * 1024); } while (0)
; #define PG8_LDB(dst, b, h) do { _Pragma("unroll") for (int n = 0; n < 2; ++n) _Pragma("unroll") for (int k = 0; k < 2; ++k) dst[n][k] = *(const LAS bf16x8*)(lds + PG8_SB(b, h) + boff + n * 2048 + k * 1024); } while (0)
; #define PG8_MMA(ai, bj, At, Bt) do { __builtin_amdgcn_s_setprio(1); _Pragma("unroll") for (int m = 0; m < 4; ++m) _Pragma("unroll") for (int n = 0; n < 2; ++n) _Pragma("unroll") for (int k = 0; k < 2; ++k) \
;         acc[ai][bj][m][n] = __builtin_amdgcn_mfma_f32_16x16x32_bf16(Bt[n][k], At[m][k], acc[ai][bj][m][n], 0, 0, 0); __builtin_amdgcn_s_setprio(0); } while (0)
; #define PG8_BAR __builtin_amdgcn_s_barrier()
; template <class Epi, class Sched, bool ALIGN_EPI = true, bool SP2 = true>
; __device__ __forceinline__ void gemm_phase(LAS unsigned char* lds, const Gemm g, const Sched& S, const Epi& E) {
;     ...
;         const char* nA = has_next ? PG8_ABASE(nxt) : cA; const char* nB = has_next ? PG8_BBASE(nxt) : cB;
;         for (int t = 0; t < nt; t += 2) {
;             const bool last = (t == nt - 2);
;             const char* a1 = cA + (size_t)(t + 1) * kstep;
;             const char* a2 = last ? nA : cA + (size_t)(t + 2) * kstep; const char* b2 = last ? nB : cB + (size_t)(t + 2) * kstep;
;             const char* a3 = a2 + kstep; const char* b3 = b2 + kstep;
;             if (last && has_next) S.a_ready(nxt);
;             if constexpr (SP2) {
;             PG8_LDB(B0, 0, 0); PG8_LDB(B1, 0, 1); PG8_SCHED; PG8_LDA(At, 0, 0); PG8_STAGE(PG8_SA(1, 1), a1 + hstep, voffA);
;             PG8_WAIT_V(8); PG8_WAIT_L(0); PG8_BAR; PG8_MMA(0, 0, At, B0); PG8_MMA(0, 1, At, B1); PG8_BAR; PG8_SCHED;
;             PG8_LDA(At, 0, 1); PG8_STAGE(PG8_SB(0, 0), b2, voffB); PG8_STAGE(PG8_SB(0, 1), b2 + hstep, voffB); PG8_STAGE(PG8_SA(0, 0), a2, voffA);
;             PG8_WAIT_V(8); PG8_WAIT_L(0); PG8_BAR; PG8_MMA(1, 0, At, B0); PG8_MMA(1, 1, At, B1); PG8_BAR; PG8_SCHED;
.LBB0_1639:
	ds_read_b128 v[130:133], v203
	ds_read_b128 v[134:137], v203 offset:1024
	ds_read_b128 v[138:141], v203 offset:2048
	ds_read_b128 v[142:145], v203 offset:3072
	ds_read_b128 v[146:149], v204
	ds_read_b128 v[150:153], v204 offset:1024
	ds_read_b128 v[154:157], v204 offset:2048
	ds_read_b128 v[158:161], v204 offset:3072
	s_add_u32 s54, s52, 0xfff00080
	s_addc_u32 s55, s53, -1
	s_cmp_eq_u32 s74, 60
	s_cselect_b32 s57, s43, s55
	s_cselect_b32 s56, s49, s54
	s_cselect_b32 s55, s41, s73
	s_cselect_b32 s54, s71, s72
	v_lshl_add_u64 v[198:199], s[52:53], 0, v[186:187]
	s_add_i32 m0, s51, 0xc000
	ds_read_b128 v[162:165], v205
	ds_read_b128 v[166:169], v205 offset:1024
	ds_read_b128 v[170:173], v205 offset:2048
	ds_read_b128 v[174:177], v205 offset:3072
	ds_read_b128 v[194:197], v205 offset:4096
	ds_read_b128 v[208:211], v205 offset:5120
	ds_read_b128 v[212:215], v205 offset:6144
	ds_read_b128 v[216:219], v205 offset:7168
	global_load_lds_dwordx4 v[198:199], off
	v_lshl_add_u64 v[198:199], s[52:53], 0, v[188:189]
	s_add_i32 m0, s51, 0xe000
	s_nop 0
	global_load_lds_dwordx4 v[198:199], off
	s_waitcnt vmcnt(8)
	s_waitcnt lgkmcnt(0)
	s_setprio 1
	s_barrier
	v_mfma_f32_16x16x32_bf16 v[126:129], v[130:133], v[162:165], v[126:129]
	v_mfma_f32_16x16x32_bf16 v[122:125], v[138:141], v[162:165], v[122:125]
	v_mfma_f32_16x16x32_bf16 v[110:113], v[130:133], v[170:173], v[110:113]
	v_mfma_f32_16x16x32_bf16 v[106:109], v[138:141], v[170:173], v[106:109]
	v_mfma_f32_16x16x32_bf16 v[94:97], v[130:133], v[194:197], v[94:97]
	v_mfma_f32_16x16x32_bf16 v[90:93], v[138:141], v[194:197], v[90:93]
	v_mfma_f32_16x16x32_bf16 v[78:81], v[130:133], v[212:215], v[78:81]
	v_mfma_f32_16x16x32_bf16 v[74:77], v[138:141], v[212:215], v[74:77]
	v_mfma_f32_16x16x32_bf16 v[126:129], v[134:137], v[166:169], v[126:129]
	v_mfma_f32_16x16x32_bf16 v[122:125], v[142:145], v[166:169], v[122:125]
	v_mfma_f32_16x16x32_bf16 v[110:113], v[134:137], v[174:177], v[110:113]
	v_mfma_f32_16x16x32_bf16 v[106:109], v[142:145], v[174:177], v[106:109]
	v_mfma_f32_16x16x32_bf16 v[94:97], v[134:137], v[208:211], v[94:97]
	v_mfma_f32_16x16x32_bf16 v[90:93], v[142:145], v[208:211], v[90:93]
	v_mfma_f32_16x16x32_bf16 v[78:81], v[134:137], v[216:219], v[78:81]
	v_mfma_f32_16x16x32_bf16 v[74:77], v[142:145], v[216:219], v[74:77]
	v_mfma_f32_16x16x32_bf16 v[118:121], v[146:149], v[162:165], v[118:121]
	v_mfma_f32_16x16x32_bf16 v[114:117], v[154:157], v[162:165], v[114:117]
	v_mfma_f32_16x16x32_bf16 v[102:105], v[146:149], v[170:173], v[102:105]
	v_mfma_f32_16x16x32_bf16 v[98:101], v[154:157], v[170:173], v[98:101]
	v_mfma_f32_16x16x32_bf16 v[86:89], v[146:149], v[194:197], v[86:89]
	v_mfma_f32_16x16x32_bf16 v[82:85], v[154:157], v[194:197], v[82:85]
	v_mfma_f32_16x16x32_bf16 v[70:73], v[146:149], v[212:215], v[70:73]
	v_mfma_f32_16x16x32_bf16 v[66:69], v[154:157], v[212:215], v[66:69]
	v_mfma_f32_16x16x32_bf16 v[118:121], v[150:153], v[166:169], v[118:121]
	v_mfma_f32_16x16x32_bf16 v[114:117], v[158:161], v[166:169], v[114:117]
	v_mfma_f32_16x16x32_bf16 v[102:105], v[150:153], v[174:177], v[102:105]
	v_mfma_f32_16x16x32_bf16 v[98:101], v[158:161], v[174:177], v[98:101]
	v_mfma_f32_16x16x32_bf16 v[86:89], v[150:153], v[208:211], v[86:89]
	v_mfma_f32_16x16x32_bf16 v[82:85], v[158:161], v[208:211], v[82:85]
	v_mfma_f32_16x16x32_bf16 v[70:73], v[150:153], v[216:219], v[70:73]
	v_mfma_f32_16x16x32_bf16 v[66:69], v[158:161], v[216:219], v[66:69]
	s_barrier
	s_setprio 0
	s_add_i32 s75, s66, s33
	v_lshl_add_u64 v[198:199], s[54:55], 0, v[180:181]
	s_mov_b32 m0, s75
	ds_read_b128 v[162:165], v205 offset:16384
	ds_read_b128 v[166:169], v205 offset:17408
	ds_read_b128 v[170:173], v205 offset:18432
	ds_read_b128 v[174:177], v205 offset:19456
	ds_read_b128 v[194:197], v205 offset:20480
	ds_read_b128 v[208:211], v205 offset:21504
	ds_read_b128 v[212:215], v205 offset:22528
	ds_read_b128 v[216:219], v205 offset:23552
	global_load_lds_dwordx4 v[198:199], off
	s_add_i32 m0, s75, 0x2000
	s_add_u32 s76, s54, 0x100000
	v_lshl_add_u64 v[220:221], s[54:55], 0, v[184:185]
	s_addc_u32 s77, s55, 0
	s_add_i32 s75, s67, s33
	global_load_lds_dwordx4 v[220:221], off
	v_lshl_add_u64 v[222:223], s[76:77], 0, v[180:181]
	s_mov_b32 m0, s75
	v_lshl_add_u64 v[224:225], s[56:57], 0, v[182:183]
	global_load_lds_dwordx4 v[222:223], off
	v_lshl_add_u64 v[222:223], s[76:77], 0, v[184:185]
	s_add_i32 m0, s75, 0x2000
	s_nop 0
	global_load_lds_dwordx4 v[222:223], off
	v_lshl_add_u64 v[222:223], s[56:57], 0, v[178:179]
	s_mov_b32 m0, s51
	s_nop 0
	global_load_lds_dwordx4 v[222:223], off
	s_mov_b32 m0, s58
	s_nop 0
	global_load_lds_dwordx4 v[224:225], off
	s_waitcnt vmcnt(8)
	s_waitcnt lgkmcnt(0)
	s_setprio 1
	s_barrier
; #define PG8_STAGE(bufoff, gbase, voff) do { _Pragma("unroll") for (int _i = 0; _i < 2; ++_i) \
;         __builtin_amdgcn_global_load_lds((const unsigned*)((const char*)(gbase) + (voff)[_i]), (LAS unsigned*)(lds + (bufoff) + ldsw + _i * 8192), 16, 0, 0); } while (0)
; #define PG8_LDA(dst, b, h) do { _Pragma("unroll") for (int m = 0; m < 4; ++m) _Pragma("unroll") for (int k = 0; k < 2; ++k) dst[m][k] = *(const LAS bf16x8*)(lds + PG8_SA(b, h) + aoff + m * 2048 + k * 1024); } while (0)
; #define PG8_LDB(dst, b, h) do { _Pragma("unroll") for (int n = 0; n < 2; ++n) _Pragma("unroll") for (int k = 0; k < 2; ++k) dst[n][k] = *(const LAS bf16x8*)(lds + PG8_SB(b, h) + boff + n * 2048 + k * 1024); } while (0)
; #define PG8_MMA(ai, bj, At, Bt) do { __builtin_amdgcn_s_setprio(1); _Pragma("unroll") for (int m = 0; m < 4; ++m) _Pragma("unroll") for (int n = 0; n < 2; ++n) _Pragma("unroll") for (int k = 0; k < 2; ++k) \
;         acc[ai][bj][m][n] = __builtin_amdgcn_mfma_f32_16x16x32_bf16(Bt[n][k], At[m][k], acc[ai][bj][m][n], 0, 0, 0); __builtin_amdgcn_s_setprio(0); } while (0)
; #define PG8_WAIT_V(n) asm volatile("s_waitcnt vmcnt(" #n ")" ::: "memory")
; #define PG8_WAIT_L(n) asm volatile("s_waitcnt lgkmcnt(" #n ")" ::: "memory")
; #define PG8_BAR __builtin_amdgcn_s_barrier()
; #define PG8_SCHED __builtin_amdgcn_sched_barrier(0)
; template <class Epi, class Sched, bool ALIGN_EPI = true, bool SP2 = true>
; __device__ __forceinline__ void gemm_phase(LAS unsigned char* lds, const Gemm g, const Sched& S, const Epi& E) {
;     ...
;             PG8_WAIT_V(8); PG8_WAIT_L(0); PG8_BAR; PG8_MMA(1, 0, At, B0); PG8_MMA(1, 1, At, B1); PG8_BAR; PG8_SCHED;
;             PG8_LDB(B0, 1, 0); PG8_LDB(B1, 1, 1); PG8_SCHED; PG8_LDA(At, 1, 0); PG8_STAGE(PG8_SA(0, 1), a2 + hstep, voffA);
;             PG8_WAIT_V(8); PG8_WAIT_L(0); PG8_BAR; PG8_MMA(0, 0, At, B0); PG8_MMA(0, 1, At, B1); PG8_BAR; PG8_SCHED;
	v_mfma_f32_16x16x32_bf16 v[62:65], v[130:133], v[162:165], v[62:65]
	v_mfma_f32_16x16x32_bf16 v[58:61], v[138:141], v[162:165], v[58:61]
	v_mfma_f32_16x16x32_bf16 v[46:49], v[130:133], v[170:173], v[46:49]
	v_mfma_f32_16x16x32_bf16 v[42:45], v[138:141], v[170:173], v[42:45]
	v_mfma_f32_16x16x32_bf16 v[30:33], v[130:133], v[194:197], v[30:33]
	v_mfma_f32_16x16x32_bf16 v[26:29], v[138:141], v[194:197], v[26:29]
	v_mfma_f32_16x16x32_bf16 v[14:17], v[130:133], v[212:215], v[14:17]
	v_mfma_f32_16x16x32_bf16 v[10:13], v[138:141], v[212:215], v[10:13]
	v_mfma_f32_16x16x32_bf16 v[62:65], v[134:137], v[166:169], v[62:65]
	v_mfma_f32_16x16x32_bf16 v[58:61], v[142:145], v[166:169], v[58:61]
	v_mfma_f32_16x16x32_bf16 v[46:49], v[134:137], v[174:177], v[46:49]
	v_mfma_f32_16x16x32_bf16 v[42:45], v[142:145], v[174:177], v[42:45]
	v_mfma_f32_16x16x32_bf16 v[30:33], v[134:137], v[208:211], v[30:33]
	v_mfma_f32_16x16x32_bf16 v[26:29], v[142:145], v[208:211], v[26:29]
	v_mfma_f32_16x16x32_bf16 v[14:17], v[134:137], v[216:219], v[14:17]
	v_mfma_f32_16x16x32_bf16 v[10:13], v[142:145], v[216:219], v[10:13]
	v_mfma_f32_16x16x32_bf16 v[54:57], v[146:149], v[162:165], v[54:57]
	v_mfma_f32_16x16x32_bf16 v[50:53], v[154:157], v[162:165], v[50:53]
	v_mfma_f32_16x16x32_bf16 v[38:41], v[146:149], v[170:173], v[38:41]
	v_mfma_f32_16x16x32_bf16 v[34:37], v[154:157], v[170:173], v[34:37]
	v_mfma_f32_16x16x32_bf16 v[22:25], v[146:149], v[194:197], v[22:25]
	v_mfma_f32_16x16x32_bf16 v[18:21], v[154:157], v[194:197], v[18:21]
	v_mfma_f32_16x16x32_bf16 v[6:9], v[146:149], v[212:215], v[6:9]
	v_mfma_f32_16x16x32_bf16 v[2:5], v[154:157], v[212:215], v[2:5]
	v_mfma_f32_16x16x32_bf16 v[54:57], v[150:153], v[166:169], v[54:57]
	v_mfma_f32_16x16x32_bf16 v[50:53], v[158:161], v[166:169], v[50:53]
	v_mfma_f32_16x16x32_bf16 v[38:41], v[150:153], v[174:177], v[38:41]
	v_mfma_f32_16x16x32_bf16 v[34:37], v[158:161], v[174:177], v[34:37]
	v_mfma_f32_16x16x32_bf16 v[22:25], v[150:153], v[208:211], v[22:25]
	v_mfma_f32_16x16x32_bf16 v[18:21], v[158:161], v[208:211], v[18:21]
	v_mfma_f32_16x16x32_bf16 v[6:9], v[150:153], v[216:219], v[6:9]
	v_mfma_f32_16x16x32_bf16 v[2:5], v[158:161], v[216:219], v[2:5]
	s_barrier
	s_setprio 0
	s_add_i32 s75, 0, 0x18000
	s_add_i32 s76, 0, 0x1c000
	v_add_u32_e32 v142, s75, v201
	v_add_u32_e32 v158, s76, v201
	ds_read_b128 v[130:133], v142
	ds_read_b128 v[134:137], v142 offset:1024
	ds_read_b128 v[138:141], v142 offset:2048
	ds_read_b128 v[142:145], v142 offset:3072
	ds_read_b128 v[146:149], v158
	ds_read_b128 v[150:153], v158 offset:1024
	ds_read_b128 v[154:157], v158 offset:2048
	ds_read_b128 v[158:161], v158 offset:3072
	s_add_u32 s56, s56, 0x100000
	s_addc_u32 s57, s57, 0
	s_mov_b32 m0, s59
	v_lshl_add_u64 v[226:227], s[56:57], 0, v[178:179]
	ds_read_b128 v[162:165], v205 offset:32768
	ds_read_b128 v[166:169], v205 offset:33792
	ds_read_b128 v[170:173], v205 offset:34816
	ds_read_b128 v[174:177], v205 offset:35840
	ds_read_b128 v[194:197], v205 offset:36864
	ds_read_b128 v[208:211], v205 offset:37888
	ds_read_b128 v[212:215], v205 offset:38912
	ds_read_b128 v[216:219], v205 offset:39936
	global_load_lds_dwordx4 v[226:227], off
	v_lshl_add_u64 v[226:227], s[56:57], 0, v[182:183]
	s_mov_b32 m0, s60
	s_nop 0
	global_load_lds_dwordx4 v[226:227], off
	s_waitcnt vmcnt(8)
	s_waitcnt lgkmcnt(0)
	s_setprio 1
	s_barrier
	v_mfma_f32_16x16x32_bf16 v[126:129], v[130:133], v[162:165], v[126:129]
	v_mfma_f32_16x16x32_bf16 v[122:125], v[138:141], v[162:165], v[122:125]
	v_mfma_f32_16x16x32_bf16 v[110:113], v[130:133], v[170:173], v[110:113]
	v_mfma_f32_16x16x32_bf16 v[106:109], v[138:141], v[170:173], v[106:109]
	v_mfma_f32_16x16x32_bf16 v[94:97], v[130:133], v[194:197], v[94:97]
	v_mfma_f32_16x16x32_bf16 v[90:93], v[138:141], v[194:197], v[90:93]
	v_mfma_f32_16x16x32_bf16 v[78:81], v[130:133], v[212:215], v[78:81]
	v_mfma_f32_16x16x32_bf16 v[74:77], v[138:141], v[212:215], v[74:77]
	v_mfma_f32_16x16x32_bf16 v[126:129], v[134:137], v[166:169], v[126:129]
	v_mfma_f32_16x16x32_bf16 v[122:125], v[142:145], v[166:169], v[122:125]
	v_mfma_f32_16x16x32_bf16 v[110:113], v[134:137], v[174:177], v[110:113]
	v_mfma_f32_16x16x32_bf16 v[106:109], v[142:145], v[174:177], v[106:109]
	v_mfma_f32_16x16x32_bf16 v[94:97], v[134:137], v[208:211], v[94:97]
	v_mfma_f32_16x16x32_bf16 v[90:93], v[142:145], v[208:211], v[90:93]
	v_mfma_f32_16x16x32_bf16 v[78:81], v[134:137], v[216:219], v[78:81]
	v_mfma_f32_16x16x32_bf16 v[74:77], v[142:145], v[216:219], v[74:77]
	v_mfma_f32_16x16x32_bf16 v[118:121], v[146:149], v[162:165], v[118:121]
	v_mfma_f32_16x16x32_bf16 v[114:117], v[154:157], v[162:165], v[114:117]
	v_mfma_f32_16x16x32_bf16 v[102:105], v[146:149], v[170:173], v[102:105]
	v_mfma_f32_16x16x32_bf16 v[98:101], v[154:157], v[170:173], v[98:101]
	v_mfma_f32_16x16x32_bf16 v[86:89], v[146:149], v[194:197], v[86:89]
	v_mfma_f32_16x16x32_bf16 v[82:85], v[154:157], v[194:197], v[82:85]
	v_mfma_f32_16x16x32_bf16 v[70:73], v[146:149], v[212:215], v[70:73]
	v_mfma_f32_16x16x32_bf16 v[66:69], v[154:157], v[212:215], v[66:69]
	v_mfma_f32_16x16x32_bf16 v[118:121], v[150:153], v[166:169], v[118:121]
	v_mfma_f32_16x16x32_bf16 v[114:117], v[158:161], v[166:169], v[114:117]
	v_mfma_f32_16x16x32_bf16 v[102:105], v[150:153], v[174:177], v[102:105]
	v_mfma_f32_16x16x32_bf16 v[98:101], v[158:161], v[174:177], v[98:101]
	v_mfma_f32_16x16x32_bf16 v[86:89], v[150:153], v[208:211], v[86:89]
	v_mfma_f32_16x16x32_bf16 v[82:85], v[158:161], v[208:211], v[82:85]
	v_mfma_f32_16x16x32_bf16 v[70:73], v[150:153], v[216:219], v[70:73]
	v_mfma_f32_16x16x32_bf16 v[66:69], v[158:161], v[216:219], v[66:69]
	s_barrier
; #define PG8_STAGE(bufoff, gbase, voff) do { _Pragma("unroll") for (int _i = 0; _i < 2; ++_i) \
;         __builtin_amdgcn_global_load_lds((const unsigned*)((const char*)(gbase) + (voff)[_i]), (LAS unsigned*)(lds + (bufoff) + ldsw + _i * 8192), 16, 0, 0); } while (0)
; #define PG8_LDA(dst, b, h) do { _Pragma("unroll") for (int m = 0; m < 4; ++m) _Pragma("unroll") for (int k = 0; k < 2; ++k) dst[m][k] = *(const LAS bf16x8*)(lds + PG8_SA(b, h) + aoff + m * 2048 + k * 1024); } while (0)
; #define PG8_MMA(ai, bj, At, Bt) do { __builtin_amdgcn_s_setprio(1); _Pragma("unroll") for (int m = 0; m < 4; ++m) _Pragma("unroll") for (int n = 0; n < 2; ++n) _Pragma("unroll") for (int k = 0; k < 2; ++k) \
;         acc[ai][bj][m][n] = __builtin_amdgcn_mfma_f32_16x16x32_bf16(Bt[n][k], At[m][k], acc[ai][bj][m][n], 0, 0, 0); __builtin_amdgcn_s_setprio(0); } while (0)
; #define PG8_WAIT_V(n) asm volatile("s_waitcnt vmcnt(" #n ")" ::: "memory")
; #define PG8_WAIT_L(n) asm volatile("s_waitcnt lgkmcnt(" #n ")" ::: "memory")
; #define PG8_BAR __builtin_amdgcn_s_barrier()
; #define PG8_SCHED __builtin_amdgcn_sched_barrier(0)
; template <class Epi, class Sched, bool ALIGN_EPI = true, bool SP2 = true>
; __device__ __forceinline__ void gemm_phase(LAS unsigned char* lds, const Gemm g, const Sched& S, const Epi& E) {
;     ...
;             PG8_WAIT_V(8); PG8_WAIT_L(0); PG8_BAR; PG8_MMA(0, 0, At, B0); PG8_MMA(0, 1, At, B1); PG8_BAR; PG8_SCHED;
;             PG8_LDA(At, 1, 1); PG8_STAGE(PG8_SB(1, 0), b3, voffB); PG8_STAGE(PG8_SB(1, 1), b3 + hstep, voffB); PG8_STAGE(PG8_SA(1, 0), a3, voffA);
;             PG8_WAIT_V(8); PG8_WAIT_L(0); PG8_BAR; PG8_MMA(1, 0, At, B0); PG8_MMA(1, 1, At, B1); PG8_BAR; PG8_SCHED;
;     ...
;         if constexpr (ALIGN_EPI) { if (wr == 0) PG8_BAR; }
	s_setprio 0
	s_add_i32 s56, s75, s33
	v_lshl_add_u64 v[198:199], v[198:199], 0, s[22:23]
	s_mov_b32 m0, s56
	ds_read_b128 v[162:165], v205 offset:49152
	ds_read_b128 v[166:169], v205 offset:50176
	ds_read_b128 v[170:173], v205 offset:51200
	ds_read_b128 v[174:177], v205 offset:52224
	ds_read_b128 v[194:197], v205 offset:53248
	ds_read_b128 v[208:211], v205 offset:54272
	ds_read_b128 v[212:215], v205 offset:55296
	ds_read_b128 v[216:219], v205 offset:56320
	global_load_lds_dwordx4 v[198:199], off
	s_add_i32 m0, s56, 0x2000
	s_add_u32 s54, s54, 0x100080
	v_lshl_add_u64 v[198:199], v[220:221], 0, s[22:23]
	s_addc_u32 s55, s55, 0
	s_add_i32 s56, s76, s33
	global_load_lds_dwordx4 v[198:199], off
	v_lshl_add_u64 v[198:199], s[54:55], 0, v[180:181]
	s_mov_b32 m0, s56
	s_nop 0
	global_load_lds_dwordx4 v[198:199], off
	v_lshl_add_u64 v[198:199], s[54:55], 0, v[184:185]
	s_add_i32 m0, s56, 0x2000
	s_nop 0
	global_load_lds_dwordx4 v[198:199], off
	v_lshl_add_u64 v[198:199], v[222:223], 0, s[22:23]
	s_mov_b32 m0, s62
	s_nop 0
	global_load_lds_dwordx4 v[198:199], off
	v_lshl_add_u64 v[198:199], v[224:225], 0, s[22:23]
	s_mov_b32 m0, s63
	s_nop 0
	global_load_lds_dwordx4 v[198:199], off
	s_waitcnt vmcnt(8)
	s_waitcnt lgkmcnt(0)
	s_setprio 1
	s_barrier
	v_mfma_f32_16x16x32_bf16 v[62:65], v[130:133], v[162:165], v[62:65]
	v_mfma_f32_16x16x32_bf16 v[58:61], v[138:141], v[162:165], v[58:61]
	v_mfma_f32_16x16x32_bf16 v[46:49], v[130:133], v[170:173], v[46:49]
	v_mfma_f32_16x16x32_bf16 v[42:45], v[138:141], v[170:173], v[42:45]
	v_mfma_f32_16x16x32_bf16 v[30:33], v[130:133], v[194:197], v[30:33]
	v_mfma_f32_16x16x32_bf16 v[26:29], v[138:141], v[194:197], v[26:29]
	v_mfma_f32_16x16x32_bf16 v[14:17], v[130:133], v[212:215], v[14:17]
	v_mfma_f32_16x16x32_bf16 v[10:13], v[138:141], v[212:215], v[10:13]
	v_mfma_f32_16x16x32_bf16 v[62:65], v[134:137], v[166:169], v[62:65]
	v_mfma_f32_16x16x32_bf16 v[58:61], v[142:145], v[166:169], v[58:61]
	v_mfma_f32_16x16x32_bf16 v[46:49], v[134:137], v[174:177], v[46:49]
	v_mfma_f32_16x16x32_bf16 v[42:45], v[142:145], v[174:177], v[42:45]
	v_mfma_f32_16x16x32_bf16 v[30:33], v[134:137], v[208:211], v[30:33]
	v_mfma_f32_16x16x32_bf16 v[26:29], v[142:145], v[208:211], v[26:29]
	v_mfma_f32_16x16x32_bf16 v[14:17], v[134:137], v[216:219], v[14:17]
	v_mfma_f32_16x16x32_bf16 v[10:13], v[142:145], v[216:219], v[10:13]
	v_mfma_f32_16x16x32_bf16 v[54:57], v[146:149], v[162:165], v[54:57]
	v_mfma_f32_16x16x32_bf16 v[50:53], v[154:157], v[162:165], v[50:53]
	v_mfma_f32_16x16x32_bf16 v[38:41], v[146:149], v[170:173], v[38:41]
	v_mfma_f32_16x16x32_bf16 v[34:37], v[154:157], v[170:173], v[34:37]
	v_mfma_f32_16x16x32_bf16 v[22:25], v[146:149], v[194:197], v[22:25]
	v_mfma_f32_16x16x32_bf16 v[18:21], v[154:157], v[194:197], v[18:21]
	v_mfma_f32_16x16x32_bf16 v[6:9], v[146:149], v[212:215], v[6:9]
	v_mfma_f32_16x16x32_bf16 v[2:5], v[154:157], v[212:215], v[2:5]
	v_mfma_f32_16x16x32_bf16 v[54:57], v[150:153], v[166:169], v[54:57]
	v_mfma_f32_16x16x32_bf16 v[50:53], v[158:161], v[166:169], v[50:53]
	v_mfma_f32_16x16x32_bf16 v[38:41], v[150:153], v[174:177], v[38:41]
	v_mfma_f32_16x16x32_bf16 v[34:37], v[158:161], v[174:177], v[34:37]
	v_mfma_f32_16x16x32_bf16 v[22:25], v[150:153], v[208:211], v[22:25]
	v_mfma_f32_16x16x32_bf16 v[18:21], v[158:161], v[208:211], v[18:21]
	v_mfma_f32_16x16x32_bf16 v[6:9], v[150:153], v[216:219], v[6:9]
	v_mfma_f32_16x16x32_bf16 v[2:5], v[158:161], v[216:219], v[2:5]
	s_barrier
	s_setprio 0
	s_add_i32 s74, s74, 2
	s_add_u32 s52, s52, 0x100
	s_addc_u32 s53, s53, 0
	s_add_u32 s72, s72, 0x100
	s_addc_u32 s73, s73, 0
	s_cmp_gt_u32 s74, 61
	s_cbranch_scc0 .LBB0_1639
	s_and_b64 vcc, exec, s[26:27]
	s_cbranch_vccz .LBB0_1642
	s_barrier

; #define PG8_STAGE(bufoff, gbase, voff) do { _Pragma("unroll") for (int _i = 0; _i < 2; ++_i) \
;         __builtin_amdgcn_global_load_lds((const unsigned*)((const char*)(gbase) + (voff)[_i]), (LAS unsigned*)(lds + (bufoff) + ldsw + _i * 8192), 16, 0, 0); } while (0)
; #define PG8_LDA(dst, b, h) do { _Pragma("unroll") for (int m = 0; m < 4; ++m) _Pragma("unroll") for (int k = 0; k < 2; ++k) dst[m][k] = *(const LAS bf16x8*)(lds + PG8_SA(b, h) + aoff + m * 2048 + k * 1024); } while (0)
; #define PG8_LDB(dst, b, h) do { _Pragma("unroll") for (int n = 0; n < 2; ++n) _Pragma("unroll") for (int k = 0; k < 2; ++k) dst[n][k] = *(const LAS bf16x8*)(lds + PG8_SB(b, h) + boff + n * 2048 + k * 1024); } while (0)
; #define PG8_MMA(ai, bj, At, Bt) do { __builtin_amdgcn_s_setprio(1); _Pragma("unroll") for (int m = 0; m < 4; ++m) _Pragma("unroll") for (int n = 0; n < 2; ++n) _Pragma("unroll") for (int k = 0; k < 2; ++k) \
;         acc[ai][bj][m][n] = __builtin_amdgcn_mfma_f32_16x16x32_bf16(Bt[n][k], At[m][k], acc[ai][bj][m][n], 0, 0, 0); __builtin_amdgcn_s_setprio(0); } while (0)
; #define PG8_BAR __builtin_amdgcn_s_barrier()
; template <class Epi, class Sched, bool ALIGN_EPI = true, bool SP2 = true>
; __device__ __forceinline__ void gemm_phase(LAS unsigned char* lds, const Gemm g, const Sched& S, const Epi& E) {
;     ...
;         const char* nA = has_next ? PG8_ABASE(nxt) : cA; const char* nB = has_next ? PG8_BBASE(nxt) : cB;
;         for (int t = 0; t < nt; t += 2) {
;             const bool last = (t == nt - 2);
;             const char* a1 = cA + (size_t)(t + 1) * kstep;
;             const char* a2 = last ? nA : cA + (size_t)(t + 2) * kstep; const char* b2 = last ? nB : cB + (size_t)(t + 2) * kstep;
;             const char* a3 = a2 + kstep; const char* b3 = b2 + kstep;
;             if (last && has_next) S.a_ready(nxt);
;             if constexpr (SP2) {
;             PG8_LDB(B0, 0, 0); PG8_LDB(B1, 0, 1); PG8_SCHED; PG8_LDA(At, 0, 0); PG8_STAGE(PG8_SA(1, 1), a1 + hstep, voffA);
;             PG8_WAIT_V(8); PG8_WAIT_L(0); PG8_BAR; PG8_MMA(0, 0, At, B0); PG8_MMA(0, 1, At, B1); PG8_BAR; PG8_SCHED;
;             PG8_LDA(At, 0, 1); PG8_STAGE(PG8_SB(0, 0), b2, voffB); PG8_STAGE(PG8_SB(0, 1), b2 + hstep, voffB); PG8_STAGE(PG8_SA(0, 0), a2, voffA);
;             PG8_WAIT_V(8); PG8_WAIT_L(0); PG8_BAR; PG8_MMA(1, 0, At, B0); PG8_MMA(1, 1, At, B1); PG8_BAR; PG8_SCHED;
.LBB0_1810:
	ds_read_b128 v[148:151], v168
	ds_read_b128 v[152:155], v168 offset:1024
	ds_read_b128 v[156:159], v168 offset:2048
	ds_read_b128 v[160:163], v168 offset:3072
	ds_read_b128 v[174:177], v169
	ds_read_b128 v[178:181], v169 offset:1024
	ds_read_b128 v[182:185], v169 offset:2048
	ds_read_b128 v[186:189], v169 offset:3072
	s_add_u32 s30, s4, 0xfff00080
	s_addc_u32 s31, s5, -1
	s_cmp_eq_u32 s56, 60
	s_cselect_b32 s35, s25, s31
	s_cselect_b32 s34, s52, s30
	s_cselect_b32 s31, s23, s55
	s_cselect_b32 s30, s53, s54
	v_lshl_add_u64 v[164:165], s[4:5], 0, v[140:141]
	s_add_i32 m0, s40, 0xc000
	ds_read_b128 v[190:193], v170
	ds_read_b128 v[194:197], v170 offset:1024
	ds_read_b128 v[198:201], v170 offset:2048
	ds_read_b128 v[202:205], v170 offset:3072
	ds_read_b128 v[206:209], v170 offset:4096
	ds_read_b128 v[210:213], v170 offset:5120
	ds_read_b128 v[214:217], v170 offset:6144
	ds_read_b128 v[218:221], v170 offset:7168
	global_load_lds_dwordx4 v[164:165], off
	v_lshl_add_u64 v[164:165], s[4:5], 0, v[142:143]
	s_add_i32 m0, s40, 0xe000
	s_nop 0
	global_load_lds_dwordx4 v[164:165], off
	s_waitcnt vmcnt(8)
	s_waitcnt lgkmcnt(0)
	s_setprio 1
	s_barrier
	v_mfma_f32_16x16x32_bf16 v[126:129], v[148:151], v[190:193], v[126:129]
	v_mfma_f32_16x16x32_bf16 v[122:125], v[156:159], v[190:193], v[122:125]
	v_mfma_f32_16x16x32_bf16 v[106:109], v[156:159], v[198:201], v[106:109]
	v_mfma_f32_16x16x32_bf16 v[110:113], v[148:151], v[198:201], v[110:113]
	v_mfma_f32_16x16x32_bf16 v[94:97], v[148:151], v[206:209], v[94:97]
	v_mfma_f32_16x16x32_bf16 v[90:93], v[156:159], v[206:209], v[90:93]
	v_mfma_f32_16x16x32_bf16 v[74:77], v[156:159], v[214:217], v[74:77]
	v_mfma_f32_16x16x32_bf16 v[78:81], v[148:151], v[214:217], v[78:81]
	v_mfma_f32_16x16x32_bf16 v[126:129], v[152:155], v[194:197], v[126:129]
	v_mfma_f32_16x16x32_bf16 v[122:125], v[160:163], v[194:197], v[122:125]
	v_mfma_f32_16x16x32_bf16 v[106:109], v[160:163], v[202:205], v[106:109]
	v_mfma_f32_16x16x32_bf16 v[110:113], v[152:155], v[202:205], v[110:113]
	v_mfma_f32_16x16x32_bf16 v[94:97], v[152:155], v[210:213], v[94:97]
	v_mfma_f32_16x16x32_bf16 v[90:93], v[160:163], v[210:213], v[90:93]
	v_mfma_f32_16x16x32_bf16 v[74:77], v[160:163], v[218:221], v[74:77]
	v_mfma_f32_16x16x32_bf16 v[78:81], v[152:155], v[218:221], v[78:81]
	v_mfma_f32_16x16x32_bf16 v[118:121], v[174:177], v[190:193], v[118:121]
	v_mfma_f32_16x16x32_bf16 v[114:117], v[182:185], v[190:193], v[114:117]
	v_mfma_f32_16x16x32_bf16 v[98:101], v[182:185], v[198:201], v[98:101]
	v_mfma_f32_16x16x32_bf16 v[102:105], v[174:177], v[198:201], v[102:105]
	v_mfma_f32_16x16x32_bf16 v[86:89], v[174:177], v[206:209], v[86:89]
	v_mfma_f32_16x16x32_bf16 v[82:85], v[182:185], v[206:209], v[82:85]
	v_mfma_f32_16x16x32_bf16 v[66:69], v[182:185], v[214:217], v[66:69]
	v_mfma_f32_16x16x32_bf16 v[70:73], v[174:177], v[214:217], v[70:73]
	v_mfma_f32_16x16x32_bf16 v[118:121], v[178:181], v[194:197], v[118:121]
	v_mfma_f32_16x16x32_bf16 v[114:117], v[186:189], v[194:197], v[114:117]
	v_mfma_f32_16x16x32_bf16 v[98:101], v[186:189], v[202:205], v[98:101]
	v_mfma_f32_16x16x32_bf16 v[102:105], v[178:181], v[202:205], v[102:105]
	v_mfma_f32_16x16x32_bf16 v[86:89], v[178:181], v[210:213], v[86:89]
	v_mfma_f32_16x16x32_bf16 v[82:85], v[186:189], v[210:213], v[82:85]
	v_mfma_f32_16x16x32_bf16 v[66:69], v[186:189], v[218:221], v[66:69]
	v_mfma_f32_16x16x32_bf16 v[70:73], v[178:181], v[218:221], v[70:73]
	s_barrier
	s_setprio 0
	s_add_i32 s57, s48, s37
	v_lshl_add_u64 v[164:165], s[30:31], 0, v[134:135]
	s_mov_b32 m0, s57
	ds_read_b128 v[190:193], v170 offset:16384
	ds_read_b128 v[194:197], v170 offset:17408
	ds_read_b128 v[198:201], v170 offset:18432
	ds_read_b128 v[202:205], v170 offset:19456
	ds_read_b128 v[206:209], v170 offset:20480
	ds_read_b128 v[210:213], v170 offset:21504
	ds_read_b128 v[214:217], v170 offset:22528
	ds_read_b128 v[218:221], v170 offset:23552
	global_load_lds_dwordx4 v[164:165], off
	s_add_i32 m0, s57, 0x2000
	s_add_u32 s58, s30, 0x100000
	v_lshl_add_u64 v[222:223], s[30:31], 0, v[130:131]
	s_addc_u32 s59, s31, 0
	s_add_i32 s57, s49, s37
	global_load_lds_dwordx4 v[222:223], off
	v_lshl_add_u64 v[224:225], s[58:59], 0, v[134:135]
	s_mov_b32 m0, s57
	v_lshl_add_u64 v[226:227], s[34:35], 0, v[132:133]
	global_load_lds_dwordx4 v[224:225], off
	v_lshl_add_u64 v[224:225], s[58:59], 0, v[130:131]
	s_add_i32 m0, s57, 0x2000
	s_nop 0
	global_load_lds_dwordx4 v[224:225], off
	v_lshl_add_u64 v[224:225], s[34:35], 0, v[136:137]
	s_mov_b32 m0, s40
	s_nop 0
	global_load_lds_dwordx4 v[224:225], off
	s_mov_b32 m0, s41
	s_nop 0
	global_load_lds_dwordx4 v[226:227], off
	s_waitcnt vmcnt(8)
	s_waitcnt lgkmcnt(0)
	s_setprio 1
	s_barrier
; #define PG8_STAGE(bufoff, gbase, voff) do { _Pragma("unroll") for (int _i = 0; _i < 2; ++_i) \
;         __builtin_amdgcn_global_load_lds((const unsigned*)((const char*)(gbase) + (voff)[_i]), (LAS unsigned*)(lds + (bufoff) + ldsw + _i * 8192), 16, 0, 0); } while (0)
; #define PG8_LDA(dst, b, h) do { _Pragma("unroll") for (int m = 0; m < 4; ++m) _Pragma("unroll") for (int k = 0; k < 2; ++k) dst[m][k] = *(const LAS bf16x8*)(lds + PG8_SA(b, h) + aoff + m * 2048 + k * 1024); } while (0)
; #define PG8_LDB(dst, b, h) do { _Pragma("unroll") for (int n = 0; n < 2; ++n) _Pragma("unroll") for (int k = 0; k < 2; ++k) dst[n][k] = *(const LAS bf16x8*)(lds + PG8_SB(b, h) + boff + n * 2048 + k * 1024); } while (0)
; #define PG8_MMA(ai, bj, At, Bt) do { __builtin_amdgcn_s_setprio(1); _Pragma("unroll") for (int m = 0; m < 4; ++m) _Pragma("unroll") for (int n = 0; n < 2; ++n) _Pragma("unroll") for (int k = 0; k < 2; ++k) \
;         acc[ai][bj][m][n] = __builtin_amdgcn_mfma_f32_16x16x32_bf16(Bt[n][k], At[m][k], acc[ai][bj][m][n], 0, 0, 0); __builtin_amdgcn_s_setprio(0); } while (0)
; #define PG8_WAIT_V(n) asm volatile("s_waitcnt vmcnt(" #n ")" ::: "memory")
; #define PG8_WAIT_L(n) asm volatile("s_waitcnt lgkmcnt(" #n ")" ::: "memory")
; #define PG8_BAR __builtin_amdgcn_s_barrier()
; #define PG8_SCHED __builtin_amdgcn_sched_barrier(0)
; template <class Epi, class Sched, bool ALIGN_EPI = true, bool SP2 = true>
; __device__ __forceinline__ void gemm_phase(LAS unsigned char* lds, const Gemm g, const Sched& S, const Epi& E) {
;     ...
;             PG8_WAIT_V(8); PG8_WAIT_L(0); PG8_BAR; PG8_MMA(1, 0, At, B0); PG8_MMA(1, 1, At, B1); PG8_BAR; PG8_SCHED;
;             PG8_LDB(B0, 1, 0); PG8_LDB(B1, 1, 1); PG8_SCHED; PG8_LDA(At, 1, 0); PG8_STAGE(PG8_SA(0, 1), a2 + hstep, voffA);
;             PG8_WAIT_V(8); PG8_WAIT_L(0); PG8_BAR; PG8_MMA(0, 0, At, B0); PG8_MMA(0, 1, At, B1); PG8_BAR; PG8_SCHED;
	v_mfma_f32_16x16x32_bf16 v[62:65], v[148:151], v[190:193], v[62:65]
	v_mfma_f32_16x16x32_bf16 v[58:61], v[156:159], v[190:193], v[58:61]
	v_mfma_f32_16x16x32_bf16 v[42:45], v[156:159], v[198:201], v[42:45]
	v_mfma_f32_16x16x32_bf16 v[46:49], v[148:151], v[198:201], v[46:49]
	v_mfma_f32_16x16x32_bf16 v[30:33], v[148:151], v[206:209], v[30:33]
	v_mfma_f32_16x16x32_bf16 v[26:29], v[156:159], v[206:209], v[26:29]
	v_mfma_f32_16x16x32_bf16 v[10:13], v[156:159], v[214:217], v[10:13]
	v_mfma_f32_16x16x32_bf16 v[14:17], v[148:151], v[214:217], v[14:17]
	v_mfma_f32_16x16x32_bf16 v[62:65], v[152:155], v[194:197], v[62:65]
	v_mfma_f32_16x16x32_bf16 v[58:61], v[160:163], v[194:197], v[58:61]
	v_mfma_f32_16x16x32_bf16 v[42:45], v[160:163], v[202:205], v[42:45]
	v_mfma_f32_16x16x32_bf16 v[46:49], v[152:155], v[202:205], v[46:49]
	v_mfma_f32_16x16x32_bf16 v[30:33], v[152:155], v[210:213], v[30:33]
	v_mfma_f32_16x16x32_bf16 v[26:29], v[160:163], v[210:213], v[26:29]
	v_mfma_f32_16x16x32_bf16 v[10:13], v[160:163], v[218:221], v[10:13]
	v_mfma_f32_16x16x32_bf16 v[14:17], v[152:155], v[218:221], v[14:17]
	v_mfma_f32_16x16x32_bf16 v[54:57], v[174:177], v[190:193], v[54:57]
	v_mfma_f32_16x16x32_bf16 v[50:53], v[182:185], v[190:193], v[50:53]
	v_mfma_f32_16x16x32_bf16 v[34:37], v[182:185], v[198:201], v[34:37]
	v_mfma_f32_16x16x32_bf16 v[38:41], v[174:177], v[198:201], v[38:41]
	v_mfma_f32_16x16x32_bf16 v[22:25], v[174:177], v[206:209], v[22:25]
	v_mfma_f32_16x16x32_bf16 v[18:21], v[182:185], v[206:209], v[18:21]
	v_mfma_f32_16x16x32_bf16 v[2:5], v[182:185], v[214:217], v[2:5]
	v_mfma_f32_16x16x32_bf16 v[6:9], v[174:177], v[214:217], v[6:9]
	v_mfma_f32_16x16x32_bf16 v[54:57], v[178:181], v[194:197], v[54:57]
	v_mfma_f32_16x16x32_bf16 v[50:53], v[186:189], v[194:197], v[50:53]
	v_mfma_f32_16x16x32_bf16 v[34:37], v[186:189], v[202:205], v[34:37]
	v_mfma_f32_16x16x32_bf16 v[38:41], v[178:181], v[202:205], v[38:41]
	v_mfma_f32_16x16x32_bf16 v[22:25], v[178:181], v[210:213], v[22:25]
	v_mfma_f32_16x16x32_bf16 v[18:21], v[186:189], v[210:213], v[18:21]
	v_mfma_f32_16x16x32_bf16 v[2:5], v[186:189], v[218:221], v[2:5]
	v_mfma_f32_16x16x32_bf16 v[6:9], v[178:181], v[218:221], v[6:9]
	s_barrier
	s_setprio 0
	s_add_i32 s57, 0, 0x18000
	s_add_i32 s58, 0, 0x1c000
	v_add_u32_e32 v160, s57, v167
	v_add_u32_e32 v173, s58, v167
	ds_read_b128 v[148:151], v160
	ds_read_b128 v[152:155], v160 offset:1024
	ds_read_b128 v[156:159], v160 offset:2048
	ds_read_b128 v[160:163], v160 offset:3072
	ds_read_b128 v[174:177], v173
	ds_read_b128 v[178:181], v173 offset:1024
	ds_read_b128 v[182:185], v173 offset:2048
	ds_read_b128 v[186:189], v173 offset:3072
	s_add_u32 s34, s34, 0x100000
	s_addc_u32 s35, s35, 0
	s_mov_b32 m0, s42
	v_lshl_add_u64 v[228:229], s[34:35], 0, v[136:137]
	ds_read_b128 v[190:193], v170 offset:32768
	ds_read_b128 v[194:197], v170 offset:33792
	ds_read_b128 v[198:201], v170 offset:34816
	ds_read_b128 v[202:205], v170 offset:35840
	ds_read_b128 v[206:209], v170 offset:36864
	ds_read_b128 v[210:213], v170 offset:37888
	ds_read_b128 v[214:217], v170 offset:38912
	ds_read_b128 v[218:221], v170 offset:39936
	global_load_lds_dwordx4 v[228:229], off
	v_lshl_add_u64 v[228:229], s[34:35], 0, v[132:133]
	s_mov_b32 m0, s43
	s_nop 0
	global_load_lds_dwordx4 v[228:229], off
	s_waitcnt vmcnt(8)
	s_waitcnt lgkmcnt(0)
	s_setprio 1
	s_barrier
	v_mfma_f32_16x16x32_bf16 v[126:129], v[148:151], v[190:193], v[126:129]
	v_mfma_f32_16x16x32_bf16 v[122:125], v[156:159], v[190:193], v[122:125]
	v_mfma_f32_16x16x32_bf16 v[106:109], v[156:159], v[198:201], v[106:109]
	v_mfma_f32_16x16x32_bf16 v[110:113], v[148:151], v[198:201], v[110:113]
	v_mfma_f32_16x16x32_bf16 v[94:97], v[148:151], v[206:209], v[94:97]
	v_mfma_f32_16x16x32_bf16 v[90:93], v[156:159], v[206:209], v[90:93]
	v_mfma_f32_16x16x32_bf16 v[74:77], v[156:159], v[214:217], v[74:77]
	v_mfma_f32_16x16x32_bf16 v[78:81], v[148:151], v[214:217], v[78:81]
	v_mfma_f32_16x16x32_bf16 v[126:129], v[152:155], v[194:197], v[126:129]
	v_mfma_f32_16x16x32_bf16 v[122:125], v[160:163], v[194:197], v[122:125]
	v_mfma_f32_16x16x32_bf16 v[106:109], v[160:163], v[202:205], v[106:109]
	v_mfma_f32_16x16x32_bf16 v[110:113], v[152:155], v[202:205], v[110:113]
	v_mfma_f32_16x16x32_bf16 v[94:97], v[152:155], v[210:213], v[94:97]
	v_mfma_f32_16x16x32_bf16 v[90:93], v[160:163], v[210:213], v[90:93]
	v_mfma_f32_16x16x32_bf16 v[74:77], v[160:163], v[218:221], v[74:77]
	v_mfma_f32_16x16x32_bf16 v[78:81], v[152:155], v[218:221], v[78:81]
	v_mfma_f32_16x16x32_bf16 v[118:121], v[174:177], v[190:193], v[118:121]
	v_mfma_f32_16x16x32_bf16 v[114:117], v[182:185], v[190:193], v[114:117]
	v_mfma_f32_16x16x32_bf16 v[98:101], v[182:185], v[198:201], v[98:101]
	v_mfma_f32_16x16x32_bf16 v[102:105], v[174:177], v[198:201], v[102:105]
	v_mfma_f32_16x16x32_bf16 v[86:89], v[174:177], v[206:209], v[86:89]
	v_mfma_f32_16x16x32_bf16 v[82:85], v[182:185], v[206:209], v[82:85]
	v_mfma_f32_16x16x32_bf16 v[66:69], v[182:185], v[214:217], v[66:69]
	v_mfma_f32_16x16x32_bf16 v[70:73], v[174:177], v[214:217], v[70:73]
	v_mfma_f32_16x16x32_bf16 v[118:121], v[178:181], v[194:197], v[118:121]
	v_mfma_f32_16x16x32_bf16 v[114:117], v[186:189], v[194:197], v[114:117]
	v_mfma_f32_16x16x32_bf16 v[98:101], v[186:189], v[202:205], v[98:101]
	v_mfma_f32_16x16x32_bf16 v[102:105], v[178:181], v[202:205], v[102:105]
	v_mfma_f32_16x16x32_bf16 v[86:89], v[178:181], v[210:213], v[86:89]
	v_mfma_f32_16x16x32_bf16 v[82:85], v[186:189], v[210:213], v[82:85]
	v_mfma_f32_16x16x32_bf16 v[66:69], v[186:189], v[218:221], v[66:69]
	v_mfma_f32_16x16x32_bf16 v[70:73], v[178:181], v[218:221], v[70:73]
	s_barrier
; #define PG8_STAGE(bufoff, gbase, voff) do { _Pragma("unroll") for (int _i = 0; _i < 2; ++_i) \
;         __builtin_amdgcn_global_load_lds((const unsigned*)((const char*)(gbase) + (voff)[_i]), (LAS unsigned*)(lds + (bufoff) + ldsw + _i * 8192), 16, 0, 0); } while (0)
; #define PG8_LDA(dst, b, h) do { _Pragma("unroll") for (int m = 0; m < 4; ++m) _Pragma("unroll") for (int k = 0; k < 2; ++k) dst[m][k] = *(const LAS bf16x8*)(lds + PG8_SA(b, h) + aoff + m * 2048 + k * 1024); } while (0)
; #define PG8_MMA(ai, bj, At, Bt) do { __builtin_amdgcn_s_setprio(1); _Pragma("unroll") for (int m = 0; m < 4; ++m) _Pragma("unroll") for (int n = 0; n < 2; ++n) _Pragma("unroll") for (int k = 0; k < 2; ++k) \
;         acc[ai][bj][m][n] = __builtin_amdgcn_mfma_f32_16x16x32_bf16(Bt[n][k], At[m][k], acc[ai][bj][m][n], 0, 0, 0); __builtin_amdgcn_s_setprio(0); } while (0)
; #define PG8_WAIT_V(n) asm volatile("s_waitcnt vmcnt(" #n ")" ::: "memory")
; #define PG8_WAIT_L(n) asm volatile("s_waitcnt lgkmcnt(" #n ")" ::: "memory")
; #define PG8_BAR __builtin_amdgcn_s_barrier()
; #define PG8_SCHED __builtin_amdgcn_sched_barrier(0)
; template <class Epi, class Sched, bool ALIGN_EPI = true, bool SP2 = true>
; __device__ __forceinline__ void gemm_phase(LAS unsigned char* lds, const Gemm g, const Sched& S, const Epi& E) {
;     ...
;             PG8_WAIT_V(8); PG8_WAIT_L(0); PG8_BAR; PG8_MMA(0, 0, At, B0); PG8_MMA(0, 1, At, B1); PG8_BAR; PG8_SCHED;
;             PG8_LDA(At, 1, 1); PG8_STAGE(PG8_SB(1, 0), b3, voffB); PG8_STAGE(PG8_SB(1, 1), b3 + hstep, voffB); PG8_STAGE(PG8_SA(1, 0), a3, voffA);
;             PG8_WAIT_V(8); PG8_WAIT_L(0); PG8_BAR; PG8_MMA(1, 0, At, B0); PG8_MMA(1, 1, At, B1); PG8_BAR; PG8_SCHED;
;     ...
;         if constexpr (ALIGN_EPI) { if (wr == 0) PG8_BAR; }
	s_setprio 0
	s_add_i32 s34, s57, s37
	v_lshl_add_u64 v[164:165], v[164:165], 0, s[18:19]
	s_mov_b32 m0, s34
	ds_read_b128 v[190:193], v170 offset:49152
	ds_read_b128 v[194:197], v170 offset:50176
	ds_read_b128 v[198:201], v170 offset:51200
	ds_read_b128 v[202:205], v170 offset:52224
	ds_read_b128 v[206:209], v170 offset:53248
	ds_read_b128 v[210:213], v170 offset:54272
	ds_read_b128 v[214:217], v170 offset:55296
	ds_read_b128 v[218:221], v170 offset:56320
	global_load_lds_dwordx4 v[164:165], off
	s_add_i32 m0, s34, 0x2000
	s_add_u32 s30, s30, 0x100080
	v_lshl_add_u64 v[164:165], v[222:223], 0, s[18:19]
	s_addc_u32 s31, s31, 0
	s_add_i32 s34, s58, s37
	global_load_lds_dwordx4 v[164:165], off
	v_lshl_add_u64 v[164:165], s[30:31], 0, v[134:135]
	s_mov_b32 m0, s34
	s_nop 0
	global_load_lds_dwordx4 v[164:165], off
	v_lshl_add_u64 v[164:165], s[30:31], 0, v[130:131]
	s_add_i32 m0, s34, 0x2000
	s_nop 0
	global_load_lds_dwordx4 v[164:165], off
	v_lshl_add_u64 v[164:165], v[224:225], 0, s[18:19]
	s_mov_b32 m0, s45
	s_nop 0
	global_load_lds_dwordx4 v[164:165], off
	v_lshl_add_u64 v[164:165], v[226:227], 0, s[18:19]
	s_mov_b32 m0, s46
	s_nop 0
	global_load_lds_dwordx4 v[164:165], off
	s_waitcnt vmcnt(8)
	s_waitcnt lgkmcnt(0)
	s_setprio 1
	s_barrier
	v_mfma_f32_16x16x32_bf16 v[62:65], v[148:151], v[190:193], v[62:65]
	v_mfma_f32_16x16x32_bf16 v[58:61], v[156:159], v[190:193], v[58:61]
	v_mfma_f32_16x16x32_bf16 v[42:45], v[156:159], v[198:201], v[42:45]
	v_mfma_f32_16x16x32_bf16 v[46:49], v[148:151], v[198:201], v[46:49]
	v_mfma_f32_16x16x32_bf16 v[30:33], v[148:151], v[206:209], v[30:33]
	v_mfma_f32_16x16x32_bf16 v[26:29], v[156:159], v[206:209], v[26:29]
	v_mfma_f32_16x16x32_bf16 v[10:13], v[156:159], v[214:217], v[10:13]
	v_mfma_f32_16x16x32_bf16 v[14:17], v[148:151], v[214:217], v[14:17]
	v_mfma_f32_16x16x32_bf16 v[62:65], v[152:155], v[194:197], v[62:65]
	v_mfma_f32_16x16x32_bf16 v[58:61], v[160:163], v[194:197], v[58:61]
	v_mfma_f32_16x16x32_bf16 v[42:45], v[160:163], v[202:205], v[42:45]
	v_mfma_f32_16x16x32_bf16 v[46:49], v[152:155], v[202:205], v[46:49]
	v_mfma_f32_16x16x32_bf16 v[30:33], v[152:155], v[210:213], v[30:33]
	v_mfma_f32_16x16x32_bf16 v[26:29], v[160:163], v[210:213], v[26:29]
	v_mfma_f32_16x16x32_bf16 v[10:13], v[160:163], v[218:221], v[10:13]
	v_mfma_f32_16x16x32_bf16 v[14:17], v[152:155], v[218:221], v[14:17]
	v_mfma_f32_16x16x32_bf16 v[54:57], v[174:177], v[190:193], v[54:57]
	v_mfma_f32_16x16x32_bf16 v[50:53], v[182:185], v[190:193], v[50:53]
	v_mfma_f32_16x16x32_bf16 v[34:37], v[182:185], v[198:201], v[34:37]
	v_mfma_f32_16x16x32_bf16 v[38:41], v[174:177], v[198:201], v[38:41]
	v_mfma_f32_16x16x32_bf16 v[22:25], v[174:177], v[206:209], v[22:25]
	v_mfma_f32_16x16x32_bf16 v[18:21], v[182:185], v[206:209], v[18:21]
	v_mfma_f32_16x16x32_bf16 v[2:5], v[182:185], v[214:217], v[2:5]
	v_mfma_f32_16x16x32_bf16 v[6:9], v[174:177], v[214:217], v[6:9]
	v_mfma_f32_16x16x32_bf16 v[54:57], v[178:181], v[194:197], v[54:57]
	v_mfma_f32_16x16x32_bf16 v[50:53], v[186:189], v[194:197], v[50:53]
	v_mfma_f32_16x16x32_bf16 v[34:37], v[186:189], v[202:205], v[34:37]
	v_mfma_f32_16x16x32_bf16 v[38:41], v[178:181], v[202:205], v[38:41]
	v_mfma_f32_16x16x32_bf16 v[22:25], v[178:181], v[210:213], v[22:25]
	v_mfma_f32_16x16x32_bf16 v[18:21], v[186:189], v[210:213], v[18:21]
	v_mfma_f32_16x16x32_bf16 v[2:5], v[186:189], v[218:221], v[2:5]
	v_mfma_f32_16x16x32_bf16 v[6:9], v[178:181], v[218:221], v[6:9]
	s_barrier
	s_setprio 0
	s_add_i32 s56, s56, 2
	s_add_u32 s4, s4, 0x100
	s_addc_u32 s5, s5, 0
	s_add_u32 s54, s54, 0x100
	s_addc_u32 s55, s55, 0
	s_cmp_gt_u32 s56, 61
	s_cbranch_scc0 .LBB0_1810
	s_and_b64 vcc, exec, s[20:21]
	s_cbranch_vccz .LBB0_1813
	s_barrier

; #define PG8_STAGE(bufoff, gbase, voff) do { _Pragma("unroll") for (int _i = 0; _i < 2; ++_i) \
;         __builtin_amdgcn_global_load_lds((const unsigned*)((const char*)(gbase) + (voff)[_i]), (LAS unsigned*)(lds + (bufoff) + ldsw + _i * 8192), 16, 0, 0); } while (0)
; #define PG8_LDA(dst, b, h) do { _Pragma("unroll") for (int m = 0; m < 4; ++m) _Pragma("unroll") for (int k = 0; k < 2; ++k) dst[m][k] = *(const LAS bf16x8*)(lds + PG8_SA(b, h) + aoff + m * 2048 + k * 1024); } while (0)
; #define PG8_LDB(dst, b, h) do { _Pragma("unroll") for (int n = 0; n < 2; ++n) _Pragma("unroll") for (int k = 0; k < 2; ++k) dst[n][k] = *(const LAS bf16x8*)(lds + PG8_SB(b, h) + boff + n * 2048 + k * 1024); } while (0)
; #define PG8_MMA(ai, bj, At, Bt) do { __builtin_amdgcn_s_setprio(1); _Pragma("unroll") for (int m = 0; m < 4; ++m) _Pragma("unroll") for (int n = 0; n < 2; ++n) _Pragma("unroll") for (int k = 0; k < 2; ++k) \
;         acc[ai][bj][m][n] = __builtin_amdgcn_mfma_f32_16x16x32_bf16(Bt[n][k], At[m][k], acc[ai][bj][m][n], 0, 0, 0); __builtin_amdgcn_s_setprio(0); } while (0)
; #define PG8_BAR __builtin_amdgcn_s_barrier()
; template <class Epi, class Sched, bool ALIGN_EPI = true, bool SP2 = true>
; __device__ __forceinline__ void gemm_phase(LAS unsigned char* lds, const Gemm g, const Sched& S, const Epi& E) {
;     ...
;         const char* nA = has_next ? PG8_ABASE(nxt) : cA; const char* nB = has_next ? PG8_BBASE(nxt) : cB;
;         for (int t = 0; t < nt; t += 2) {
;             const bool last = (t == nt - 2);
;             const char* a1 = cA + (size_t)(t + 1) * kstep;
;             const char* a2 = last ? nA : cA + (size_t)(t + 2) * kstep; const char* b2 = last ? nB : cB + (size_t)(t + 2) * kstep;
;             const char* a3 = a2 + kstep; const char* b3 = b2 + kstep;
;             if (last && has_next) S.a_ready(nxt);
;             if constexpr (SP2) {
;             PG8_LDB(B0, 0, 0); PG8_LDB(B1, 0, 1); PG8_SCHED; PG8_LDA(At, 0, 0); PG8_STAGE(PG8_SA(1, 1), a1 + hstep, voffA);
;             PG8_WAIT_V(8); PG8_WAIT_L(0); PG8_BAR; PG8_MMA(0, 0, At, B0); PG8_MMA(0, 1, At, B1); PG8_BAR; PG8_SCHED;
;             PG8_LDA(At, 0, 1); PG8_STAGE(PG8_SB(0, 0), b2, voffB); PG8_STAGE(PG8_SB(0, 1), b2 + hstep, voffB); PG8_STAGE(PG8_SA(0, 0), a2, voffA);
;             PG8_WAIT_V(8); PG8_WAIT_L(0); PG8_BAR; PG8_MMA(1, 0, At, B0); PG8_MMA(1, 1, At, B1); PG8_BAR; PG8_SCHED;
.LBB0_2060:
	ds_read_b128 v[130:133], v187
	ds_read_b128 v[134:137], v187 offset:1024
	ds_read_b128 v[138:141], v187 offset:2048
	ds_read_b128 v[142:145], v187 offset:3072
	ds_read_b128 v[146:149], v188
	ds_read_b128 v[150:153], v188 offset:1024
	ds_read_b128 v[170:173], v188 offset:2048
	ds_read_b128 v[192:195], v188 offset:3072
	s_add_u32 s26, s24, 0xffd50080
	s_addc_u32 s27, s25, -1
	s_cmpk_eq_i32 s53, 0xa8
	s_cselect_b32 s29, s7, s27
	s_cselect_b32 s28, s6, s26
	s_cselect_b32 s27, s23, s52
	s_cselect_b32 s26, s22, s51
	v_lshl_add_u64 v[174:175], s[24:25], 0, v[162:163]
	s_add_i32 m0, s36, 0xc000
	ds_read_b128 v[196:199], v189
	ds_read_b128 v[200:203], v189 offset:1024
	ds_read_b128 v[204:207], v189 offset:2048
	ds_read_b128 v[208:211], v189 offset:3072
	ds_read_b128 v[212:215], v189 offset:4096
	ds_read_b128 v[216:219], v189 offset:5120
	ds_read_b128 v[220:223], v189 offset:6144
	ds_read_b128 v[224:227], v189 offset:7168
	global_load_lds_dwordx4 v[174:175], off
	v_lshl_add_u64 v[174:175], s[24:25], 0, v[164:165]
	s_add_i32 m0, s36, 0xe000
	s_nop 0
	global_load_lds_dwordx4 v[174:175], off
	s_waitcnt vmcnt(8)
	s_waitcnt lgkmcnt(0)
	s_setprio 1
	s_barrier
	v_mfma_f32_16x16x32_bf16 v[126:129], v[130:133], v[196:199], v[126:129]
	v_mfma_f32_16x16x32_bf16 v[122:125], v[138:141], v[196:199], v[122:125]
	v_mfma_f32_16x16x32_bf16 v[110:113], v[130:133], v[204:207], v[110:113]
	v_mfma_f32_16x16x32_bf16 v[106:109], v[138:141], v[204:207], v[106:109]
	v_mfma_f32_16x16x32_bf16 v[94:97], v[130:133], v[212:215], v[94:97]
	v_mfma_f32_16x16x32_bf16 v[90:93], v[138:141], v[212:215], v[90:93]
	v_mfma_f32_16x16x32_bf16 v[78:81], v[130:133], v[220:223], v[78:81]
	v_mfma_f32_16x16x32_bf16 v[74:77], v[138:141], v[220:223], v[74:77]
	v_mfma_f32_16x16x32_bf16 v[126:129], v[134:137], v[200:203], v[126:129]
	v_mfma_f32_16x16x32_bf16 v[122:125], v[142:145], v[200:203], v[122:125]
	v_mfma_f32_16x16x32_bf16 v[110:113], v[134:137], v[208:211], v[110:113]
	v_mfma_f32_16x16x32_bf16 v[106:109], v[142:145], v[208:211], v[106:109]
	v_mfma_f32_16x16x32_bf16 v[94:97], v[134:137], v[216:219], v[94:97]
	v_mfma_f32_16x16x32_bf16 v[90:93], v[142:145], v[216:219], v[90:93]
	v_mfma_f32_16x16x32_bf16 v[78:81], v[134:137], v[224:227], v[78:81]
	v_mfma_f32_16x16x32_bf16 v[74:77], v[142:145], v[224:227], v[74:77]
	v_mfma_f32_16x16x32_bf16 v[118:121], v[146:149], v[196:199], v[118:121]
	v_mfma_f32_16x16x32_bf16 v[114:117], v[170:173], v[196:199], v[114:117]
	v_mfma_f32_16x16x32_bf16 v[102:105], v[146:149], v[204:207], v[102:105]
	v_mfma_f32_16x16x32_bf16 v[98:101], v[170:173], v[204:207], v[98:101]
	v_mfma_f32_16x16x32_bf16 v[86:89], v[146:149], v[212:215], v[86:89]
	v_mfma_f32_16x16x32_bf16 v[82:85], v[170:173], v[212:215], v[82:85]
	v_mfma_f32_16x16x32_bf16 v[70:73], v[146:149], v[220:223], v[70:73]
	v_mfma_f32_16x16x32_bf16 v[66:69], v[170:173], v[220:223], v[66:69]
	v_mfma_f32_16x16x32_bf16 v[118:121], v[150:153], v[200:203], v[118:121]
	v_mfma_f32_16x16x32_bf16 v[114:117], v[192:195], v[200:203], v[114:117]
	v_mfma_f32_16x16x32_bf16 v[102:105], v[150:153], v[208:211], v[102:105]
	v_mfma_f32_16x16x32_bf16 v[98:101], v[192:195], v[208:211], v[98:101]
	v_mfma_f32_16x16x32_bf16 v[86:89], v[150:153], v[216:219], v[86:89]
	v_mfma_f32_16x16x32_bf16 v[82:85], v[192:195], v[216:219], v[82:85]
	v_mfma_f32_16x16x32_bf16 v[70:73], v[150:153], v[224:227], v[70:73]
	v_mfma_f32_16x16x32_bf16 v[66:69], v[192:195], v[224:227], v[66:69]
	s_barrier
	s_setprio 0
	s_add_i32 s54, s45, s35
	v_lshl_add_u64 v[174:175], s[26:27], 0, v[156:157]
	s_mov_b32 m0, s54
	ds_read_b128 v[196:199], v189 offset:16384
	ds_read_b128 v[200:203], v189 offset:17408
	ds_read_b128 v[204:207], v189 offset:18432
	ds_read_b128 v[208:211], v189 offset:19456
	ds_read_b128 v[212:215], v189 offset:20480
	ds_read_b128 v[216:219], v189 offset:21504
	ds_read_b128 v[220:223], v189 offset:22528
	ds_read_b128 v[224:227], v189 offset:23552
	global_load_lds_dwordx4 v[174:175], off
	s_add_i32 m0, s54, 0x2000
	s_add_u32 s54, s26, 0x2b0000
	v_lshl_add_u64 v[228:229], s[26:27], 0, v[160:161]
	s_addc_u32 s55, s27, 0
	s_add_i32 s56, s46, s35
	global_load_lds_dwordx4 v[228:229], off
	v_lshl_add_u64 v[230:231], s[54:55], 0, v[156:157]
	s_mov_b32 m0, s56
	v_lshl_add_u64 v[232:233], s[28:29], 0, v[158:159]
	global_load_lds_dwordx4 v[230:231], off
	v_lshl_add_u64 v[230:231], s[54:55], 0, v[160:161]
	s_add_i32 m0, s56, 0x2000
	s_nop 0
	global_load_lds_dwordx4 v[230:231], off
	v_lshl_add_u64 v[230:231], s[28:29], 0, v[154:155]
	s_mov_b32 m0, s36
	s_nop 0
	global_load_lds_dwordx4 v[230:231], off
	s_mov_b32 m0, s37
	s_nop 0
	global_load_lds_dwordx4 v[232:233], off
	s_waitcnt vmcnt(8)
	s_waitcnt lgkmcnt(0)
	s_setprio 1
	s_barrier
; #define PG8_STAGE(bufoff, gbase, voff) do { _Pragma("unroll") for (int _i = 0; _i < 2; ++_i) \
;         __builtin_amdgcn_global_load_lds((const unsigned*)((const char*)(gbase) + (voff)[_i]), (LAS unsigned*)(lds + (bufoff) + ldsw + _i * 8192), 16, 0, 0); } while (0)
; #define PG8_LDA(dst, b, h) do { _Pragma("unroll") for (int m = 0; m < 4; ++m) _Pragma("unroll") for (int k = 0; k < 2; ++k) dst[m][k] = *(const LAS bf16x8*)(lds + PG8_SA(b, h) + aoff + m * 2048 + k * 1024); } while (0)
; #define PG8_LDB(dst, b, h) do { _Pragma("unroll") for (int n = 0; n < 2; ++n) _Pragma("unroll") for (int k = 0; k < 2; ++k) dst[n][k] = *(const LAS bf16x8*)(lds + PG8_SB(b, h) + boff + n * 2048 + k * 1024); } while (0)
; #define PG8_MMA(ai, bj, At, Bt) do { __builtin_amdgcn_s_setprio(1); _Pragma("unroll") for (int m = 0; m < 4; ++m) _Pragma("unroll") for (int n = 0; n < 2; ++n) _Pragma("unroll") for (int k = 0; k < 2; ++k) \
;         acc[ai][bj][m][n] = __builtin_amdgcn_mfma_f32_16x16x32_bf16(Bt[n][k], At[m][k], acc[ai][bj][m][n], 0, 0, 0); __builtin_amdgcn_s_setprio(0); } while (0)
; #define PG8_WAIT_V(n) asm volatile("s_waitcnt vmcnt(" #n ")" ::: "memory")
; #define PG8_WAIT_L(n) asm volatile("s_waitcnt lgkmcnt(" #n ")" ::: "memory")
; #define PG8_BAR __builtin_amdgcn_s_barrier()
; #define PG8_SCHED __builtin_amdgcn_sched_barrier(0)
; template <class Epi, class Sched, bool ALIGN_EPI = true, bool SP2 = true>
; __device__ __forceinline__ void gemm_phase(LAS unsigned char* lds, const Gemm g, const Sched& S, const Epi& E) {
;     ...
;             PG8_WAIT_V(8); PG8_WAIT_L(0); PG8_BAR; PG8_MMA(1, 0, At, B0); PG8_MMA(1, 1, At, B1); PG8_BAR; PG8_SCHED;
;             PG8_LDB(B0, 1, 0); PG8_LDB(B1, 1, 1); PG8_SCHED; PG8_LDA(At, 1, 0); PG8_STAGE(PG8_SA(0, 1), a2 + hstep, voffA);
;             PG8_WAIT_V(8); PG8_WAIT_L(0); PG8_BAR; PG8_MMA(0, 0, At, B0); PG8_MMA(0, 1, At, B1); PG8_BAR; PG8_SCHED;
	v_mfma_f32_16x16x32_bf16 v[62:65], v[130:133], v[196:199], v[62:65]
	v_mfma_f32_16x16x32_bf16 v[58:61], v[138:141], v[196:199], v[58:61]
	v_mfma_f32_16x16x32_bf16 v[46:49], v[130:133], v[204:207], v[46:49]
	v_mfma_f32_16x16x32_bf16 v[42:45], v[138:141], v[204:207], v[42:45]
	v_mfma_f32_16x16x32_bf16 v[30:33], v[130:133], v[212:215], v[30:33]
	v_mfma_f32_16x16x32_bf16 v[26:29], v[138:141], v[212:215], v[26:29]
	v_mfma_f32_16x16x32_bf16 v[14:17], v[130:133], v[220:223], v[14:17]
	v_mfma_f32_16x16x32_bf16 v[10:13], v[138:141], v[220:223], v[10:13]
	v_mfma_f32_16x16x32_bf16 v[62:65], v[134:137], v[200:203], v[62:65]
	v_mfma_f32_16x16x32_bf16 v[58:61], v[142:145], v[200:203], v[58:61]
	v_mfma_f32_16x16x32_bf16 v[46:49], v[134:137], v[208:211], v[46:49]
	v_mfma_f32_16x16x32_bf16 v[42:45], v[142:145], v[208:211], v[42:45]
	v_mfma_f32_16x16x32_bf16 v[30:33], v[134:137], v[216:219], v[30:33]
	v_mfma_f32_16x16x32_bf16 v[26:29], v[142:145], v[216:219], v[26:29]
	v_mfma_f32_16x16x32_bf16 v[14:17], v[134:137], v[224:227], v[14:17]
	v_mfma_f32_16x16x32_bf16 v[10:13], v[142:145], v[224:227], v[10:13]
	v_mfma_f32_16x16x32_bf16 v[54:57], v[146:149], v[196:199], v[54:57]
	v_mfma_f32_16x16x32_bf16 v[50:53], v[170:173], v[196:199], v[50:53]
	v_mfma_f32_16x16x32_bf16 v[38:41], v[146:149], v[204:207], v[38:41]
	v_mfma_f32_16x16x32_bf16 v[34:37], v[170:173], v[204:207], v[34:37]
	v_mfma_f32_16x16x32_bf16 v[22:25], v[146:149], v[212:215], v[22:25]
	v_mfma_f32_16x16x32_bf16 v[18:21], v[170:173], v[212:215], v[18:21]
	v_mfma_f32_16x16x32_bf16 v[6:9], v[146:149], v[220:223], v[6:9]
	v_mfma_f32_16x16x32_bf16 v[2:5], v[170:173], v[220:223], v[2:5]
	v_mfma_f32_16x16x32_bf16 v[54:57], v[150:153], v[200:203], v[54:57]
	v_mfma_f32_16x16x32_bf16 v[50:53], v[192:195], v[200:203], v[50:53]
	v_mfma_f32_16x16x32_bf16 v[38:41], v[150:153], v[208:211], v[38:41]
	v_mfma_f32_16x16x32_bf16 v[34:37], v[192:195], v[208:211], v[34:37]
	v_mfma_f32_16x16x32_bf16 v[22:25], v[150:153], v[216:219], v[22:25]
	v_mfma_f32_16x16x32_bf16 v[18:21], v[192:195], v[216:219], v[18:21]
	v_mfma_f32_16x16x32_bf16 v[6:9], v[150:153], v[224:227], v[6:9]
	v_mfma_f32_16x16x32_bf16 v[2:5], v[192:195], v[224:227], v[2:5]
	s_barrier
	s_setprio 0
	s_add_i32 s54, 0, 0x18000
	s_add_i32 s55, 0, 0x1c000
	v_add_u32_e32 v142, s54, v185
	v_add_u32_e32 v191, s55, v185
	ds_read_b128 v[130:133], v142
	ds_read_b128 v[134:137], v142 offset:1024
	ds_read_b128 v[138:141], v142 offset:2048
	ds_read_b128 v[142:145], v142 offset:3072
	ds_read_b128 v[146:149], v191
	ds_read_b128 v[150:153], v191 offset:1024
	ds_read_b128 v[170:173], v191 offset:2048
	ds_read_b128 v[192:195], v191 offset:3072
	s_add_u32 s28, s28, 0x2b0000
	s_addc_u32 s29, s29, 0
	s_mov_b32 m0, s38
	v_lshl_add_u64 v[234:235], s[28:29], 0, v[154:155]
	ds_read_b128 v[196:199], v189 offset:32768
	ds_read_b128 v[200:203], v189 offset:33792
	ds_read_b128 v[204:207], v189 offset:34816
	ds_read_b128 v[208:211], v189 offset:35840
	ds_read_b128 v[212:215], v189 offset:36864
	ds_read_b128 v[216:219], v189 offset:37888
	ds_read_b128 v[220:223], v189 offset:38912
	ds_read_b128 v[224:227], v189 offset:39936
	global_load_lds_dwordx4 v[234:235], off
	v_lshl_add_u64 v[234:235], s[28:29], 0, v[158:159]
	s_mov_b32 m0, s39
	s_nop 0
	global_load_lds_dwordx4 v[234:235], off
	s_waitcnt vmcnt(8)
	s_waitcnt lgkmcnt(0)
	s_setprio 1
	s_barrier
	v_mfma_f32_16x16x32_bf16 v[126:129], v[130:133], v[196:199], v[126:129]
	v_mfma_f32_16x16x32_bf16 v[122:125], v[138:141], v[196:199], v[122:125]
	v_mfma_f32_16x16x32_bf16 v[110:113], v[130:133], v[204:207], v[110:113]
	v_mfma_f32_16x16x32_bf16 v[106:109], v[138:141], v[204:207], v[106:109]
	v_mfma_f32_16x16x32_bf16 v[94:97], v[130:133], v[212:215], v[94:97]
	v_mfma_f32_16x16x32_bf16 v[90:93], v[138:141], v[212:215], v[90:93]
	v_mfma_f32_16x16x32_bf16 v[78:81], v[130:133], v[220:223], v[78:81]
	v_mfma_f32_16x16x32_bf16 v[74:77], v[138:141], v[220:223], v[74:77]
	v_mfma_f32_16x16x32_bf16 v[126:129], v[134:137], v[200:203], v[126:129]
	v_mfma_f32_16x16x32_bf16 v[122:125], v[142:145], v[200:203], v[122:125]
	v_mfma_f32_16x16x32_bf16 v[110:113], v[134:137], v[208:211], v[110:113]
	v_mfma_f32_16x16x32_bf16 v[106:109], v[142:145], v[208:211], v[106:109]
	v_mfma_f32_16x16x32_bf16 v[94:97], v[134:137], v[216:219], v[94:97]
	v_mfma_f32_16x16x32_bf16 v[90:93], v[142:145], v[216:219], v[90:93]
	v_mfma_f32_16x16x32_bf16 v[78:81], v[134:137], v[224:227], v[78:81]
	v_mfma_f32_16x16x32_bf16 v[74:77], v[142:145], v[224:227], v[74:77]
	v_mfma_f32_16x16x32_bf16 v[118:121], v[146:149], v[196:199], v[118:121]
	v_mfma_f32_16x16x32_bf16 v[114:117], v[170:173], v[196:199], v[114:117]
	v_mfma_f32_16x16x32_bf16 v[102:105], v[146:149], v[204:207], v[102:105]
	v_mfma_f32_16x16x32_bf16 v[98:101], v[170:173], v[204:207], v[98:101]
	v_mfma_f32_16x16x32_bf16 v[86:89], v[146:149], v[212:215], v[86:89]
	v_mfma_f32_16x16x32_bf16 v[82:85], v[170:173], v[212:215], v[82:85]
	v_mfma_f32_16x16x32_bf16 v[70:73], v[146:149], v[220:223], v[70:73]
	v_mfma_f32_16x16x32_bf16 v[66:69], v[170:173], v[220:223], v[66:69]
	v_mfma_f32_16x16x32_bf16 v[118:121], v[150:153], v[200:203], v[118:121]
	v_mfma_f32_16x16x32_bf16 v[114:117], v[192:195], v[200:203], v[114:117]
	v_mfma_f32_16x16x32_bf16 v[102:105], v[150:153], v[208:211], v[102:105]
	v_mfma_f32_16x16x32_bf16 v[98:101], v[192:195], v[208:211], v[98:101]
	v_mfma_f32_16x16x32_bf16 v[86:89], v[150:153], v[216:219], v[86:89]
	v_mfma_f32_16x16x32_bf16 v[82:85], v[192:195], v[216:219], v[82:85]
	v_mfma_f32_16x16x32_bf16 v[70:73], v[150:153], v[224:227], v[70:73]
	v_mfma_f32_16x16x32_bf16 v[66:69], v[192:195], v[224:227], v[66:69]
	s_barrier
; #define PG8_STAGE(bufoff, gbase, voff) do { _Pragma("unroll") for (int _i = 0; _i < 2; ++_i) \
;         __builtin_amdgcn_global_load_lds((const unsigned*)((const char*)(gbase) + (voff)[_i]), (LAS unsigned*)(lds + (bufoff) + ldsw + _i * 8192), 16, 0, 0); } while (0)
; #define PG8_LDA(dst, b, h) do { _Pragma("unroll") for (int m = 0; m < 4; ++m) _Pragma("unroll") for (int k = 0; k < 2; ++k) dst[m][k] = *(const LAS bf16x8*)(lds + PG8_SA(b, h) + aoff + m * 2048 + k * 1024); } while (0)
; #define PG8_MMA(ai, bj, At, Bt) do { __builtin_amdgcn_s_setprio(1); _Pragma("unroll") for (int m = 0; m < 4; ++m) _Pragma("unroll") for (int n = 0; n < 2; ++n) _Pragma("unroll") for (int k = 0; k < 2; ++k) \
;         acc[ai][bj][m][n] = __builtin_amdgcn_mfma_f32_16x16x32_bf16(Bt[n][k], At[m][k], acc[ai][bj][m][n], 0, 0, 0); __builtin_amdgcn_s_setprio(0); } while (0)
; #define PG8_WAIT_V(n) asm volatile("s_waitcnt vmcnt(" #n ")" ::: "memory")
; #define PG8_WAIT_L(n) asm volatile("s_waitcnt lgkmcnt(" #n ")" ::: "memory")
; #define PG8_BAR __builtin_amdgcn_s_barrier()
; #define PG8_SCHED __builtin_amdgcn_sched_barrier(0)
; template <class Epi, class Sched, bool ALIGN_EPI = true, bool SP2 = true>
; __device__ __forceinline__ void gemm_phase(LAS unsigned char* lds, const Gemm g, const Sched& S, const Epi& E) {
;     ...
;             PG8_WAIT_V(8); PG8_WAIT_L(0); PG8_BAR; PG8_MMA(0, 0, At, B0); PG8_MMA(0, 1, At, B1); PG8_BAR; PG8_SCHED;
;             PG8_LDA(At, 1, 1); PG8_STAGE(PG8_SB(1, 0), b3, voffB); PG8_STAGE(PG8_SB(1, 1), b3 + hstep, voffB); PG8_STAGE(PG8_SA(1, 0), a3, voffA);
;             PG8_WAIT_V(8); PG8_WAIT_L(0); PG8_BAR; PG8_MMA(1, 0, At, B0); PG8_MMA(1, 1, At, B1); PG8_BAR; PG8_SCHED;
;     ...
;         if constexpr (ALIGN_EPI) { if (wr == 0) PG8_BAR; }
	s_setprio 0
	s_add_i32 s28, s54, s35
	v_lshl_add_u64 v[174:175], v[174:175], 0, s[18:19]
	s_mov_b32 m0, s28
	ds_read_b128 v[196:199], v189 offset:49152
	ds_read_b128 v[200:203], v189 offset:50176
	ds_read_b128 v[204:207], v189 offset:51200
	ds_read_b128 v[208:211], v189 offset:52224
	ds_read_b128 v[212:215], v189 offset:53248
	ds_read_b128 v[216:219], v189 offset:54272
	ds_read_b128 v[220:223], v189 offset:55296
	ds_read_b128 v[224:227], v189 offset:56320
	global_load_lds_dwordx4 v[174:175], off
	s_add_i32 m0, s28, 0x2000
	s_add_u32 s26, s26, 0x2b0080
	v_lshl_add_u64 v[174:175], v[228:229], 0, s[18:19]
	s_addc_u32 s27, s27, 0
	s_add_i32 s28, s55, s35
	global_load_lds_dwordx4 v[174:175], off
	v_lshl_add_u64 v[174:175], s[26:27], 0, v[156:157]
	s_mov_b32 m0, s28
	s_nop 0
	global_load_lds_dwordx4 v[174:175], off
	v_lshl_add_u64 v[174:175], s[26:27], 0, v[160:161]
	s_add_i32 m0, s28, 0x2000
	s_nop 0
	global_load_lds_dwordx4 v[174:175], off
	v_lshl_add_u64 v[174:175], v[230:231], 0, s[18:19]
	s_mov_b32 m0, s41
	s_nop 0
	global_load_lds_dwordx4 v[174:175], off
	v_lshl_add_u64 v[174:175], v[232:233], 0, s[18:19]
	s_mov_b32 m0, s42
	s_nop 0
	global_load_lds_dwordx4 v[174:175], off
	s_waitcnt vmcnt(8)
	s_waitcnt lgkmcnt(0)
	s_setprio 1
	s_barrier
	v_mfma_f32_16x16x32_bf16 v[62:65], v[130:133], v[196:199], v[62:65]
	v_mfma_f32_16x16x32_bf16 v[58:61], v[138:141], v[196:199], v[58:61]
	v_mfma_f32_16x16x32_bf16 v[46:49], v[130:133], v[204:207], v[46:49]
	v_mfma_f32_16x16x32_bf16 v[42:45], v[138:141], v[204:207], v[42:45]
	v_mfma_f32_16x16x32_bf16 v[30:33], v[130:133], v[212:215], v[30:33]
	v_mfma_f32_16x16x32_bf16 v[26:29], v[138:141], v[212:215], v[26:29]
	v_mfma_f32_16x16x32_bf16 v[14:17], v[130:133], v[220:223], v[14:17]
	v_mfma_f32_16x16x32_bf16 v[10:13], v[138:141], v[220:223], v[10:13]
	v_mfma_f32_16x16x32_bf16 v[62:65], v[134:137], v[200:203], v[62:65]
	v_mfma_f32_16x16x32_bf16 v[58:61], v[142:145], v[200:203], v[58:61]
	v_mfma_f32_16x16x32_bf16 v[46:49], v[134:137], v[208:211], v[46:49]
	v_mfma_f32_16x16x32_bf16 v[42:45], v[142:145], v[208:211], v[42:45]
	v_mfma_f32_16x16x32_bf16 v[30:33], v[134:137], v[216:219], v[30:33]
	v_mfma_f32_16x16x32_bf16 v[26:29], v[142:145], v[216:219], v[26:29]
	v_mfma_f32_16x16x32_bf16 v[14:17], v[134:137], v[224:227], v[14:17]
	v_mfma_f32_16x16x32_bf16 v[10:13], v[142:145], v[224:227], v[10:13]
	v_mfma_f32_16x16x32_bf16 v[54:57], v[146:149], v[196:199], v[54:57]
	v_mfma_f32_16x16x32_bf16 v[50:53], v[170:173], v[196:199], v[50:53]
	v_mfma_f32_16x16x32_bf16 v[38:41], v[146:149], v[204:207], v[38:41]
	v_mfma_f32_16x16x32_bf16 v[34:37], v[170:173], v[204:207], v[34:37]
	v_mfma_f32_16x16x32_bf16 v[22:25], v[146:149], v[212:215], v[22:25]
	v_mfma_f32_16x16x32_bf16 v[18:21], v[170:173], v[212:215], v[18:21]
	v_mfma_f32_16x16x32_bf16 v[6:9], v[146:149], v[220:223], v[6:9]
	v_mfma_f32_16x16x32_bf16 v[2:5], v[170:173], v[220:223], v[2:5]
	v_mfma_f32_16x16x32_bf16 v[54:57], v[150:153], v[200:203], v[54:57]
	v_mfma_f32_16x16x32_bf16 v[50:53], v[192:195], v[200:203], v[50:53]
	v_mfma_f32_16x16x32_bf16 v[38:41], v[150:153], v[208:211], v[38:41]
	v_mfma_f32_16x16x32_bf16 v[34:37], v[192:195], v[208:211], v[34:37]
	v_mfma_f32_16x16x32_bf16 v[22:25], v[150:153], v[216:219], v[22:25]
	v_mfma_f32_16x16x32_bf16 v[18:21], v[192:195], v[216:219], v[18:21]
	v_mfma_f32_16x16x32_bf16 v[6:9], v[150:153], v[224:227], v[6:9]
	v_mfma_f32_16x16x32_bf16 v[2:5], v[192:195], v[224:227], v[2:5]
	s_barrier
	s_setprio 0
	s_add_i32 s53, s53, 2
	s_add_u32 s24, s24, 0x100
	s_addc_u32 s25, s25, 0
	s_add_u32 s51, s51, 0x100
	s_addc_u32 s52, s52, 0
	s_cmpk_gt_u32 s53, 0xa9
	s_cbranch_scc0 .LBB0_2060
	s_and_b64 vcc, exec, s[20:21]
	s_cbranch_vccz .LBB0_2063
	s_barrier

;     __host__ __device__ bool next(int i, Unit& u) const { const bool ok = StaticOrder::next(i >> 1, u); u.z = i & 1; return ok; }
; #define PG8_STAGE(bufoff, gbase, voff) do { _Pragma("unroll") for (int _i = 0; _i < 2; ++_i) \
;         __builtin_amdgcn_global_load_lds((const unsigned*)((const char*)(gbase) + (voff)[_i]), (LAS unsigned*)(lds + (bufoff) + ldsw + _i * 8192), 16, 0, 0); } while (0)
; #define PG8_LDA(dst, b, h) do { _Pragma("unroll") for (int m = 0; m < 4; ++m) _Pragma("unroll") for (int k = 0; k < 2; ++k) dst[m][k] = *(const LAS bf16x8*)(lds + PG8_SA(b, h) + aoff + m * 2048 + k * 1024); } while (0)
; #define PG8_LDB(dst, b, h) do { _Pragma("unroll") for (int n = 0; n < 2; ++n) _Pragma("unroll") for (int k = 0; k < 2; ++k) dst[n][k] = *(const LAS bf16x8*)(lds + PG8_SB(b, h) + boff + n * 2048 + k * 1024); } while (0)
; #define PG8_WAIT_V(n) asm volatile("s_waitcnt vmcnt(" #n ")" ::: "memory")
; #define PG8_WAIT_L(n) asm volatile("s_waitcnt lgkmcnt(" #n ")" ::: "memory")
; #define PG8_BAR __builtin_amdgcn_s_barrier()
; template <class Epi, class Sched, bool ALIGN_EPI = true, bool SP2 = true>
; __device__ __forceinline__ void gemm_phase(LAS unsigned char* lds, const Gemm g, const Sched& S, const Epi& E) {
;     ...
;         const bool has_next = S.next(ui + 1, nxt);
;         const char* nA = has_next ? PG8_ABASE(nxt) : cA; const char* nB = has_next ? PG8_BBASE(nxt) : cB;
;         for (int t = 0; t < nt; t += 2) {
;             const bool last = (t == nt - 2);
;             const char* a1 = cA + (size_t)(t + 1) * kstep;
;             const char* a2 = last ? nA : cA + (size_t)(t + 2) * kstep; const char* b2 = last ? nB : cB + (size_t)(t + 2) * kstep;
;             const char* a3 = a2 + kstep; const char* b3 = b2 + kstep;
;             if (last && has_next) S.a_ready(nxt);
;             if constexpr (SP2) {
;             PG8_LDB(B0, 0, 0); PG8_LDB(B1, 0, 1); PG8_SCHED; PG8_LDA(At, 0, 0); PG8_STAGE(PG8_SA(1, 1), a1 + hstep, voffA);
;             PG8_WAIT_V(8); PG8_WAIT_L(0); PG8_BAR; PG8_MMA(0, 0, At, B0); PG8_MMA(0, 1, At, B1); PG8_BAR; PG8_SCHED;
;             PG8_LDA(At, 0, 1); PG8_STAGE(PG8_SB(0, 0), b2, voffB); PG8_STAGE(PG8_SB(0, 1), b2 + hstep, voffB); PG8_STAGE(PG8_SA(0, 0), a2, voffA);
;             PG8_WAIT_V(8); PG8_WAIT_L(0); PG8_BAR; PG8_MMA(1, 0, At, B0); PG8_MMA(1, 1, At, B1); PG8_BAR; PG8_SCHED;
.LBB0_2100:
	s_add_u32 s31, s24, s30
	s_addc_u32 s38, s25, 0
	s_add_u32 s36, s31, 0x100
	s_addc_u32 s37, s38, 0
	s_and_b64 s[34:35], s[28:29], exec
	s_cselect_b32 s35, s15, s37
	s_cselect_b32 s34, s57, s36
	s_add_u32 s30, s22, s30
	s_addc_u32 s36, s23, 0
	s_add_u32 s30, s30, 0x100
	s_addc_u32 s36, s36, 0
	s_and_b64 s[28:29], s[28:29], exec
	s_cselect_b32 s37, s13, s36
	s_cselect_b32 s36, s58, s30
	s_add_u32 s40, s31, 0x10080
	ds_read_b128 v[142:145], v148
	ds_read_b128 v[152:155], v148 offset:1024
	ds_read_b128 v[156:159], v148 offset:2048
	ds_read_b128 v[160:163], v148 offset:3072
	ds_read_b128 v[164:167], v149
	ds_read_b128 v[168:171], v149 offset:1024
	ds_read_b128 v[172:175], v149 offset:2048
	ds_read_b128 v[176:179], v149 offset:3072
	s_addc_u32 s41, s38, 0
	s_add_i32 s66, s54, s46
	s_add_i32 m0, s21, 0xc000
	s_add_i32 s69, s21, 0xe000
	s_add_i32 s63, s66, 0x2000
	s_add_u32 s38, s36, 0x10000
	s_addc_u32 s39, s37, 0
	s_add_i32 s65, s55, s46
	s_add_i32 s64, s65, 0x2000
	s_add_i32 s62, 0, 0x18000
	s_add_i32 s61, 0, 0x1c000
	s_add_u32 s30, s34, 0x10000
	s_addc_u32 s31, s35, 0
	s_add_i32 s60, s62, s46
	s_add_i32 s59, s60, 0x2000
	s_add_u32 s28, s36, 0x10080
	s_addc_u32 s29, s37, 0
	s_add_i32 s68, s61, s46
	s_add_i32 s67, s68, 0x2000
	v_lshl_add_u64 v[212:213], s[40:41], 0, v[130:131]
	ds_read_b128 v[180:183], v150
	ds_read_b128 v[184:187], v150 offset:1024
	ds_read_b128 v[188:191], v150 offset:2048
	ds_read_b128 v[192:195], v150 offset:3072
	ds_read_b128 v[196:199], v150 offset:4096
	ds_read_b128 v[200:203], v150 offset:5120
	ds_read_b128 v[204:207], v150 offset:6144
	ds_read_b128 v[208:211], v150 offset:7168
	global_load_lds_dwordx4 v[212:213], off
	v_lshl_add_u64 v[212:213], s[40:41], 0, v[134:135]
	s_mov_b32 m0, s69
	s_nop 0
	global_load_lds_dwordx4 v[212:213], off
	s_waitcnt vmcnt(8)
	s_waitcnt lgkmcnt(0)
	s_setprio 1
	s_barrier
	v_mfma_f32_16x16x32_bf16 v[126:129], v[142:145], v[180:183], v[126:129]
	v_mfma_f32_16x16x32_bf16 v[122:125], v[156:159], v[180:183], v[122:125]
	v_mfma_f32_16x16x32_bf16 v[118:121], v[142:145], v[188:191], v[118:121]
	v_mfma_f32_16x16x32_bf16 v[110:113], v[156:159], v[188:191], v[110:113]
	v_mfma_f32_16x16x32_bf16 v[102:105], v[142:145], v[196:199], v[102:105]
	v_mfma_f32_16x16x32_bf16 v[94:97], v[156:159], v[196:199], v[94:97]
	v_mfma_f32_16x16x32_bf16 v[86:89], v[142:145], v[204:207], v[86:89]
	v_mfma_f32_16x16x32_bf16 v[78:81], v[156:159], v[204:207], v[78:81]
	v_mfma_f32_16x16x32_bf16 v[126:129], v[152:155], v[184:187], v[126:129]
	v_mfma_f32_16x16x32_bf16 v[122:125], v[160:163], v[184:187], v[122:125]
	v_mfma_f32_16x16x32_bf16 v[118:121], v[152:155], v[192:195], v[118:121]
	v_mfma_f32_16x16x32_bf16 v[110:113], v[160:163], v[192:195], v[110:113]
	v_mfma_f32_16x16x32_bf16 v[102:105], v[152:155], v[200:203], v[102:105]
	v_mfma_f32_16x16x32_bf16 v[94:97], v[160:163], v[200:203], v[94:97]
	v_mfma_f32_16x16x32_bf16 v[86:89], v[152:155], v[208:211], v[86:89]
	v_mfma_f32_16x16x32_bf16 v[78:81], v[160:163], v[208:211], v[78:81]
	v_mfma_f32_16x16x32_bf16 v[114:117], v[164:167], v[180:183], v[114:117]
	v_mfma_f32_16x16x32_bf16 v[106:109], v[172:175], v[180:183], v[106:109]
	v_mfma_f32_16x16x32_bf16 v[98:101], v[164:167], v[188:191], v[98:101]
	v_mfma_f32_16x16x32_bf16 v[90:93], v[172:175], v[188:191], v[90:93]
	v_mfma_f32_16x16x32_bf16 v[82:85], v[164:167], v[196:199], v[82:85]
	v_mfma_f32_16x16x32_bf16 v[74:77], v[172:175], v[196:199], v[74:77]
	v_mfma_f32_16x16x32_bf16 v[70:73], v[164:167], v[204:207], v[70:73]
	v_mfma_f32_16x16x32_bf16 v[66:69], v[172:175], v[204:207], v[66:69]
	v_mfma_f32_16x16x32_bf16 v[114:117], v[168:171], v[184:187], v[114:117]
	v_mfma_f32_16x16x32_bf16 v[106:109], v[176:179], v[184:187], v[106:109]
	v_mfma_f32_16x16x32_bf16 v[98:101], v[168:171], v[192:195], v[98:101]
	v_mfma_f32_16x16x32_bf16 v[90:93], v[176:179], v[192:195], v[90:93]
	v_mfma_f32_16x16x32_bf16 v[82:85], v[168:171], v[200:203], v[82:85]
	v_mfma_f32_16x16x32_bf16 v[74:77], v[176:179], v[200:203], v[74:77]
	v_mfma_f32_16x16x32_bf16 v[70:73], v[168:171], v[208:211], v[70:73]
	v_mfma_f32_16x16x32_bf16 v[66:69], v[176:179], v[208:211], v[66:69]
	s_barrier
	s_setprio 0
	s_mov_b32 m0, s66
	v_lshl_add_u64 v[212:213], s[36:37], 0, v[132:133]
	ds_read_b128 v[180:183], v150 offset:16384
	ds_read_b128 v[184:187], v150 offset:17408
	ds_read_b128 v[188:191], v150 offset:18432
	ds_read_b128 v[192:195], v150 offset:19456
	ds_read_b128 v[196:199], v150 offset:20480
	ds_read_b128 v[200:203], v150 offset:21504
	ds_read_b128 v[204:207], v150 offset:22528
	ds_read_b128 v[208:211], v150 offset:23552
	global_load_lds_dwordx4 v[212:213], off
	v_lshl_add_u64 v[214:215], s[36:37], 0, v[136:137]
	s_mov_b32 m0, s63
	v_lshl_add_u64 v[216:217], s[38:39], 0, v[132:133]
	global_load_lds_dwordx4 v[214:215], off
	s_mov_b32 m0, s65
	v_lshl_add_u64 v[218:219], s[34:35], 0, v[134:135]
	global_load_lds_dwordx4 v[216:217], off
	v_lshl_add_u64 v[216:217], s[38:39], 0, v[136:137]
	s_mov_b32 m0, s64
	s_nop 0
	global_load_lds_dwordx4 v[216:217], off
	v_lshl_add_u64 v[216:217], s[34:35], 0, v[130:131]
	s_mov_b32 m0, s21
	s_nop 0
	global_load_lds_dwordx4 v[216:217], off
	s_mov_b32 m0, s47
	s_nop 0
	global_load_lds_dwordx4 v[218:219], off
	s_waitcnt vmcnt(8)
	s_waitcnt lgkmcnt(0)
	s_setprio 1
	s_barrier
; #define PG8_STAGE(bufoff, gbase, voff) do { _Pragma("unroll") for (int _i = 0; _i < 2; ++_i) \
;         __builtin_amdgcn_global_load_lds((const unsigned*)((const char*)(gbase) + (voff)[_i]), (LAS unsigned*)(lds + (bufoff) + ldsw + _i * 8192), 16, 0, 0); } while (0)
; #define PG8_LDA(dst, b, h) do { _Pragma("unroll") for (int m = 0; m < 4; ++m) _Pragma("unroll") for (int k = 0; k < 2; ++k) dst[m][k] = *(const LAS bf16x8*)(lds + PG8_SA(b, h) + aoff + m * 2048 + k * 1024); } while (0)
; #define PG8_LDB(dst, b, h) do { _Pragma("unroll") for (int n = 0; n < 2; ++n) _Pragma("unroll") for (int k = 0; k < 2; ++k) dst[n][k] = *(const LAS bf16x8*)(lds + PG8_SB(b, h) + boff + n * 2048 + k * 1024); } while (0)
; #define PG8_MMA(ai, bj, At, Bt) do { __builtin_amdgcn_s_setprio(1); _Pragma("unroll") for (int m = 0; m < 4; ++m) _Pragma("unroll") for (int n = 0; n < 2; ++n) _Pragma("unroll") for (int k = 0; k < 2; ++k) \
;         acc[ai][bj][m][n] = __builtin_amdgcn_mfma_f32_16x16x32_bf16(Bt[n][k], At[m][k], acc[ai][bj][m][n], 0, 0, 0); __builtin_amdgcn_s_setprio(0); } while (0)
; #define PG8_WAIT_V(n) asm volatile("s_waitcnt vmcnt(" #n ")" ::: "memory")
; #define PG8_WAIT_L(n) asm volatile("s_waitcnt lgkmcnt(" #n ")" ::: "memory")
; #define PG8_BAR __builtin_amdgcn_s_barrier()
; #define PG8_SCHED __builtin_amdgcn_sched_barrier(0)
; template <class Epi, class Sched, bool ALIGN_EPI = true, bool SP2 = true>
; __device__ __forceinline__ void gemm_phase(LAS unsigned char* lds, const Gemm g, const Sched& S, const Epi& E) {
;     ...
;             PG8_WAIT_V(8); PG8_WAIT_L(0); PG8_BAR; PG8_MMA(1, 0, At, B0); PG8_MMA(1, 1, At, B1); PG8_BAR; PG8_SCHED;
;             PG8_LDB(B0, 1, 0); PG8_LDB(B1, 1, 1); PG8_SCHED; PG8_LDA(At, 1, 0); PG8_STAGE(PG8_SA(0, 1), a2 + hstep, voffA);
;             PG8_WAIT_V(8); PG8_WAIT_L(0); PG8_BAR; PG8_MMA(0, 0, At, B0); PG8_MMA(0, 1, At, B1); PG8_BAR; PG8_SCHED;
	v_mfma_f32_16x16x32_bf16 v[62:65], v[142:145], v[180:183], v[62:65]
	v_mfma_f32_16x16x32_bf16 v[58:61], v[156:159], v[180:183], v[58:61]
	v_mfma_f32_16x16x32_bf16 v[54:57], v[142:145], v[188:191], v[54:57]
	v_mfma_f32_16x16x32_bf16 v[46:49], v[156:159], v[188:191], v[46:49]
	v_mfma_f32_16x16x32_bf16 v[38:41], v[142:145], v[196:199], v[38:41]
	v_mfma_f32_16x16x32_bf16 v[30:33], v[156:159], v[196:199], v[30:33]
	v_mfma_f32_16x16x32_bf16 v[22:25], v[142:145], v[204:207], v[22:25]
	v_mfma_f32_16x16x32_bf16 v[14:17], v[156:159], v[204:207], v[14:17]
	v_mfma_f32_16x16x32_bf16 v[62:65], v[152:155], v[184:187], v[62:65]
	v_mfma_f32_16x16x32_bf16 v[58:61], v[160:163], v[184:187], v[58:61]
	v_mfma_f32_16x16x32_bf16 v[54:57], v[152:155], v[192:195], v[54:57]
	v_mfma_f32_16x16x32_bf16 v[46:49], v[160:163], v[192:195], v[46:49]
	v_mfma_f32_16x16x32_bf16 v[38:41], v[152:155], v[200:203], v[38:41]
	v_mfma_f32_16x16x32_bf16 v[30:33], v[160:163], v[200:203], v[30:33]
	v_mfma_f32_16x16x32_bf16 v[22:25], v[152:155], v[208:211], v[22:25]
	v_mfma_f32_16x16x32_bf16 v[14:17], v[160:163], v[208:211], v[14:17]
	v_mfma_f32_16x16x32_bf16 v[50:53], v[164:167], v[180:183], v[50:53]
	v_mfma_f32_16x16x32_bf16 v[42:45], v[172:175], v[180:183], v[42:45]
	v_mfma_f32_16x16x32_bf16 v[34:37], v[164:167], v[188:191], v[34:37]
	v_mfma_f32_16x16x32_bf16 v[26:29], v[172:175], v[188:191], v[26:29]
	v_mfma_f32_16x16x32_bf16 v[18:21], v[164:167], v[196:199], v[18:21]
	v_mfma_f32_16x16x32_bf16 v[10:13], v[172:175], v[196:199], v[10:13]
	v_mfma_f32_16x16x32_bf16 v[6:9], v[164:167], v[204:207], v[6:9]
	v_mfma_f32_16x16x32_bf16 v[2:5], v[172:175], v[204:207], v[2:5]
	v_mfma_f32_16x16x32_bf16 v[50:53], v[168:171], v[184:187], v[50:53]
	v_mfma_f32_16x16x32_bf16 v[42:45], v[176:179], v[184:187], v[42:45]
	v_mfma_f32_16x16x32_bf16 v[34:37], v[168:171], v[192:195], v[34:37]
	v_mfma_f32_16x16x32_bf16 v[26:29], v[176:179], v[192:195], v[26:29]
	v_mfma_f32_16x16x32_bf16 v[18:21], v[168:171], v[200:203], v[18:21]
	v_mfma_f32_16x16x32_bf16 v[10:13], v[176:179], v[200:203], v[10:13]
	v_mfma_f32_16x16x32_bf16 v[6:9], v[168:171], v[208:211], v[6:9]
	v_mfma_f32_16x16x32_bf16 v[2:5], v[176:179], v[208:211], v[2:5]
	s_barrier
	s_setprio 0
	v_add_u32_e32 v151, s62, v147
	ds_read_b128 v[142:145], v151
	ds_read_b128 v[152:155], v151 offset:1024
	ds_read_b128 v[156:159], v151 offset:2048
	ds_read_b128 v[160:163], v151 offset:3072
	v_add_u32_e32 v151, s61, v147
	ds_read_b128 v[164:167], v151
	ds_read_b128 v[168:171], v151 offset:1024
	ds_read_b128 v[172:175], v151 offset:2048
	ds_read_b128 v[176:179], v151 offset:3072
	s_mov_b32 m0, s48
	v_lshl_add_u64 v[220:221], s[30:31], 0, v[130:131]
	ds_read_b128 v[180:183], v150 offset:32768
	ds_read_b128 v[184:187], v150 offset:33792
	ds_read_b128 v[188:191], v150 offset:34816
	ds_read_b128 v[192:195], v150 offset:35840
	ds_read_b128 v[196:199], v150 offset:36864
	ds_read_b128 v[200:203], v150 offset:37888
	ds_read_b128 v[204:207], v150 offset:38912
	ds_read_b128 v[208:211], v150 offset:39936
	global_load_lds_dwordx4 v[220:221], off
	v_lshl_add_u64 v[220:221], s[30:31], 0, v[134:135]
	s_mov_b32 m0, s49
	s_nop 0
	global_load_lds_dwordx4 v[220:221], off
	s_waitcnt vmcnt(8)
	s_waitcnt lgkmcnt(0)
	s_setprio 1
	s_barrier
	v_mfma_f32_16x16x32_bf16 v[126:129], v[142:145], v[180:183], v[126:129]
	v_mfma_f32_16x16x32_bf16 v[122:125], v[156:159], v[180:183], v[122:125]
	v_mfma_f32_16x16x32_bf16 v[118:121], v[142:145], v[188:191], v[118:121]
	v_mfma_f32_16x16x32_bf16 v[110:113], v[156:159], v[188:191], v[110:113]
	v_mfma_f32_16x16x32_bf16 v[102:105], v[142:145], v[196:199], v[102:105]
	v_mfma_f32_16x16x32_bf16 v[94:97], v[156:159], v[196:199], v[94:97]
	v_mfma_f32_16x16x32_bf16 v[86:89], v[142:145], v[204:207], v[86:89]
	v_mfma_f32_16x16x32_bf16 v[78:81], v[156:159], v[204:207], v[78:81]
	v_mfma_f32_16x16x32_bf16 v[126:129], v[152:155], v[184:187], v[126:129]
	v_mfma_f32_16x16x32_bf16 v[122:125], v[160:163], v[184:187], v[122:125]
	v_mfma_f32_16x16x32_bf16 v[118:121], v[152:155], v[192:195], v[118:121]
	v_mfma_f32_16x16x32_bf16 v[110:113], v[160:163], v[192:195], v[110:113]
	v_mfma_f32_16x16x32_bf16 v[102:105], v[152:155], v[200:203], v[102:105]
	v_mfma_f32_16x16x32_bf16 v[94:97], v[160:163], v[200:203], v[94:97]
	v_mfma_f32_16x16x32_bf16 v[86:89], v[152:155], v[208:211], v[86:89]
	v_mfma_f32_16x16x32_bf16 v[78:81], v[160:163], v[208:211], v[78:81]
	v_mfma_f32_16x16x32_bf16 v[114:117], v[164:167], v[180:183], v[114:117]
	v_mfma_f32_16x16x32_bf16 v[106:109], v[172:175], v[180:183], v[106:109]
	v_mfma_f32_16x16x32_bf16 v[98:101], v[164:167], v[188:191], v[98:101]
	v_mfma_f32_16x16x32_bf16 v[90:93], v[172:175], v[188:191], v[90:93]
	v_mfma_f32_16x16x32_bf16 v[82:85], v[164:167], v[196:199], v[82:85]
	v_mfma_f32_16x16x32_bf16 v[74:77], v[172:175], v[196:199], v[74:77]
	v_mfma_f32_16x16x32_bf16 v[70:73], v[164:167], v[204:207], v[70:73]
	v_mfma_f32_16x16x32_bf16 v[66:69], v[172:175], v[204:207], v[66:69]
	v_mfma_f32_16x16x32_bf16 v[114:117], v[168:171], v[184:187], v[114:117]
	v_mfma_f32_16x16x32_bf16 v[106:109], v[176:179], v[184:187], v[106:109]
	v_mfma_f32_16x16x32_bf16 v[98:101], v[168:171], v[192:195], v[98:101]
	v_mfma_f32_16x16x32_bf16 v[90:93], v[176:179], v[192:195], v[90:93]
	v_mfma_f32_16x16x32_bf16 v[82:85], v[168:171], v[200:203], v[82:85]
	v_mfma_f32_16x16x32_bf16 v[74:77], v[176:179], v[200:203], v[74:77]
	v_mfma_f32_16x16x32_bf16 v[70:73], v[168:171], v[208:211], v[70:73]
	v_mfma_f32_16x16x32_bf16 v[66:69], v[176:179], v[208:211], v[66:69]
	s_barrier
; #define PG8_STAGE(bufoff, gbase, voff) do { _Pragma("unroll") for (int _i = 0; _i < 2; ++_i) \
;         __builtin_amdgcn_global_load_lds((const unsigned*)((const char*)(gbase) + (voff)[_i]), (LAS unsigned*)(lds + (bufoff) + ldsw + _i * 8192), 16, 0, 0); } while (0)
; #define PG8_LDA(dst, b, h) do { _Pragma("unroll") for (int m = 0; m < 4; ++m) _Pragma("unroll") for (int k = 0; k < 2; ++k) dst[m][k] = *(const LAS bf16x8*)(lds + PG8_SA(b, h) + aoff + m * 2048 + k * 1024); } while (0)
; #define PG8_MMA(ai, bj, At, Bt) do { __builtin_amdgcn_s_setprio(1); _Pragma("unroll") for (int m = 0; m < 4; ++m) _Pragma("unroll") for (int n = 0; n < 2; ++n) _Pragma("unroll") for (int k = 0; k < 2; ++k) \
;         acc[ai][bj][m][n] = __builtin_amdgcn_mfma_f32_16x16x32_bf16(Bt[n][k], At[m][k], acc[ai][bj][m][n], 0, 0, 0); __builtin_amdgcn_s_setprio(0); } while (0)
; #define PG8_WAIT_V(n) asm volatile("s_waitcnt vmcnt(" #n ")" ::: "memory")
; #define PG8_WAIT_L(n) asm volatile("s_waitcnt lgkmcnt(" #n ")" ::: "memory")
; #define PG8_BAR __builtin_amdgcn_s_barrier()
; #define PG8_SCHED __builtin_amdgcn_sched_barrier(0)
; template <class Epi, class Sched, bool ALIGN_EPI = true, bool SP2 = true>
; __device__ __forceinline__ void gemm_phase(LAS unsigned char* lds, const Gemm g, const Sched& S, const Epi& E) {
;     ...
;             PG8_WAIT_V(8); PG8_WAIT_L(0); PG8_BAR; PG8_MMA(0, 0, At, B0); PG8_MMA(0, 1, At, B1); PG8_BAR; PG8_SCHED;
;             PG8_LDA(At, 1, 1); PG8_STAGE(PG8_SB(1, 0), b3, voffB); PG8_STAGE(PG8_SB(1, 1), b3 + hstep, voffB); PG8_STAGE(PG8_SA(1, 0), a3, voffA);
;             PG8_WAIT_V(8); PG8_WAIT_L(0); PG8_BAR; PG8_MMA(1, 0, At, B0); PG8_MMA(1, 1, At, B1); PG8_BAR; PG8_SCHED;
	s_setprio 0
	s_mov_b32 m0, s60
	v_lshl_add_u64 v[212:213], v[212:213], 0, s[6:7]
	ds_read_b128 v[180:183], v150 offset:49152
	ds_read_b128 v[184:187], v150 offset:50176
	ds_read_b128 v[188:191], v150 offset:51200
	ds_read_b128 v[192:195], v150 offset:52224
	ds_read_b128 v[196:199], v150 offset:53248
	ds_read_b128 v[200:203], v150 offset:54272
	ds_read_b128 v[204:207], v150 offset:55296
	ds_read_b128 v[208:211], v150 offset:56320
	global_load_lds_dwordx4 v[212:213], off
	v_lshl_add_u64 v[212:213], v[214:215], 0, s[6:7]
	s_mov_b32 m0, s59
	s_nop 0
	global_load_lds_dwordx4 v[212:213], off
	v_lshl_add_u64 v[212:213], s[28:29], 0, v[132:133]
	s_mov_b32 m0, s68
	s_nop 0
	global_load_lds_dwordx4 v[212:213], off
	v_lshl_add_u64 v[212:213], s[28:29], 0, v[136:137]
	s_mov_b32 m0, s67
	s_nop 0
	global_load_lds_dwordx4 v[212:213], off
	v_lshl_add_u64 v[212:213], v[216:217], 0, s[6:7]
	s_mov_b32 m0, s51
	s_nop 0
	global_load_lds_dwordx4 v[212:213], off
	v_lshl_add_u64 v[212:213], v[218:219], 0, s[6:7]
	s_mov_b32 m0, s52
	s_nop 0
	global_load_lds_dwordx4 v[212:213], off
	s_waitcnt vmcnt(8)
	s_waitcnt lgkmcnt(0)
	s_setprio 1
	s_barrier
	v_mfma_f32_16x16x32_bf16 v[62:65], v[142:145], v[180:183], v[62:65]
	v_mfma_f32_16x16x32_bf16 v[58:61], v[156:159], v[180:183], v[58:61]
	v_mfma_f32_16x16x32_bf16 v[54:57], v[142:145], v[188:191], v[54:57]
	v_mfma_f32_16x16x32_bf16 v[46:49], v[156:159], v[188:191], v[46:49]
	v_mfma_f32_16x16x32_bf16 v[38:41], v[142:145], v[196:199], v[38:41]
	v_mfma_f32_16x16x32_bf16 v[30:33], v[156:159], v[196:199], v[30:33]
	v_mfma_f32_16x16x32_bf16 v[22:25], v[142:145], v[204:207], v[22:25]
	v_mfma_f32_16x16x32_bf16 v[14:17], v[156:159], v[204:207], v[14:17]
	v_mfma_f32_16x16x32_bf16 v[62:65], v[152:155], v[184:187], v[62:65]
	v_mfma_f32_16x16x32_bf16 v[58:61], v[160:163], v[184:187], v[58:61]
	v_mfma_f32_16x16x32_bf16 v[54:57], v[152:155], v[192:195], v[54:57]
	v_mfma_f32_16x16x32_bf16 v[46:49], v[160:163], v[192:195], v[46:49]
	v_mfma_f32_16x16x32_bf16 v[38:41], v[152:155], v[200:203], v[38:41]
	v_mfma_f32_16x16x32_bf16 v[30:33], v[160:163], v[200:203], v[30:33]
	v_mfma_f32_16x16x32_bf16 v[22:25], v[152:155], v[208:211], v[22:25]
	v_mfma_f32_16x16x32_bf16 v[14:17], v[160:163], v[208:211], v[14:17]
	v_mfma_f32_16x16x32_bf16 v[50:53], v[164:167], v[180:183], v[50:53]
	v_mfma_f32_16x16x32_bf16 v[42:45], v[172:175], v[180:183], v[42:45]
	v_mfma_f32_16x16x32_bf16 v[34:37], v[164:167], v[188:191], v[34:37]
	v_mfma_f32_16x16x32_bf16 v[26:29], v[172:175], v[188:191], v[26:29]
	v_mfma_f32_16x16x32_bf16 v[18:21], v[164:167], v[196:199], v[18:21]
	v_mfma_f32_16x16x32_bf16 v[10:13], v[172:175], v[196:199], v[10:13]
	v_mfma_f32_16x16x32_bf16 v[6:9], v[164:167], v[204:207], v[6:9]
	v_mfma_f32_16x16x32_bf16 v[2:5], v[172:175], v[204:207], v[2:5]
	v_mfma_f32_16x16x32_bf16 v[50:53], v[168:171], v[184:187], v[50:53]
	v_mfma_f32_16x16x32_bf16 v[42:45], v[176:179], v[184:187], v[42:45]
	v_mfma_f32_16x16x32_bf16 v[34:37], v[168:171], v[192:195], v[34:37]
	v_mfma_f32_16x16x32_bf16 v[26:29], v[176:179], v[192:195], v[26:29]
	v_mfma_f32_16x16x32_bf16 v[18:21], v[168:171], v[200:203], v[18:21]
	v_mfma_f32_16x16x32_bf16 v[10:13], v[176:179], v[200:203], v[10:13]
	v_mfma_f32_16x16x32_bf16 v[6:9], v[168:171], v[208:211], v[6:9]
	v_mfma_f32_16x16x32_bf16 v[2:5], v[176:179], v[208:211], v[2:5]
	s_barrier
	s_setprio 0
	s_movk_i32 s30, 0x100
	s_andn2_b64 vcc, exec, s[26:27]
	s_mov_b64 s[28:29], -1
	s_mov_b64 s[26:27], 0
	s_cbranch_vccz .LBB0_2100
	s_and_b64 vcc, exec, s[10:11]
	s_cbranch_vccz .LBB0_2103
	s_barrier

; #define PG8_STAGE(bufoff, gbase, voff) do { _Pragma("unroll") for (int _i = 0; _i < 2; ++_i) \
;         __builtin_amdgcn_global_load_lds((const unsigned*)((const char*)(gbase) + (voff)[_i]), (LAS unsigned*)(lds + (bufoff) + ldsw + _i * 8192), 16, 0, 0); } while (0)
; #define PG8_LDA(dst, b, h) do { _Pragma("unroll") for (int m = 0; m < 4; ++m) _Pragma("unroll") for (int k = 0; k < 2; ++k) dst[m][k] = *(const LAS bf16x8*)(lds + PG8_SA(b, h) + aoff + m * 2048 + k * 1024); } while (0)
; #define PG8_LDB(dst, b, h) do { _Pragma("unroll") for (int n = 0; n < 2; ++n) _Pragma("unroll") for (int k = 0; k < 2; ++k) dst[n][k] = *(const LAS bf16x8*)(lds + PG8_SB(b, h) + boff + n * 2048 + k * 1024); } while (0)
; #define PG8_MMA(ai, bj, At, Bt) do { __builtin_amdgcn_s_setprio(1); _Pragma("unroll") for (int m = 0; m < 4; ++m) _Pragma("unroll") for (int n = 0; n < 2; ++n) _Pragma("unroll") for (int k = 0; k < 2; ++k) \
;         acc[ai][bj][m][n] = __builtin_amdgcn_mfma_f32_16x16x32_bf16(Bt[n][k], At[m][k], acc[ai][bj][m][n], 0, 0, 0); __builtin_amdgcn_s_setprio(0); } while (0)
; #define PG8_BAR __builtin_amdgcn_s_barrier()
; template <class Epi, class Sched, bool ALIGN_EPI = true, bool SP2 = true>
; __device__ __forceinline__ void gemm_phase(LAS unsigned char* lds, const Gemm g, const Sched& S, const Epi& E) {
;     ...
;         const char* nA = has_next ? PG8_ABASE(nxt) : cA; const char* nB = has_next ? PG8_BBASE(nxt) : cB;
;         for (int t = 0; t < nt; t += 2) {
;             const bool last = (t == nt - 2);
;             const char* a1 = cA + (size_t)(t + 1) * kstep;
;             const char* a2 = last ? nA : cA + (size_t)(t + 2) * kstep; const char* b2 = last ? nB : cB + (size_t)(t + 2) * kstep;
;             const char* a3 = a2 + kstep; const char* b3 = b2 + kstep;
;             if (last && has_next) S.a_ready(nxt);
;             if constexpr (SP2) {
;             PG8_LDB(B0, 0, 0); PG8_LDB(B1, 0, 1); PG8_SCHED; PG8_LDA(At, 0, 0); PG8_STAGE(PG8_SA(1, 1), a1 + hstep, voffA);
;             PG8_WAIT_V(8); PG8_WAIT_L(0); PG8_BAR; PG8_MMA(0, 0, At, B0); PG8_MMA(0, 1, At, B1); PG8_BAR; PG8_SCHED;
;             PG8_LDA(At, 0, 1); PG8_STAGE(PG8_SB(0, 0), b2, voffB); PG8_STAGE(PG8_SB(0, 1), b2 + hstep, voffB); PG8_STAGE(PG8_SA(0, 0), a2, voffA);
;             PG8_WAIT_V(8); PG8_WAIT_L(0); PG8_BAR; PG8_MMA(1, 0, At, B0); PG8_MMA(1, 1, At, B1); PG8_BAR; PG8_SCHED;
.LBB0_2179:
	ds_read_b128 v[120:123], v201
	ds_read_b128 v[124:127], v201 offset:1024
	ds_read_b128 v[132:135], v201 offset:2048
	ds_read_b128 v[140:143], v201 offset:3072
	ds_read_b128 v[144:147], v202
	ds_read_b128 v[148:151], v202 offset:1024
	ds_read_b128 v[152:155], v202 offset:2048
	ds_read_b128 v[156:159], v202 offset:3072
	s_add_u32 s36, s34, 0xfff00080
	s_addc_u32 s37, s35, -1
	s_cmp_eq_u32 s61, 60
	s_cselect_b32 s39, s27, s37
	s_cselect_b32 s38, s57, s36
	s_cselect_b32 s37, s25, s60
	s_cselect_b32 s36, s58, s59
	v_lshl_add_u64 v[196:197], s[34:35], 0, v[184:185]
	s_add_i32 m0, s43, 0xc000
	ds_read_b128 v[160:163], v203
	ds_read_b128 v[164:167], v203 offset:1024
	ds_read_b128 v[168:171], v203 offset:2048
	ds_read_b128 v[172:175], v203 offset:3072
	ds_read_b128 v[192:195], v203 offset:4096
	ds_read_b128 v[206:209], v203 offset:5120
	ds_read_b128 v[210:213], v203 offset:6144
	ds_read_b128 v[214:217], v203 offset:7168
	global_load_lds_dwordx4 v[196:197], off
	v_lshl_add_u64 v[196:197], s[34:35], 0, v[186:187]
	s_add_i32 m0, s43, 0xe000
	s_nop 0
	global_load_lds_dwordx4 v[196:197], off
	s_waitcnt vmcnt(8)
	s_waitcnt lgkmcnt(0)
	s_setprio 1
	s_barrier
	v_mfma_f32_16x16x32_bf16 v[136:139], v[120:123], v[160:163], v[136:139]
	v_mfma_f32_16x16x32_bf16 v[128:131], v[132:135], v[160:163], v[128:131]
	v_mfma_f32_16x16x32_bf16 v[108:111], v[120:123], v[168:171], v[108:111]
	v_mfma_f32_16x16x32_bf16 v[104:107], v[132:135], v[168:171], v[104:107]
	v_mfma_f32_16x16x32_bf16 v[92:95], v[120:123], v[192:195], v[92:95]
	v_mfma_f32_16x16x32_bf16 v[88:91], v[132:135], v[192:195], v[88:91]
	v_mfma_f32_16x16x32_bf16 v[76:79], v[120:123], v[210:213], v[76:79]
	v_mfma_f32_16x16x32_bf16 v[72:75], v[132:135], v[210:213], v[72:75]
	v_mfma_f32_16x16x32_bf16 v[136:139], v[124:127], v[164:167], v[136:139]
	v_mfma_f32_16x16x32_bf16 v[128:131], v[140:143], v[164:167], v[128:131]
	v_mfma_f32_16x16x32_bf16 v[108:111], v[124:127], v[172:175], v[108:111]
	v_mfma_f32_16x16x32_bf16 v[104:107], v[140:143], v[172:175], v[104:107]
	v_mfma_f32_16x16x32_bf16 v[92:95], v[124:127], v[206:209], v[92:95]
	v_mfma_f32_16x16x32_bf16 v[88:91], v[140:143], v[206:209], v[88:91]
	v_mfma_f32_16x16x32_bf16 v[76:79], v[124:127], v[214:217], v[76:79]
	v_mfma_f32_16x16x32_bf16 v[72:75], v[140:143], v[214:217], v[72:75]
	v_mfma_f32_16x16x32_bf16 v[116:119], v[144:147], v[160:163], v[116:119]
	v_mfma_f32_16x16x32_bf16 v[112:115], v[152:155], v[160:163], v[112:115]
	v_mfma_f32_16x16x32_bf16 v[100:103], v[144:147], v[168:171], v[100:103]
	v_mfma_f32_16x16x32_bf16 v[96:99], v[152:155], v[168:171], v[96:99]
	v_mfma_f32_16x16x32_bf16 v[84:87], v[144:147], v[192:195], v[84:87]
	v_mfma_f32_16x16x32_bf16 v[80:83], v[152:155], v[192:195], v[80:83]
	v_mfma_f32_16x16x32_bf16 v[68:71], v[144:147], v[210:213], v[68:71]
	v_mfma_f32_16x16x32_bf16 v[64:67], v[152:155], v[210:213], v[64:67]
	v_mfma_f32_16x16x32_bf16 v[116:119], v[148:151], v[164:167], v[116:119]
	v_mfma_f32_16x16x32_bf16 v[112:115], v[156:159], v[164:167], v[112:115]
	v_mfma_f32_16x16x32_bf16 v[100:103], v[148:151], v[172:175], v[100:103]
	v_mfma_f32_16x16x32_bf16 v[96:99], v[156:159], v[172:175], v[96:99]
	v_mfma_f32_16x16x32_bf16 v[84:87], v[148:151], v[206:209], v[84:87]
	v_mfma_f32_16x16x32_bf16 v[80:83], v[156:159], v[206:209], v[80:83]
	v_mfma_f32_16x16x32_bf16 v[68:71], v[148:151], v[214:217], v[68:71]
	v_mfma_f32_16x16x32_bf16 v[64:67], v[156:159], v[214:217], v[64:67]
	s_barrier
	s_setprio 0
	s_add_i32 s62, s51, s42
	v_lshl_add_u64 v[196:197], s[36:37], 0, v[178:179]
	s_mov_b32 m0, s62
	ds_read_b128 v[160:163], v203 offset:16384
	ds_read_b128 v[164:167], v203 offset:17408
	ds_read_b128 v[168:171], v203 offset:18432
	ds_read_b128 v[172:175], v203 offset:19456
	ds_read_b128 v[192:195], v203 offset:20480
	ds_read_b128 v[206:209], v203 offset:21504
	ds_read_b128 v[210:213], v203 offset:22528
	ds_read_b128 v[214:217], v203 offset:23552
	global_load_lds_dwordx4 v[196:197], off
	s_add_i32 m0, s62, 0x2000
	s_add_u32 s62, s36, 0x100000
	v_lshl_add_u64 v[218:219], s[36:37], 0, v[182:183]
	s_addc_u32 s63, s37, 0
	s_add_i32 s64, s52, s42
	global_load_lds_dwordx4 v[218:219], off
	v_lshl_add_u64 v[220:221], s[62:63], 0, v[178:179]
	s_mov_b32 m0, s64
	v_lshl_add_u64 v[222:223], s[38:39], 0, v[180:181]
	global_load_lds_dwordx4 v[220:221], off
	v_lshl_add_u64 v[220:221], s[62:63], 0, v[182:183]
	s_add_i32 m0, s64, 0x2000
	s_nop 0
	global_load_lds_dwordx4 v[220:221], off
	v_lshl_add_u64 v[220:221], s[38:39], 0, v[176:177]
	s_mov_b32 m0, s43
	s_nop 0
	global_load_lds_dwordx4 v[220:221], off
	s_mov_b32 m0, s44
	s_nop 0
	global_load_lds_dwordx4 v[222:223], off
	s_waitcnt vmcnt(8)
	s_waitcnt lgkmcnt(0)
	s_setprio 1
	s_barrier
; #define PG8_STAGE(bufoff, gbase, voff) do { _Pragma("unroll") for (int _i = 0; _i < 2; ++_i) \
;         __builtin_amdgcn_global_load_lds((const unsigned*)((const char*)(gbase) + (voff)[_i]), (LAS unsigned*)(lds + (bufoff) + ldsw + _i * 8192), 16, 0, 0); } while (0)
; #define PG8_LDA(dst, b, h) do { _Pragma("unroll") for (int m = 0; m < 4; ++m) _Pragma("unroll") for (int k = 0; k < 2; ++k) dst[m][k] = *(const LAS bf16x8*)(lds + PG8_SA(b, h) + aoff + m * 2048 + k * 1024); } while (0)
; #define PG8_LDB(dst, b, h) do { _Pragma("unroll") for (int n = 0; n < 2; ++n) _Pragma("unroll") for (int k = 0; k < 2; ++k) dst[n][k] = *(const LAS bf16x8*)(lds + PG8_SB(b, h) + boff + n * 2048 + k * 1024); } while (0)
; #define PG8_MMA(ai, bj, At, Bt) do { __builtin_amdgcn_s_setprio(1); _Pragma("unroll") for (int m = 0; m < 4; ++m) _Pragma("unroll") for (int n = 0; n < 2; ++n) _Pragma("unroll") for (int k = 0; k < 2; ++k) \
;         acc[ai][bj][m][n] = __builtin_amdgcn_mfma_f32_16x16x32_bf16(Bt[n][k], At[m][k], acc[ai][bj][m][n], 0, 0, 0); __builtin_amdgcn_s_setprio(0); } while (0)
; #define PG8_WAIT_V(n) asm volatile("s_waitcnt vmcnt(" #n ")" ::: "memory")
; #define PG8_WAIT_L(n) asm volatile("s_waitcnt lgkmcnt(" #n ")" ::: "memory")
; #define PG8_BAR __builtin_amdgcn_s_barrier()
; #define PG8_SCHED __builtin_amdgcn_sched_barrier(0)
; template <class Epi, class Sched, bool ALIGN_EPI = true, bool SP2 = true>
; __device__ __forceinline__ void gemm_phase(LAS unsigned char* lds, const Gemm g, const Sched& S, const Epi& E) {
;     ...
;             PG8_WAIT_V(8); PG8_WAIT_L(0); PG8_BAR; PG8_MMA(1, 0, At, B0); PG8_MMA(1, 1, At, B1); PG8_BAR; PG8_SCHED;
;             PG8_LDB(B0, 1, 0); PG8_LDB(B1, 1, 1); PG8_SCHED; PG8_LDA(At, 1, 0); PG8_STAGE(PG8_SA(0, 1), a2 + hstep, voffA);
;             PG8_WAIT_V(8); PG8_WAIT_L(0); PG8_BAR; PG8_MMA(0, 0, At, B0); PG8_MMA(0, 1, At, B1); PG8_BAR; PG8_SCHED;
	v_mfma_f32_16x16x32_bf16 v[60:63], v[120:123], v[160:163], v[60:63]
	v_mfma_f32_16x16x32_bf16 v[56:59], v[132:135], v[160:163], v[56:59]
	v_mfma_f32_16x16x32_bf16 v[44:47], v[120:123], v[168:171], v[44:47]
	v_mfma_f32_16x16x32_bf16 v[40:43], v[132:135], v[168:171], v[40:43]
	v_mfma_f32_16x16x32_bf16 v[28:31], v[120:123], v[192:195], v[28:31]
	v_mfma_f32_16x16x32_bf16 v[24:27], v[132:135], v[192:195], v[24:27]
	v_mfma_f32_16x16x32_bf16 v[12:15], v[120:123], v[210:213], v[12:15]
	v_mfma_f32_16x16x32_bf16 v[8:11], v[132:135], v[210:213], v[8:11]
	v_mfma_f32_16x16x32_bf16 v[60:63], v[124:127], v[164:167], v[60:63]
	v_mfma_f32_16x16x32_bf16 v[56:59], v[140:143], v[164:167], v[56:59]
	v_mfma_f32_16x16x32_bf16 v[44:47], v[124:127], v[172:175], v[44:47]
	v_mfma_f32_16x16x32_bf16 v[40:43], v[140:143], v[172:175], v[40:43]
	v_mfma_f32_16x16x32_bf16 v[28:31], v[124:127], v[206:209], v[28:31]
	v_mfma_f32_16x16x32_bf16 v[24:27], v[140:143], v[206:209], v[24:27]
	v_mfma_f32_16x16x32_bf16 v[12:15], v[124:127], v[214:217], v[12:15]
	v_mfma_f32_16x16x32_bf16 v[8:11], v[140:143], v[214:217], v[8:11]
	v_mfma_f32_16x16x32_bf16 v[52:55], v[144:147], v[160:163], v[52:55]
	v_mfma_f32_16x16x32_bf16 v[48:51], v[152:155], v[160:163], v[48:51]
	v_mfma_f32_16x16x32_bf16 v[36:39], v[144:147], v[168:171], v[36:39]
	v_mfma_f32_16x16x32_bf16 v[32:35], v[152:155], v[168:171], v[32:35]
	v_mfma_f32_16x16x32_bf16 v[20:23], v[144:147], v[192:195], v[20:23]
	v_mfma_f32_16x16x32_bf16 v[16:19], v[152:155], v[192:195], v[16:19]
	v_mfma_f32_16x16x32_bf16 v[4:7], v[144:147], v[210:213], v[4:7]
	v_mfma_f32_16x16x32_bf16 v[0:3], v[152:155], v[210:213], v[0:3]
	v_mfma_f32_16x16x32_bf16 v[52:55], v[148:151], v[164:167], v[52:55]
	v_mfma_f32_16x16x32_bf16 v[48:51], v[156:159], v[164:167], v[48:51]
	v_mfma_f32_16x16x32_bf16 v[36:39], v[148:151], v[172:175], v[36:39]
	v_mfma_f32_16x16x32_bf16 v[32:35], v[156:159], v[172:175], v[32:35]
	v_mfma_f32_16x16x32_bf16 v[20:23], v[148:151], v[206:209], v[20:23]
	v_mfma_f32_16x16x32_bf16 v[16:19], v[156:159], v[206:209], v[16:19]
	v_mfma_f32_16x16x32_bf16 v[4:7], v[148:151], v[214:217], v[4:7]
	v_mfma_f32_16x16x32_bf16 v[0:3], v[156:159], v[214:217], v[0:3]
	s_barrier
	s_setprio 0
	s_add_i32 s62, 0, 0x18000
	s_add_i32 s63, 0, 0x1c000
	v_add_u32_e32 v140, s62, v199
	v_add_u32_e32 v156, s63, v199
	ds_read_b128 v[120:123], v140
	ds_read_b128 v[124:127], v140 offset:1024
	ds_read_b128 v[132:135], v140 offset:2048
	ds_read_b128 v[140:143], v140 offset:3072
	ds_read_b128 v[144:147], v156
	ds_read_b128 v[148:151], v156 offset:1024
	ds_read_b128 v[152:155], v156 offset:2048
	ds_read_b128 v[156:159], v156 offset:3072
	s_add_u32 s38, s38, 0x100000
	s_addc_u32 s39, s39, 0
	s_mov_b32 m0, s45
	v_lshl_add_u64 v[224:225], s[38:39], 0, v[176:177]
	ds_read_b128 v[160:163], v203 offset:32768
	ds_read_b128 v[164:167], v203 offset:33792
	ds_read_b128 v[168:171], v203 offset:34816
	ds_read_b128 v[172:175], v203 offset:35840
	ds_read_b128 v[192:195], v203 offset:36864
	ds_read_b128 v[206:209], v203 offset:37888
	ds_read_b128 v[210:213], v203 offset:38912
	ds_read_b128 v[214:217], v203 offset:39936
	global_load_lds_dwordx4 v[224:225], off
	v_lshl_add_u64 v[224:225], s[38:39], 0, v[180:181]
	s_mov_b32 m0, s46
	s_nop 0
	global_load_lds_dwordx4 v[224:225], off
	s_waitcnt vmcnt(8)
	s_waitcnt lgkmcnt(0)
	s_setprio 1
	s_barrier
	v_mfma_f32_16x16x32_bf16 v[136:139], v[120:123], v[160:163], v[136:139]
	v_mfma_f32_16x16x32_bf16 v[128:131], v[132:135], v[160:163], v[128:131]
	v_mfma_f32_16x16x32_bf16 v[108:111], v[120:123], v[168:171], v[108:111]
	v_mfma_f32_16x16x32_bf16 v[104:107], v[132:135], v[168:171], v[104:107]
	v_mfma_f32_16x16x32_bf16 v[92:95], v[120:123], v[192:195], v[92:95]
	v_mfma_f32_16x16x32_bf16 v[88:91], v[132:135], v[192:195], v[88:91]
	v_mfma_f32_16x16x32_bf16 v[76:79], v[120:123], v[210:213], v[76:79]
	v_mfma_f32_16x16x32_bf16 v[72:75], v[132:135], v[210:213], v[72:75]
	v_mfma_f32_16x16x32_bf16 v[136:139], v[124:127], v[164:167], v[136:139]
	v_mfma_f32_16x16x32_bf16 v[128:131], v[140:143], v[164:167], v[128:131]
	v_mfma_f32_16x16x32_bf16 v[108:111], v[124:127], v[172:175], v[108:111]
	v_mfma_f32_16x16x32_bf16 v[104:107], v[140:143], v[172:175], v[104:107]
	v_mfma_f32_16x16x32_bf16 v[92:95], v[124:127], v[206:209], v[92:95]
	v_mfma_f32_16x16x32_bf16 v[88:91], v[140:143], v[206:209], v[88:91]
	v_mfma_f32_16x16x32_bf16 v[76:79], v[124:127], v[214:217], v[76:79]
	v_mfma_f32_16x16x32_bf16 v[72:75], v[140:143], v[214:217], v[72:75]
	v_mfma_f32_16x16x32_bf16 v[116:119], v[144:147], v[160:163], v[116:119]
	v_mfma_f32_16x16x32_bf16 v[112:115], v[152:155], v[160:163], v[112:115]
	v_mfma_f32_16x16x32_bf16 v[100:103], v[144:147], v[168:171], v[100:103]
	v_mfma_f32_16x16x32_bf16 v[96:99], v[152:155], v[168:171], v[96:99]
	v_mfma_f32_16x16x32_bf16 v[84:87], v[144:147], v[192:195], v[84:87]
	v_mfma_f32_16x16x32_bf16 v[80:83], v[152:155], v[192:195], v[80:83]
	v_mfma_f32_16x16x32_bf16 v[68:71], v[144:147], v[210:213], v[68:71]
	v_mfma_f32_16x16x32_bf16 v[64:67], v[152:155], v[210:213], v[64:67]
	v_mfma_f32_16x16x32_bf16 v[116:119], v[148:151], v[164:167], v[116:119]
	v_mfma_f32_16x16x32_bf16 v[112:115], v[156:159], v[164:167], v[112:115]
	v_mfma_f32_16x16x32_bf16 v[100:103], v[148:151], v[172:175], v[100:103]
	v_mfma_f32_16x16x32_bf16 v[96:99], v[156:159], v[172:175], v[96:99]
	v_mfma_f32_16x16x32_bf16 v[84:87], v[148:151], v[206:209], v[84:87]
	v_mfma_f32_16x16x32_bf16 v[80:83], v[156:159], v[206:209], v[80:83]
	v_mfma_f32_16x16x32_bf16 v[68:71], v[148:151], v[214:217], v[68:71]
	v_mfma_f32_16x16x32_bf16 v[64:67], v[156:159], v[214:217], v[64:67]
	s_barrier
; #define PG8_STAGE(bufoff, gbase, voff) do { _Pragma("unroll") for (int _i = 0; _i < 2; ++_i) \
;         __builtin_amdgcn_global_load_lds((const unsigned*)((const char*)(gbase) + (voff)[_i]), (LAS unsigned*)(lds + (bufoff) + ldsw + _i * 8192), 16, 0, 0); } while (0)
; #define PG8_LDA(dst, b, h) do { _Pragma("unroll") for (int m = 0; m < 4; ++m) _Pragma("unroll") for (int k = 0; k < 2; ++k) dst[m][k] = *(const LAS bf16x8*)(lds + PG8_SA(b, h) + aoff + m * 2048 + k * 1024); } while (0)
; #define PG8_MMA(ai, bj, At, Bt) do { __builtin_amdgcn_s_setprio(1); _Pragma("unroll") for (int m = 0; m < 4; ++m) _Pragma("unroll") for (int n = 0; n < 2; ++n) _Pragma("unroll") for (int k = 0; k < 2; ++k) \
;         acc[ai][bj][m][n] = __builtin_amdgcn_mfma_f32_16x16x32_bf16(Bt[n][k], At[m][k], acc[ai][bj][m][n], 0, 0, 0); __builtin_amdgcn_s_setprio(0); } while (0)
; #define PG8_WAIT_V(n) asm volatile("s_waitcnt vmcnt(" #n ")" ::: "memory")
; #define PG8_WAIT_L(n) asm volatile("s_waitcnt lgkmcnt(" #n ")" ::: "memory")
; #define PG8_BAR __builtin_amdgcn_s_barrier()
; #define PG8_SCHED __builtin_amdgcn_sched_barrier(0)
; template <class Epi, class Sched, bool ALIGN_EPI = true, bool SP2 = true>
; __device__ __forceinline__ void gemm_phase(LAS unsigned char* lds, const Gemm g, const Sched& S, const Epi& E) {
;     ...
;             PG8_WAIT_V(8); PG8_WAIT_L(0); PG8_BAR; PG8_MMA(0, 0, At, B0); PG8_MMA(0, 1, At, B1); PG8_BAR; PG8_SCHED;
;             PG8_LDA(At, 1, 1); PG8_STAGE(PG8_SB(1, 0), b3, voffB); PG8_STAGE(PG8_SB(1, 1), b3 + hstep, voffB); PG8_STAGE(PG8_SA(1, 0), a3, voffA);
;             PG8_WAIT_V(8); PG8_WAIT_L(0); PG8_BAR; PG8_MMA(1, 0, At, B0); PG8_MMA(1, 1, At, B1); PG8_BAR; PG8_SCHED;
;     ...
;         if constexpr (ALIGN_EPI) { if (wr == 0) PG8_BAR; }
	s_setprio 0
	s_add_i32 s38, s62, s42
	v_lshl_add_u64 v[196:197], v[196:197], 0, s[14:15]
	s_mov_b32 m0, s38
	ds_read_b128 v[160:163], v203 offset:49152
	ds_read_b128 v[164:167], v203 offset:50176
	ds_read_b128 v[168:171], v203 offset:51200
	ds_read_b128 v[172:175], v203 offset:52224
	ds_read_b128 v[192:195], v203 offset:53248
	ds_read_b128 v[206:209], v203 offset:54272
	ds_read_b128 v[210:213], v203 offset:55296
	ds_read_b128 v[214:217], v203 offset:56320
	global_load_lds_dwordx4 v[196:197], off
	s_add_i32 m0, s38, 0x2000
	s_add_u32 s36, s36, 0x100080
	v_lshl_add_u64 v[196:197], v[218:219], 0, s[14:15]
	s_addc_u32 s37, s37, 0
	s_add_i32 s38, s63, s42
	global_load_lds_dwordx4 v[196:197], off
	v_lshl_add_u64 v[196:197], s[36:37], 0, v[178:179]
	s_mov_b32 m0, s38
	s_nop 0
	global_load_lds_dwordx4 v[196:197], off
	v_lshl_add_u64 v[196:197], s[36:37], 0, v[182:183]
	s_add_i32 m0, s38, 0x2000
	s_nop 0
	global_load_lds_dwordx4 v[196:197], off
	v_lshl_add_u64 v[196:197], v[220:221], 0, s[14:15]
	s_mov_b32 m0, s48
	s_nop 0
	global_load_lds_dwordx4 v[196:197], off
	v_lshl_add_u64 v[196:197], v[222:223], 0, s[14:15]
	s_mov_b32 m0, s49
	s_nop 0
	global_load_lds_dwordx4 v[196:197], off
	s_waitcnt vmcnt(8)
	s_waitcnt lgkmcnt(0)
	s_setprio 1
	s_barrier
	v_mfma_f32_16x16x32_bf16 v[60:63], v[120:123], v[160:163], v[60:63]
	v_mfma_f32_16x16x32_bf16 v[56:59], v[132:135], v[160:163], v[56:59]
	v_mfma_f32_16x16x32_bf16 v[44:47], v[120:123], v[168:171], v[44:47]
	v_mfma_f32_16x16x32_bf16 v[40:43], v[132:135], v[168:171], v[40:43]
	v_mfma_f32_16x16x32_bf16 v[28:31], v[120:123], v[192:195], v[28:31]
	v_mfma_f32_16x16x32_bf16 v[24:27], v[132:135], v[192:195], v[24:27]
	v_mfma_f32_16x16x32_bf16 v[12:15], v[120:123], v[210:213], v[12:15]
	v_mfma_f32_16x16x32_bf16 v[8:11], v[132:135], v[210:213], v[8:11]
	v_mfma_f32_16x16x32_bf16 v[60:63], v[124:127], v[164:167], v[60:63]
	v_mfma_f32_16x16x32_bf16 v[56:59], v[140:143], v[164:167], v[56:59]
	v_mfma_f32_16x16x32_bf16 v[44:47], v[124:127], v[172:175], v[44:47]
	v_mfma_f32_16x16x32_bf16 v[40:43], v[140:143], v[172:175], v[40:43]
	v_mfma_f32_16x16x32_bf16 v[28:31], v[124:127], v[206:209], v[28:31]
	v_mfma_f32_16x16x32_bf16 v[24:27], v[140:143], v[206:209], v[24:27]
	v_mfma_f32_16x16x32_bf16 v[12:15], v[124:127], v[214:217], v[12:15]
	v_mfma_f32_16x16x32_bf16 v[8:11], v[140:143], v[214:217], v[8:11]
	v_mfma_f32_16x16x32_bf16 v[52:55], v[144:147], v[160:163], v[52:55]
	v_mfma_f32_16x16x32_bf16 v[48:51], v[152:155], v[160:163], v[48:51]
	v_mfma_f32_16x16x32_bf16 v[36:39], v[144:147], v[168:171], v[36:39]
	v_mfma_f32_16x16x32_bf16 v[32:35], v[152:155], v[168:171], v[32:35]
	v_mfma_f32_16x16x32_bf16 v[20:23], v[144:147], v[192:195], v[20:23]
	v_mfma_f32_16x16x32_bf16 v[16:19], v[152:155], v[192:195], v[16:19]
	v_mfma_f32_16x16x32_bf16 v[4:7], v[144:147], v[210:213], v[4:7]
	v_mfma_f32_16x16x32_bf16 v[0:3], v[152:155], v[210:213], v[0:3]
	v_mfma_f32_16x16x32_bf16 v[52:55], v[148:151], v[164:167], v[52:55]
	v_mfma_f32_16x16x32_bf16 v[48:51], v[156:159], v[164:167], v[48:51]
	v_mfma_f32_16x16x32_bf16 v[36:39], v[148:151], v[172:175], v[36:39]
	v_mfma_f32_16x16x32_bf16 v[32:35], v[156:159], v[172:175], v[32:35]
	v_mfma_f32_16x16x32_bf16 v[20:23], v[148:151], v[206:209], v[20:23]
	v_mfma_f32_16x16x32_bf16 v[16:19], v[156:159], v[206:209], v[16:19]
	v_mfma_f32_16x16x32_bf16 v[4:7], v[148:151], v[214:217], v[4:7]
	v_mfma_f32_16x16x32_bf16 v[0:3], v[156:159], v[214:217], v[0:3]
	s_barrier
	s_setprio 0
	s_add_i32 s61, s61, 2
	s_add_u32 s34, s34, 0x100
	s_addc_u32 s35, s35, 0
	s_add_u32 s59, s59, 0x100
	s_addc_u32 s60, s60, 0
	s_cmp_gt_u32 s61, 61
	s_cbranch_scc0 .LBB0_2179
	s_and_b64 vcc, exec, s[16:17]
	s_cbranch_vccz .LBB0_2182
	s_barrier
